# GEMM loops without any s_setprio flips
# speedup vs baseline: 1.0117x; 1.0023x over previous
; #define PG8_STAGE(bufoff, gbase, RR, ld) do { _Pragma("unroll") for (int _i = 0; _i < 2; ++_i) \
;         __builtin_amdgcn_global_load_lds((const unsigned*)((const char*)(gbase) + (RR)[_i] * (ld) + C2[_i]), (LAS unsigned*)(lds + (bufoff) + ldsw + _i * 8192), 16, 0, 0); } while (0)
; #define PG8_LDA(dst, b, h) do { _Pragma("unroll") for (int m = 0; m < 4; ++m) _Pragma("unroll") for (int k = 0; k < 2; ++k) dst[m][k] = *(const LAS bf16x8*)(lds + PG8_SA(b, h) + aoff + m * 2048 + k * 1024); } while (0)
; #define PG8_LDB(dst, b, h) do { _Pragma("unroll") for (int n = 0; n < 2; ++n) _Pragma("unroll") for (int k = 0; k < 2; ++k) dst[n][k] = *(const LAS bf16x8*)(lds + PG8_SB(b, h) + boff + n * 2048 + k * 1024); } while (0)
; #define PG8_MMA(ai, bj, At, Bt) do { __builtin_amdgcn_s_setprio(1); _Pragma("unroll") for (int m = 0; m < 4; ++m) _Pragma("unroll") for (int n = 0; n < 2; ++n) _Pragma("unroll") for (int k = 0; k < 2; ++k) \
;         acc[ai][bj][m][n] = __builtin_amdgcn_mfma_f32_16x16x32_bf16(Bt[n][k], At[m][k], acc[ai][bj][m][n], 0, 0, 0); __builtin_amdgcn_s_setprio(0); } while (0)
; #define PG8_WAIT_V(n) asm volatile("s_waitcnt vmcnt(" #n ")" ::: "memory")
; #define PG8_WAIT_L(n) asm volatile("s_waitcnt lgkmcnt(" #n ")" ::: "memory")
; #define PG8_BAR __builtin_amdgcn_s_barrier()
; #define PG8_SCHED __builtin_amdgcn_sched_barrier(0)
; template <class Sched, class Epi>
; __device__ __forceinline__ void gemm_run(LAS unsigned char* lds, const Sched& S, const Epi& E) {
;     ...
;         for (int t = 0; t < nt; t += 2) {
;             const bool last = (t == nt - 2);
;             const char* a1 = cA + (size_t)(t + 1) * kstep;
;             const char* a2 = last ? nA : cA + (size_t)(t + 2) * kstep; const char* b2 = last ? nB : cB + (size_t)(t + 2) * kstep;
;             const unsigned la2 = last ? nlda : lda, lb2 = last ? nldb : ldb;
;             const char* a3 = a2 + kstep; const char* b3 = b2 + kstep;
;             PG8_LDB(B0, 0, 0); PG8_LDB(B1, 0, 1); PG8_SCHED; PG8_LDA(At, 0, 0); PG8_STAGE(PG8_SA(1, 1), a1 + (size_t)HALF * lda, RA, lda);
;             PG8_WAIT_V(8); PG8_WAIT_L(0); PG8_BAR; PG8_MMA(0, 0, At, B0); PG8_MMA(0, 1, At, B1); PG8_BAR; PG8_SCHED;
;             PG8_LDA(At, 0, 1); PG8_STAGE(PG8_SB(0, 0), b2, RB, lb2); PG8_STAGE(PG8_SB(0, 1), b2 + (size_t)HALF * lb2, RB, lb2); PG8_STAGE(PG8_SA(0, 0), a2, RA, la2);
.LBB0_246:
	ds_read_b128 v[154:157], v182
	ds_read_b128 v[158:161], v182 offset:1024
	ds_read_b128 v[162:165], v182 offset:2048
	ds_read_b128 v[166:169], v182 offset:3072
	ds_read_b128 v[170:173], v183
	ds_read_b128 v[186:189], v183 offset:1024
	ds_read_b128 v[190:193], v183 offset:2048
	ds_read_b128 v[194:197], v183 offset:3072
	s_add_u32 s39, s6, s54
	s_addc_u32 s40, s7, s55
	s_add_u32 s39, s39, 0x100
	s_addc_u32 s40, s40, 0
	s_add_u32 s41, s12, s54
	s_addc_u32 s42, s33, s55
	s_cmpk_eq_i32 s54, 0xf00
	s_cselect_b32 s59, s29, s40
	s_cselect_b32 s58, s28, s39
	s_cselect_b32 s57, s37, s42
	s_cselect_b32 s56, s36, s41
	v_lshl_add_u64 v[174:175], v[150:151], 0, s[54:55]
	s_add_i32 m0, s21, 0xc000
	ds_read_b128 v[198:201], v184
	ds_read_b128 v[202:205], v184 offset:1024
	ds_read_b128 v[206:209], v184 offset:2048
	ds_read_b128 v[210:213], v184 offset:3072
	ds_read_b128 v[214:217], v184 offset:4096
	ds_read_b128 v[218:221], v184 offset:5120
	ds_read_b128 v[222:225], v184 offset:6144
	ds_read_b128 v[226:229], v184 offset:7168
	global_load_lds_dwordx4 v[174:175], off
	v_lshl_add_u64 v[174:175], v[152:153], 0, s[54:55]
	s_add_i32 m0, s21, 0xe000
	s_nop 0
	global_load_lds_dwordx4 v[174:175], off
	s_waitcnt vmcnt(8)
	s_waitcnt lgkmcnt(0)
	s_barrier
	s_waitcnt lgkmcnt(0)
	v_mfma_f32_16x16x32_bf16 v[126:129], v[154:157], v[198:201], v[126:129]
	v_mfma_f32_16x16x32_bf16 v[122:125], v[162:165], v[198:201], v[122:125]
	v_mfma_f32_16x16x32_bf16 v[110:113], v[154:157], v[206:209], v[110:113]
	v_mfma_f32_16x16x32_bf16 v[106:109], v[162:165], v[206:209], v[106:109]
	v_mfma_f32_16x16x32_bf16 v[94:97], v[154:157], v[214:217], v[94:97]
	v_mfma_f32_16x16x32_bf16 v[90:93], v[162:165], v[214:217], v[90:93]
	v_mfma_f32_16x16x32_bf16 v[78:81], v[154:157], v[222:225], v[78:81]
	v_mfma_f32_16x16x32_bf16 v[74:77], v[162:165], v[222:225], v[74:77]
	v_mfma_f32_16x16x32_bf16 v[126:129], v[158:161], v[202:205], v[126:129]
	v_mfma_f32_16x16x32_bf16 v[122:125], v[166:169], v[202:205], v[122:125]
	v_mfma_f32_16x16x32_bf16 v[110:113], v[158:161], v[210:213], v[110:113]
	v_mfma_f32_16x16x32_bf16 v[106:109], v[166:169], v[210:213], v[106:109]
	v_mfma_f32_16x16x32_bf16 v[94:97], v[158:161], v[218:221], v[94:97]
	v_mfma_f32_16x16x32_bf16 v[90:93], v[166:169], v[218:221], v[90:93]
	v_mfma_f32_16x16x32_bf16 v[78:81], v[158:161], v[226:229], v[78:81]
	v_mfma_f32_16x16x32_bf16 v[74:77], v[166:169], v[226:229], v[74:77]
	v_mfma_f32_16x16x32_bf16 v[118:121], v[170:173], v[198:201], v[118:121]
	v_mfma_f32_16x16x32_bf16 v[114:117], v[190:193], v[198:201], v[114:117]
	v_mfma_f32_16x16x32_bf16 v[102:105], v[170:173], v[206:209], v[102:105]
	v_mfma_f32_16x16x32_bf16 v[98:101], v[190:193], v[206:209], v[98:101]
	v_mfma_f32_16x16x32_bf16 v[86:89], v[170:173], v[214:217], v[86:89]
	v_mfma_f32_16x16x32_bf16 v[82:85], v[190:193], v[214:217], v[82:85]
	v_mfma_f32_16x16x32_bf16 v[70:73], v[170:173], v[222:225], v[70:73]
	v_mfma_f32_16x16x32_bf16 v[66:69], v[190:193], v[222:225], v[66:69]
	v_mfma_f32_16x16x32_bf16 v[118:121], v[186:189], v[202:205], v[118:121]
	v_mfma_f32_16x16x32_bf16 v[114:117], v[194:197], v[202:205], v[114:117]
	v_mfma_f32_16x16x32_bf16 v[102:105], v[186:189], v[210:213], v[102:105]
	v_mfma_f32_16x16x32_bf16 v[98:101], v[194:197], v[210:213], v[98:101]
	v_mfma_f32_16x16x32_bf16 v[86:89], v[186:189], v[218:221], v[86:89]
	v_mfma_f32_16x16x32_bf16 v[82:85], v[194:197], v[218:221], v[82:85]
	v_mfma_f32_16x16x32_bf16 v[70:73], v[186:189], v[226:229], v[70:73]
	v_mfma_f32_16x16x32_bf16 v[66:69], v[194:197], v[226:229], v[66:69]
	s_barrier
	v_lshl_add_u64 v[174:175], s[56:57], 0, v[132:133]
	s_add_i32 s39, s71, s3
	v_lshl_add_u64 v[174:175], v[174:175], 0, v[130:131]
	s_mov_b32 m0, s39
	ds_read_b128 v[198:201], v184 offset:16384
	ds_read_b128 v[202:205], v184 offset:17408
	ds_read_b128 v[206:209], v184 offset:18432
	ds_read_b128 v[210:213], v184 offset:19456
	ds_read_b128 v[214:217], v184 offset:20480
	ds_read_b128 v[218:221], v184 offset:21504
	ds_read_b128 v[222:225], v184 offset:22528
	ds_read_b128 v[226:229], v184 offset:23552
	global_load_lds_dwordx4 v[174:175], off
	s_add_i32 m0, s39, 0x2000
	s_add_u32 s40, s56, 0x80000
	v_lshl_add_u64 v[230:231], s[56:57], 0, v[136:137]
	s_addc_u32 s41, s57, 0
	v_lshl_add_u64 v[230:231], v[230:231], 0, v[130:131]
	v_lshl_add_u64 v[232:233], s[40:41], 0, v[132:133]
	s_add_i32 s39, s72, s3
	global_load_lds_dwordx4 v[230:231], off
	v_lshl_add_u64 v[232:233], v[232:233], 0, v[130:131]
	s_mov_b32 m0, s39
	v_lshl_add_u64 v[234:235], s[58:59], 0, v[140:141]
	global_load_lds_dwordx4 v[232:233], off
	v_lshl_add_u64 v[232:233], s[40:41], 0, v[136:137]
	v_lshl_add_u64 v[232:233], v[232:233], 0, v[130:131]
	s_add_i32 m0, s39, 0x2000
	v_lshl_add_u64 v[234:235], v[234:235], 0, v[130:131]
	global_load_lds_dwordx4 v[232:233], off
	v_lshl_add_u64 v[232:233], s[58:59], 0, v[138:139]
	v_lshl_add_u64 v[232:233], v[232:233], 0, v[130:131]
	s_mov_b32 m0, s21
	s_nop 0
	global_load_lds_dwordx4 v[232:233], off
	s_mov_b32 m0, s35
	s_nop 0
	global_load_lds_dwordx4 v[234:235], off
	s_waitcnt vmcnt(8)
	s_waitcnt lgkmcnt(0)
	s_barrier
; #define PG8_STAGE(bufoff, gbase, RR, ld) do { _Pragma("unroll") for (int _i = 0; _i < 2; ++_i) \
;         __builtin_amdgcn_global_load_lds((const unsigned*)((const char*)(gbase) + (RR)[_i] * (ld) + C2[_i]), (LAS unsigned*)(lds + (bufoff) + ldsw + _i * 8192), 16, 0, 0); } while (0)
; #define PG8_LDA(dst, b, h) do { _Pragma("unroll") for (int m = 0; m < 4; ++m) _Pragma("unroll") for (int k = 0; k < 2; ++k) dst[m][k] = *(const LAS bf16x8*)(lds + PG8_SA(b, h) + aoff + m * 2048 + k * 1024); } while (0)
; #define PG8_LDB(dst, b, h) do { _Pragma("unroll") for (int n = 0; n < 2; ++n) _Pragma("unroll") for (int k = 0; k < 2; ++k) dst[n][k] = *(const LAS bf16x8*)(lds + PG8_SB(b, h) + boff + n * 2048 + k * 1024); } while (0)
; #define PG8_MMA(ai, bj, At, Bt) do { __builtin_amdgcn_s_setprio(1); _Pragma("unroll") for (int m = 0; m < 4; ++m) _Pragma("unroll") for (int n = 0; n < 2; ++n) _Pragma("unroll") for (int k = 0; k < 2; ++k) \
;         acc[ai][bj][m][n] = __builtin_amdgcn_mfma_f32_16x16x32_bf16(Bt[n][k], At[m][k], acc[ai][bj][m][n], 0, 0, 0); __builtin_amdgcn_s_setprio(0); } while (0)
; #define PG8_WAIT_V(n) asm volatile("s_waitcnt vmcnt(" #n ")" ::: "memory")
; #define PG8_WAIT_L(n) asm volatile("s_waitcnt lgkmcnt(" #n ")" ::: "memory")
; #define PG8_BAR __builtin_amdgcn_s_barrier()
; #define PG8_SCHED __builtin_amdgcn_sched_barrier(0)
; template <class Sched, class Epi>
; __device__ __forceinline__ void gemm_run(LAS unsigned char* lds, const Sched& S, const Epi& E) {
;     ...
;             PG8_WAIT_V(8); PG8_WAIT_L(0); PG8_BAR; PG8_MMA(1, 0, At, B0); PG8_MMA(1, 1, At, B1); PG8_BAR; PG8_SCHED;
;             PG8_LDB(B0, 1, 0); PG8_LDB(B1, 1, 1); PG8_SCHED; PG8_LDA(At, 1, 0); PG8_STAGE(PG8_SA(0, 1), a2 + (size_t)HALF * la2, RA, la2);
;             PG8_WAIT_V(8); PG8_WAIT_L(0); PG8_BAR; PG8_MMA(0, 0, At, B0); PG8_MMA(0, 1, At, B1); PG8_BAR; PG8_SCHED;
	s_waitcnt lgkmcnt(0)
	v_mfma_f32_16x16x32_bf16 v[62:65], v[154:157], v[198:201], v[62:65]
	v_mfma_f32_16x16x32_bf16 v[58:61], v[162:165], v[198:201], v[58:61]
	v_mfma_f32_16x16x32_bf16 v[46:49], v[154:157], v[206:209], v[46:49]
	v_mfma_f32_16x16x32_bf16 v[42:45], v[162:165], v[206:209], v[42:45]
	v_mfma_f32_16x16x32_bf16 v[30:33], v[154:157], v[214:217], v[30:33]
	v_mfma_f32_16x16x32_bf16 v[26:29], v[162:165], v[214:217], v[26:29]
	v_mfma_f32_16x16x32_bf16 v[14:17], v[154:157], v[222:225], v[14:17]
	v_mfma_f32_16x16x32_bf16 v[10:13], v[162:165], v[222:225], v[10:13]
	v_mfma_f32_16x16x32_bf16 v[62:65], v[158:161], v[202:205], v[62:65]
	v_mfma_f32_16x16x32_bf16 v[58:61], v[166:169], v[202:205], v[58:61]
	v_mfma_f32_16x16x32_bf16 v[46:49], v[158:161], v[210:213], v[46:49]
	v_mfma_f32_16x16x32_bf16 v[42:45], v[166:169], v[210:213], v[42:45]
	v_mfma_f32_16x16x32_bf16 v[30:33], v[158:161], v[218:221], v[30:33]
	v_mfma_f32_16x16x32_bf16 v[26:29], v[166:169], v[218:221], v[26:29]
	v_mfma_f32_16x16x32_bf16 v[14:17], v[158:161], v[226:229], v[14:17]
	v_mfma_f32_16x16x32_bf16 v[10:13], v[166:169], v[226:229], v[10:13]
	v_mfma_f32_16x16x32_bf16 v[54:57], v[170:173], v[198:201], v[54:57]
	v_mfma_f32_16x16x32_bf16 v[50:53], v[190:193], v[198:201], v[50:53]
	v_mfma_f32_16x16x32_bf16 v[38:41], v[170:173], v[206:209], v[38:41]
	v_mfma_f32_16x16x32_bf16 v[34:37], v[190:193], v[206:209], v[34:37]
	v_mfma_f32_16x16x32_bf16 v[22:25], v[170:173], v[214:217], v[22:25]
	v_mfma_f32_16x16x32_bf16 v[18:21], v[190:193], v[214:217], v[18:21]
	v_mfma_f32_16x16x32_bf16 v[6:9], v[170:173], v[222:225], v[6:9]
	v_mfma_f32_16x16x32_bf16 v[2:5], v[190:193], v[222:225], v[2:5]
	v_mfma_f32_16x16x32_bf16 v[54:57], v[186:189], v[202:205], v[54:57]
	v_mfma_f32_16x16x32_bf16 v[50:53], v[194:197], v[202:205], v[50:53]
	v_mfma_f32_16x16x32_bf16 v[38:41], v[186:189], v[210:213], v[38:41]
	v_mfma_f32_16x16x32_bf16 v[34:37], v[194:197], v[210:213], v[34:37]
	v_mfma_f32_16x16x32_bf16 v[22:25], v[186:189], v[218:221], v[22:25]
	v_mfma_f32_16x16x32_bf16 v[18:21], v[194:197], v[218:221], v[18:21]
	v_mfma_f32_16x16x32_bf16 v[6:9], v[186:189], v[226:229], v[6:9]
	v_mfma_f32_16x16x32_bf16 v[2:5], v[194:197], v[226:229], v[2:5]
	s_barrier
	s_add_i32 s39, 0, 0x18000
	v_add_u32_e32 v134, s39, v179
	s_add_i32 s42, 0, 0x1c000
	ds_read_b128 v[154:157], v134
	ds_read_b128 v[158:161], v134 offset:1024
	ds_read_b128 v[162:165], v134 offset:2048
	ds_read_b128 v[166:169], v134 offset:3072
	v_add_u32_e32 v134, s42, v179
	ds_read_b128 v[170:173], v134
	ds_read_b128 v[186:189], v134 offset:1024
	ds_read_b128 v[190:193], v134 offset:2048
	ds_read_b128 v[194:197], v134 offset:3072
	s_add_u32 s40, s58, 0x80000
	s_addc_u32 s41, s59, 0
	v_lshl_add_u64 v[236:237], s[40:41], 0, v[138:139]
	s_mov_b32 m0, s60
	v_lshl_add_u64 v[236:237], v[236:237], 0, v[130:131]
	ds_read_b128 v[198:201], v184 offset:32768
	ds_read_b128 v[202:205], v184 offset:33792
	ds_read_b128 v[206:209], v184 offset:34816
	ds_read_b128 v[210:213], v184 offset:35840
	ds_read_b128 v[214:217], v184 offset:36864
	ds_read_b128 v[218:221], v184 offset:37888
	ds_read_b128 v[222:225], v184 offset:38912
	ds_read_b128 v[226:229], v184 offset:39936
	global_load_lds_dwordx4 v[236:237], off
	v_lshl_add_u64 v[236:237], s[40:41], 0, v[140:141]
	v_lshl_add_u64 v[236:237], v[236:237], 0, v[130:131]
	s_mov_b32 m0, s61
	s_nop 0
	global_load_lds_dwordx4 v[236:237], off
	s_waitcnt vmcnt(8)
	s_waitcnt lgkmcnt(0)
	s_barrier
	s_waitcnt lgkmcnt(0)
	v_mfma_f32_16x16x32_bf16 v[126:129], v[154:157], v[198:201], v[126:129]
	v_mfma_f32_16x16x32_bf16 v[122:125], v[162:165], v[198:201], v[122:125]
	v_mfma_f32_16x16x32_bf16 v[110:113], v[154:157], v[206:209], v[110:113]
	v_mfma_f32_16x16x32_bf16 v[106:109], v[162:165], v[206:209], v[106:109]
	v_mfma_f32_16x16x32_bf16 v[94:97], v[154:157], v[214:217], v[94:97]
	v_mfma_f32_16x16x32_bf16 v[90:93], v[162:165], v[214:217], v[90:93]
	v_mfma_f32_16x16x32_bf16 v[78:81], v[154:157], v[222:225], v[78:81]
	v_mfma_f32_16x16x32_bf16 v[74:77], v[162:165], v[222:225], v[74:77]
	v_mfma_f32_16x16x32_bf16 v[126:129], v[158:161], v[202:205], v[126:129]
	v_mfma_f32_16x16x32_bf16 v[122:125], v[166:169], v[202:205], v[122:125]
	v_mfma_f32_16x16x32_bf16 v[110:113], v[158:161], v[210:213], v[110:113]
	v_mfma_f32_16x16x32_bf16 v[106:109], v[166:169], v[210:213], v[106:109]
	v_mfma_f32_16x16x32_bf16 v[94:97], v[158:161], v[218:221], v[94:97]
	v_mfma_f32_16x16x32_bf16 v[90:93], v[166:169], v[218:221], v[90:93]
	v_mfma_f32_16x16x32_bf16 v[78:81], v[158:161], v[226:229], v[78:81]
	v_mfma_f32_16x16x32_bf16 v[74:77], v[166:169], v[226:229], v[74:77]
	v_mfma_f32_16x16x32_bf16 v[118:121], v[170:173], v[198:201], v[118:121]
	v_mfma_f32_16x16x32_bf16 v[114:117], v[190:193], v[198:201], v[114:117]
	v_mfma_f32_16x16x32_bf16 v[102:105], v[170:173], v[206:209], v[102:105]
	v_mfma_f32_16x16x32_bf16 v[98:101], v[190:193], v[206:209], v[98:101]
	v_mfma_f32_16x16x32_bf16 v[86:89], v[170:173], v[214:217], v[86:89]
	v_mfma_f32_16x16x32_bf16 v[82:85], v[190:193], v[214:217], v[82:85]
	v_mfma_f32_16x16x32_bf16 v[70:73], v[170:173], v[222:225], v[70:73]
	v_mfma_f32_16x16x32_bf16 v[66:69], v[190:193], v[222:225], v[66:69]
	v_mfma_f32_16x16x32_bf16 v[118:121], v[186:189], v[202:205], v[118:121]
	v_mfma_f32_16x16x32_bf16 v[114:117], v[194:197], v[202:205], v[114:117]
	v_mfma_f32_16x16x32_bf16 v[102:105], v[186:189], v[210:213], v[102:105]
	v_mfma_f32_16x16x32_bf16 v[98:101], v[194:197], v[210:213], v[98:101]
	v_mfma_f32_16x16x32_bf16 v[86:89], v[186:189], v[218:221], v[86:89]
	v_mfma_f32_16x16x32_bf16 v[82:85], v[194:197], v[218:221], v[82:85]
	v_mfma_f32_16x16x32_bf16 v[70:73], v[186:189], v[226:229], v[70:73]
	v_mfma_f32_16x16x32_bf16 v[66:69], v[194:197], v[226:229], v[66:69]
	s_barrier
; #define PG8_STAGE(bufoff, gbase, RR, ld) do { _Pragma("unroll") for (int _i = 0; _i < 2; ++_i) \
;         __builtin_amdgcn_global_load_lds((const unsigned*)((const char*)(gbase) + (RR)[_i] * (ld) + C2[_i]), (LAS unsigned*)(lds + (bufoff) + ldsw + _i * 8192), 16, 0, 0); } while (0)
; #define PG8_LDA(dst, b, h) do { _Pragma("unroll") for (int m = 0; m < 4; ++m) _Pragma("unroll") for (int k = 0; k < 2; ++k) dst[m][k] = *(const LAS bf16x8*)(lds + PG8_SA(b, h) + aoff + m * 2048 + k * 1024); } while (0)
; #define PG8_MMA(ai, bj, At, Bt) do { __builtin_amdgcn_s_setprio(1); _Pragma("unroll") for (int m = 0; m < 4; ++m) _Pragma("unroll") for (int n = 0; n < 2; ++n) _Pragma("unroll") for (int k = 0; k < 2; ++k) \
;         acc[ai][bj][m][n] = __builtin_amdgcn_mfma_f32_16x16x32_bf16(Bt[n][k], At[m][k], acc[ai][bj][m][n], 0, 0, 0); __builtin_amdgcn_s_setprio(0); } while (0)
; #define PG8_WAIT_V(n) asm volatile("s_waitcnt vmcnt(" #n ")" ::: "memory")
; #define PG8_WAIT_L(n) asm volatile("s_waitcnt lgkmcnt(" #n ")" ::: "memory")
; #define PG8_BAR __builtin_amdgcn_s_barrier()
; #define PG8_SCHED __builtin_amdgcn_sched_barrier(0)
; template <class Sched, class Epi>
; __device__ __forceinline__ void gemm_run(LAS unsigned char* lds, const Sched& S, const Epi& E) {
;     ...
;             PG8_LDA(At, 1, 1); PG8_STAGE(PG8_SB(1, 0), b3, RB, lb2); PG8_STAGE(PG8_SB(1, 1), b3 + (size_t)HALF * lb2, RB, lb2); PG8_STAGE(PG8_SA(1, 0), a3, RA, la2);
;             PG8_WAIT_V(8); PG8_WAIT_L(0); PG8_BAR; PG8_MMA(1, 0, At, B0); PG8_MMA(1, 1, At, B1); PG8_BAR; PG8_SCHED;
;         }
;         if (wr == 0) PG8_BAR;
	s_add_i32 s39, s39, s3
	v_lshl_add_u64 v[174:175], v[174:175], 0, s[14:15]
	s_mov_b32 m0, s39
	ds_read_b128 v[198:201], v184 offset:49152
	ds_read_b128 v[202:205], v184 offset:50176
	ds_read_b128 v[206:209], v184 offset:51200
	ds_read_b128 v[210:213], v184 offset:52224
	ds_read_b128 v[214:217], v184 offset:53248
	ds_read_b128 v[218:221], v184 offset:54272
	ds_read_b128 v[222:225], v184 offset:55296
	ds_read_b128 v[226:229], v184 offset:56320
	global_load_lds_dwordx4 v[174:175], off
	s_add_i32 m0, s39, 0x2000
	s_add_u32 s40, s56, 0x80080
	v_lshl_add_u64 v[174:175], v[230:231], 0, s[14:15]
	s_addc_u32 s41, s57, 0
	global_load_lds_dwordx4 v[174:175], off
	v_lshl_add_u64 v[174:175], s[40:41], 0, v[132:133]
	s_add_i32 s39, s42, s3
	v_lshl_add_u64 v[174:175], v[174:175], 0, v[130:131]
	s_mov_b32 m0, s39
	s_nop 0
	global_load_lds_dwordx4 v[174:175], off
	v_lshl_add_u64 v[174:175], s[40:41], 0, v[136:137]
	v_lshl_add_u64 v[174:175], v[174:175], 0, v[130:131]
	s_add_i32 m0, s39, 0x2000
	s_nop 0
	global_load_lds_dwordx4 v[174:175], off
	v_lshl_add_u64 v[174:175], v[232:233], 0, s[14:15]
	s_mov_b32 m0, s64
	s_nop 0
	global_load_lds_dwordx4 v[174:175], off
	v_lshl_add_u64 v[174:175], v[234:235], 0, s[14:15]
	s_mov_b32 m0, s65
	s_nop 0
	global_load_lds_dwordx4 v[174:175], off
	s_waitcnt vmcnt(8)
	s_waitcnt lgkmcnt(0)
	s_barrier
	s_waitcnt lgkmcnt(0)
	v_mfma_f32_16x16x32_bf16 v[62:65], v[154:157], v[198:201], v[62:65]
	v_mfma_f32_16x16x32_bf16 v[58:61], v[162:165], v[198:201], v[58:61]
	v_mfma_f32_16x16x32_bf16 v[46:49], v[154:157], v[206:209], v[46:49]
	v_mfma_f32_16x16x32_bf16 v[42:45], v[162:165], v[206:209], v[42:45]
	v_mfma_f32_16x16x32_bf16 v[30:33], v[154:157], v[214:217], v[30:33]
	v_mfma_f32_16x16x32_bf16 v[26:29], v[162:165], v[214:217], v[26:29]
	v_mfma_f32_16x16x32_bf16 v[14:17], v[154:157], v[222:225], v[14:17]
	v_mfma_f32_16x16x32_bf16 v[10:13], v[162:165], v[222:225], v[10:13]
	v_mfma_f32_16x16x32_bf16 v[62:65], v[158:161], v[202:205], v[62:65]
	v_mfma_f32_16x16x32_bf16 v[58:61], v[166:169], v[202:205], v[58:61]
	v_mfma_f32_16x16x32_bf16 v[46:49], v[158:161], v[210:213], v[46:49]
	v_mfma_f32_16x16x32_bf16 v[42:45], v[166:169], v[210:213], v[42:45]
	v_mfma_f32_16x16x32_bf16 v[30:33], v[158:161], v[218:221], v[30:33]
	v_mfma_f32_16x16x32_bf16 v[26:29], v[166:169], v[218:221], v[26:29]
	v_mfma_f32_16x16x32_bf16 v[14:17], v[158:161], v[226:229], v[14:17]
	v_mfma_f32_16x16x32_bf16 v[10:13], v[166:169], v[226:229], v[10:13]
	v_mfma_f32_16x16x32_bf16 v[54:57], v[170:173], v[198:201], v[54:57]
	v_mfma_f32_16x16x32_bf16 v[50:53], v[190:193], v[198:201], v[50:53]
	v_mfma_f32_16x16x32_bf16 v[38:41], v[170:173], v[206:209], v[38:41]
	v_mfma_f32_16x16x32_bf16 v[34:37], v[190:193], v[206:209], v[34:37]
	v_mfma_f32_16x16x32_bf16 v[22:25], v[170:173], v[214:217], v[22:25]
	v_mfma_f32_16x16x32_bf16 v[18:21], v[190:193], v[214:217], v[18:21]
	v_mfma_f32_16x16x32_bf16 v[6:9], v[170:173], v[222:225], v[6:9]
	v_mfma_f32_16x16x32_bf16 v[2:5], v[190:193], v[222:225], v[2:5]
	v_mfma_f32_16x16x32_bf16 v[54:57], v[186:189], v[202:205], v[54:57]
	v_mfma_f32_16x16x32_bf16 v[50:53], v[194:197], v[202:205], v[50:53]
	v_mfma_f32_16x16x32_bf16 v[38:41], v[186:189], v[210:213], v[38:41]
	v_mfma_f32_16x16x32_bf16 v[34:37], v[194:197], v[210:213], v[34:37]
	v_mfma_f32_16x16x32_bf16 v[22:25], v[186:189], v[218:221], v[22:25]
	v_mfma_f32_16x16x32_bf16 v[18:21], v[194:197], v[218:221], v[18:21]
	v_mfma_f32_16x16x32_bf16 v[6:9], v[186:189], v[226:229], v[6:9]
	v_mfma_f32_16x16x32_bf16 v[2:5], v[194:197], v[226:229], v[2:5]
	s_barrier
	s_add_i32 s38, s38, 2
	s_add_u32 s54, s54, 0x100
	s_addc_u32 s55, s55, 0
	s_cmp_gt_u32 s38, 29
	s_cbranch_scc0 .LBB0_246
	s_and_b64 vcc, exec, s[16:17]
	s_cbranch_vccz .LBB0_249
	s_barrier

; #define PG8_STAGE(bufoff, gbase, RR, ld) do { _Pragma("unroll") for (int _i = 0; _i < 2; ++_i) \
;         __builtin_amdgcn_global_load_lds((const unsigned*)((const char*)(gbase) + (RR)[_i] * (ld) + C2[_i]), (LAS unsigned*)(lds + (bufoff) + ldsw + _i * 8192), 16, 0, 0); } while (0)
; #define PG8_LDA(dst, b, h) do { _Pragma("unroll") for (int m = 0; m < 4; ++m) _Pragma("unroll") for (int k = 0; k < 2; ++k) dst[m][k] = *(const LAS bf16x8*)(lds + PG8_SA(b, h) + aoff + m * 2048 + k * 1024); } while (0)
; #define PG8_LDB(dst, b, h) do { _Pragma("unroll") for (int n = 0; n < 2; ++n) _Pragma("unroll") for (int k = 0; k < 2; ++k) dst[n][k] = *(const LAS bf16x8*)(lds + PG8_SB(b, h) + boff + n * 2048 + k * 1024); } while (0)
; #define PG8_MMA(ai, bj, At, Bt) do { __builtin_amdgcn_s_setprio(1); _Pragma("unroll") for (int m = 0; m < 4; ++m) _Pragma("unroll") for (int n = 0; n < 2; ++n) _Pragma("unroll") for (int k = 0; k < 2; ++k) \
;         acc[ai][bj][m][n] = __builtin_amdgcn_mfma_f32_16x16x32_bf16(Bt[n][k], At[m][k], acc[ai][bj][m][n], 0, 0, 0); __builtin_amdgcn_s_setprio(0); } while (0)
; #define PG8_WAIT_V(n) asm volatile("s_waitcnt vmcnt(" #n ")" ::: "memory")
; #define PG8_WAIT_L(n) asm volatile("s_waitcnt lgkmcnt(" #n ")" ::: "memory")
; #define PG8_BAR __builtin_amdgcn_s_barrier()
; #define PG8_SCHED __builtin_amdgcn_sched_barrier(0)
; template <class Sched, class Epi>
; __device__ __forceinline__ void gemm_run(LAS unsigned char* lds, const Sched& S, const Epi& E) {
;     ...
;         for (int t = 0; t < nt; t += 2) {
;             const bool last = (t == nt - 2);
;             const char* a1 = cA + (size_t)(t + 1) * kstep;
;             const char* a2 = last ? nA : cA + (size_t)(t + 2) * kstep; const char* b2 = last ? nB : cB + (size_t)(t + 2) * kstep;
;             const unsigned la2 = last ? nlda : lda, lb2 = last ? nldb : ldb;
;             const char* a3 = a2 + kstep; const char* b3 = b2 + kstep;
;             PG8_LDB(B0, 0, 0); PG8_LDB(B1, 0, 1); PG8_SCHED; PG8_LDA(At, 0, 0); PG8_STAGE(PG8_SA(1, 1), a1 + (size_t)HALF * lda, RA, lda);
;             PG8_WAIT_V(8); PG8_WAIT_L(0); PG8_BAR; PG8_MMA(0, 0, At, B0); PG8_MMA(0, 1, At, B1); PG8_BAR; PG8_SCHED;
;             PG8_LDA(At, 0, 1); PG8_STAGE(PG8_SB(0, 0), b2, RB, lb2); PG8_STAGE(PG8_SB(0, 1), b2 + (size_t)HALF * lb2, RB, lb2); PG8_STAGE(PG8_SA(0, 0), a2, RA, la2);
.LBB0_440:
	s_add_i32 s41, s0, 2
	s_add_u32 s42, s58, s64
	s_addc_u32 s43, s59, s65
	ds_read_b128 v[134:137], v179
	ds_read_b128 v[138:141], v179 offset:1024
	ds_read_b128 v[142:145], v179 offset:2048
	ds_read_b128 v[162:165], v179 offset:3072
	ds_read_b128 v[166:169], v180
	ds_read_b128 v[186:189], v180 offset:1024
	ds_read_b128 v[190:193], v180 offset:2048
	ds_read_b128 v[194:197], v180 offset:3072
	s_add_u32 s46, s42, 0x100
	s_addc_u32 s47, s43, 0
	s_add_u32 s48, s39, s64
	s_addc_u32 s49, s40, s65
	s_cmp_eq_u32 s38, s0
	s_cselect_b64 s[42:43], -1, 0
	s_and_b64 s[44:45], s[42:43], exec
	s_cselect_b32 s67, s55, s47
	s_cselect_b32 s66, s61, s46
	s_cselect_b32 s71, vcc_lo, s49
	s_cselect_b32 s70, vcc_hi, s48
	s_and_b64 s[42:43], s[36:37], s[42:43]
	s_and_b64 s[42:43], s[42:43], exec
	s_cselect_b32 s0, s3, s60
	s_cselect_b32 s68, s4, s62
	v_lshl_add_u64 v[170:171], v[130:131], 0, s[64:65]
	s_add_i32 m0, s82, 0xc000
	ds_read_b128 v[198:201], v181
	ds_read_b128 v[202:205], v181 offset:1024
	ds_read_b128 v[206:209], v181 offset:2048
	ds_read_b128 v[210:213], v181 offset:3072
	ds_read_b128 v[214:217], v181 offset:4096
	ds_read_b128 v[218:221], v181 offset:5120
	ds_read_b128 v[222:225], v181 offset:6144
	ds_read_b128 v[226:229], v181 offset:7168
	global_load_lds_dwordx4 v[170:171], off
	v_lshl_add_u64 v[170:171], v[132:133], 0, s[64:65]
	s_add_i32 m0, s82, 0xe000
	s_nop 0
	global_load_lds_dwordx4 v[170:171], off
	s_waitcnt vmcnt(8)
	s_waitcnt lgkmcnt(0)
	s_barrier
	s_waitcnt lgkmcnt(0)
	v_mfma_f32_16x16x32_bf16 v[126:129], v[134:137], v[198:201], v[126:129]
	v_mfma_f32_16x16x32_bf16 v[122:125], v[142:145], v[198:201], v[122:125]
	v_mfma_f32_16x16x32_bf16 v[110:113], v[134:137], v[206:209], v[110:113]
	v_mfma_f32_16x16x32_bf16 v[106:109], v[142:145], v[206:209], v[106:109]
	v_mfma_f32_16x16x32_bf16 v[94:97], v[134:137], v[214:217], v[94:97]
	v_mfma_f32_16x16x32_bf16 v[90:93], v[142:145], v[214:217], v[90:93]
	v_mfma_f32_16x16x32_bf16 v[78:81], v[134:137], v[222:225], v[78:81]
	v_mfma_f32_16x16x32_bf16 v[74:77], v[142:145], v[222:225], v[74:77]
	v_mfma_f32_16x16x32_bf16 v[126:129], v[138:141], v[202:205], v[126:129]
	v_mfma_f32_16x16x32_bf16 v[122:125], v[162:165], v[202:205], v[122:125]
	v_mfma_f32_16x16x32_bf16 v[110:113], v[138:141], v[210:213], v[110:113]
	v_mfma_f32_16x16x32_bf16 v[106:109], v[162:165], v[210:213], v[106:109]
	v_mfma_f32_16x16x32_bf16 v[94:97], v[138:141], v[218:221], v[94:97]
	v_mfma_f32_16x16x32_bf16 v[90:93], v[162:165], v[218:221], v[90:93]
	v_mfma_f32_16x16x32_bf16 v[78:81], v[138:141], v[226:229], v[78:81]
	v_mfma_f32_16x16x32_bf16 v[74:77], v[162:165], v[226:229], v[74:77]
	v_mfma_f32_16x16x32_bf16 v[118:121], v[166:169], v[198:201], v[118:121]
	v_mfma_f32_16x16x32_bf16 v[114:117], v[190:193], v[198:201], v[114:117]
	v_mfma_f32_16x16x32_bf16 v[102:105], v[166:169], v[206:209], v[102:105]
	v_mfma_f32_16x16x32_bf16 v[98:101], v[190:193], v[206:209], v[98:101]
	v_mfma_f32_16x16x32_bf16 v[86:89], v[166:169], v[214:217], v[86:89]
	v_mfma_f32_16x16x32_bf16 v[82:85], v[190:193], v[214:217], v[82:85]
	v_mfma_f32_16x16x32_bf16 v[70:73], v[166:169], v[222:225], v[70:73]
	v_mfma_f32_16x16x32_bf16 v[66:69], v[190:193], v[222:225], v[66:69]
	v_mfma_f32_16x16x32_bf16 v[118:121], v[186:189], v[202:205], v[118:121]
	v_mfma_f32_16x16x32_bf16 v[114:117], v[194:197], v[202:205], v[114:117]
	v_mfma_f32_16x16x32_bf16 v[102:105], v[186:189], v[210:213], v[102:105]
	v_mfma_f32_16x16x32_bf16 v[98:101], v[194:197], v[210:213], v[98:101]
	v_mfma_f32_16x16x32_bf16 v[86:89], v[186:189], v[218:221], v[86:89]
	v_mfma_f32_16x16x32_bf16 v[82:85], v[194:197], v[218:221], v[82:85]
	v_mfma_f32_16x16x32_bf16 v[70:73], v[186:189], v[226:229], v[70:73]
	v_mfma_f32_16x16x32_bf16 v[66:69], v[194:197], v[226:229], v[66:69]
	s_barrier
	v_mul_lo_u32 v148, s0, v173
	v_lshl_add_u64 v[170:171], s[70:71], 0, v[148:149]
	s_add_i32 s42, s97, s81
	v_lshl_add_u64 v[170:171], v[170:171], 0, v[146:147]
	s_mov_b32 m0, s42
	ds_read_b128 v[198:201], v181 offset:16384
	ds_read_b128 v[202:205], v181 offset:17408
	ds_read_b128 v[206:209], v181 offset:18432
	ds_read_b128 v[210:213], v181 offset:19456
	ds_read_b128 v[214:217], v181 offset:20480
	ds_read_b128 v[218:221], v181 offset:21504
	ds_read_b128 v[222:225], v181 offset:22528
	ds_read_b128 v[226:229], v181 offset:23552
	global_load_lds_dwordx4 v[170:171], off
	s_add_i32 m0, s42, 0x2000
	s_lshl_b64 s[42:43], s[0:1], 7
	v_mul_lo_u32 v230, s0, v175
	v_mov_b32_e32 v231, v149
	s_add_u32 s42, s70, s42
	v_lshl_add_u64 v[232:233], s[70:71], 0, v[230:231]
	s_addc_u32 s43, s71, s43
	v_lshl_add_u64 v[232:233], v[232:233], 0, v[146:147]
	v_lshl_add_u64 v[234:235], s[42:43], 0, v[148:149]
	s_add_i32 s0, s33, s81
	global_load_lds_dwordx4 v[232:233], off
	v_lshl_add_u64 v[234:235], v[234:235], 0, v[146:147]
	s_mov_b32 m0, s0
	v_lshl_add_u64 v[230:231], s[42:43], 0, v[230:231]
	v_mul_lo_u32 v148, s68, v172
	global_load_lds_dwordx4 v[234:235], off
	v_lshl_add_u64 v[230:231], v[230:231], 0, v[146:147]
	s_add_i32 m0, s0, 0x2000
	v_lshl_add_u64 v[236:237], s[66:67], 0, v[148:149]
	v_mul_lo_u32 v238, s68, v174
	v_mov_b32_e32 v239, v149
	global_load_lds_dwordx4 v[230:231], off
	v_lshl_add_u64 v[236:237], v[236:237], 0, v[146:147]
	s_mov_b32 m0, s82
	v_lshl_add_u64 v[240:241], s[66:67], 0, v[238:239]
	global_load_lds_dwordx4 v[236:237], off
	v_lshl_add_u64 v[240:241], v[240:241], 0, v[146:147]
	s_mov_b32 m0, s83
	s_nop 0
	global_load_lds_dwordx4 v[240:241], off
	s_waitcnt vmcnt(8)
	s_waitcnt lgkmcnt(0)
	s_barrier
; #define PG8_STAGE(bufoff, gbase, RR, ld) do { _Pragma("unroll") for (int _i = 0; _i < 2; ++_i) \
;         __builtin_amdgcn_global_load_lds((const unsigned*)((const char*)(gbase) + (RR)[_i] * (ld) + C2[_i]), (LAS unsigned*)(lds + (bufoff) + ldsw + _i * 8192), 16, 0, 0); } while (0)
; #define PG8_LDA(dst, b, h) do { _Pragma("unroll") for (int m = 0; m < 4; ++m) _Pragma("unroll") for (int k = 0; k < 2; ++k) dst[m][k] = *(const LAS bf16x8*)(lds + PG8_SA(b, h) + aoff + m * 2048 + k * 1024); } while (0)
; #define PG8_LDB(dst, b, h) do { _Pragma("unroll") for (int n = 0; n < 2; ++n) _Pragma("unroll") for (int k = 0; k < 2; ++k) dst[n][k] = *(const LAS bf16x8*)(lds + PG8_SB(b, h) + boff + n * 2048 + k * 1024); } while (0)
; #define PG8_MMA(ai, bj, At, Bt) do { __builtin_amdgcn_s_setprio(1); _Pragma("unroll") for (int m = 0; m < 4; ++m) _Pragma("unroll") for (int n = 0; n < 2; ++n) _Pragma("unroll") for (int k = 0; k < 2; ++k) \
;         acc[ai][bj][m][n] = __builtin_amdgcn_mfma_f32_16x16x32_bf16(Bt[n][k], At[m][k], acc[ai][bj][m][n], 0, 0, 0); __builtin_amdgcn_s_setprio(0); } while (0)
; #define PG8_WAIT_V(n) asm volatile("s_waitcnt vmcnt(" #n ")" ::: "memory")
; #define PG8_WAIT_L(n) asm volatile("s_waitcnt lgkmcnt(" #n ")" ::: "memory")
; #define PG8_BAR __builtin_amdgcn_s_barrier()
; #define PG8_SCHED __builtin_amdgcn_sched_barrier(0)
; template <class Sched, class Epi>
; __device__ __forceinline__ void gemm_run(LAS unsigned char* lds, const Sched& S, const Epi& E) {
;     ...
;             PG8_WAIT_V(8); PG8_WAIT_L(0); PG8_BAR; PG8_MMA(1, 0, At, B0); PG8_MMA(1, 1, At, B1); PG8_BAR; PG8_SCHED;
;             PG8_LDB(B0, 1, 0); PG8_LDB(B1, 1, 1); PG8_SCHED; PG8_LDA(At, 1, 0); PG8_STAGE(PG8_SA(0, 1), a2 + (size_t)HALF * la2, RA, la2);
;             PG8_WAIT_V(8); PG8_WAIT_L(0); PG8_BAR; PG8_MMA(0, 0, At, B0); PG8_MMA(0, 1, At, B1); PG8_BAR; PG8_SCHED;
	s_waitcnt lgkmcnt(0)
	v_mfma_f32_16x16x32_bf16 v[62:65], v[134:137], v[198:201], v[62:65]
	v_mfma_f32_16x16x32_bf16 v[58:61], v[142:145], v[198:201], v[58:61]
	v_mfma_f32_16x16x32_bf16 v[46:49], v[134:137], v[206:209], v[46:49]
	v_mfma_f32_16x16x32_bf16 v[42:45], v[142:145], v[206:209], v[42:45]
	v_mfma_f32_16x16x32_bf16 v[30:33], v[134:137], v[214:217], v[30:33]
	v_mfma_f32_16x16x32_bf16 v[26:29], v[142:145], v[214:217], v[26:29]
	v_mfma_f32_16x16x32_bf16 v[14:17], v[134:137], v[222:225], v[14:17]
	v_mfma_f32_16x16x32_bf16 v[10:13], v[142:145], v[222:225], v[10:13]
	v_mfma_f32_16x16x32_bf16 v[62:65], v[138:141], v[202:205], v[62:65]
	v_mfma_f32_16x16x32_bf16 v[58:61], v[162:165], v[202:205], v[58:61]
	v_mfma_f32_16x16x32_bf16 v[46:49], v[138:141], v[210:213], v[46:49]
	v_mfma_f32_16x16x32_bf16 v[42:45], v[162:165], v[210:213], v[42:45]
	v_mfma_f32_16x16x32_bf16 v[30:33], v[138:141], v[218:221], v[30:33]
	v_mfma_f32_16x16x32_bf16 v[26:29], v[162:165], v[218:221], v[26:29]
	v_mfma_f32_16x16x32_bf16 v[14:17], v[138:141], v[226:229], v[14:17]
	v_mfma_f32_16x16x32_bf16 v[10:13], v[162:165], v[226:229], v[10:13]
	v_mfma_f32_16x16x32_bf16 v[54:57], v[166:169], v[198:201], v[54:57]
	v_mfma_f32_16x16x32_bf16 v[50:53], v[190:193], v[198:201], v[50:53]
	v_mfma_f32_16x16x32_bf16 v[38:41], v[166:169], v[206:209], v[38:41]
	v_mfma_f32_16x16x32_bf16 v[34:37], v[190:193], v[206:209], v[34:37]
	v_mfma_f32_16x16x32_bf16 v[22:25], v[166:169], v[214:217], v[22:25]
	v_mfma_f32_16x16x32_bf16 v[18:21], v[190:193], v[214:217], v[18:21]
	v_mfma_f32_16x16x32_bf16 v[6:9], v[166:169], v[222:225], v[6:9]
	v_mfma_f32_16x16x32_bf16 v[2:5], v[190:193], v[222:225], v[2:5]
	v_mfma_f32_16x16x32_bf16 v[54:57], v[186:189], v[202:205], v[54:57]
	v_mfma_f32_16x16x32_bf16 v[50:53], v[194:197], v[202:205], v[50:53]
	v_mfma_f32_16x16x32_bf16 v[38:41], v[186:189], v[210:213], v[38:41]
	v_mfma_f32_16x16x32_bf16 v[34:37], v[194:197], v[210:213], v[34:37]
	v_mfma_f32_16x16x32_bf16 v[22:25], v[186:189], v[218:221], v[22:25]
	v_mfma_f32_16x16x32_bf16 v[18:21], v[194:197], v[218:221], v[18:21]
	v_mfma_f32_16x16x32_bf16 v[6:9], v[186:189], v[226:229], v[6:9]
	v_mfma_f32_16x16x32_bf16 v[2:5], v[194:197], v[226:229], v[2:5]
	s_barrier
	s_add_i32 s0, 0, 0x18000
	s_add_i32 s44, 0, 0x1c000
	v_add_u32_e32 v162, s0, v176
	v_add_u32_e32 v185, s44, v176
	ds_read_b128 v[134:137], v162
	ds_read_b128 v[138:141], v162 offset:1024
	ds_read_b128 v[142:145], v162 offset:2048
	ds_read_b128 v[162:165], v162 offset:3072
	ds_read_b128 v[166:169], v185
	ds_read_b128 v[186:189], v185 offset:1024
	ds_read_b128 v[190:193], v185 offset:2048
	ds_read_b128 v[194:197], v185 offset:3072
	s_mov_b32 s69, s1
	s_lshl_b64 s[42:43], s[68:69], 7
	s_add_u32 s42, s66, s42
	s_addc_u32 s43, s67, s43
	v_lshl_add_u64 v[242:243], s[42:43], 0, v[148:149]
	s_mov_b32 m0, s85
	v_lshl_add_u64 v[242:243], v[242:243], 0, v[146:147]
	v_lshl_add_u64 v[238:239], s[42:43], 0, v[238:239]
	ds_read_b128 v[198:201], v181 offset:32768
	ds_read_b128 v[202:205], v181 offset:33792
	ds_read_b128 v[206:209], v181 offset:34816
	ds_read_b128 v[210:213], v181 offset:35840
	ds_read_b128 v[214:217], v181 offset:36864
	ds_read_b128 v[218:221], v181 offset:37888
	ds_read_b128 v[222:225], v181 offset:38912
	ds_read_b128 v[226:229], v181 offset:39936
	global_load_lds_dwordx4 v[242:243], off
	v_lshl_add_u64 v[238:239], v[238:239], 0, v[146:147]
	s_mov_b32 m0, s90
	s_nop 0
	global_load_lds_dwordx4 v[238:239], off
	s_waitcnt vmcnt(8)
	s_waitcnt lgkmcnt(0)
	s_barrier
	s_waitcnt lgkmcnt(0)
	v_mfma_f32_16x16x32_bf16 v[126:129], v[134:137], v[198:201], v[126:129]
	v_mfma_f32_16x16x32_bf16 v[122:125], v[142:145], v[198:201], v[122:125]
	v_mfma_f32_16x16x32_bf16 v[110:113], v[134:137], v[206:209], v[110:113]
	v_mfma_f32_16x16x32_bf16 v[106:109], v[142:145], v[206:209], v[106:109]
	v_mfma_f32_16x16x32_bf16 v[94:97], v[134:137], v[214:217], v[94:97]
	v_mfma_f32_16x16x32_bf16 v[90:93], v[142:145], v[214:217], v[90:93]
	v_mfma_f32_16x16x32_bf16 v[78:81], v[134:137], v[222:225], v[78:81]
	v_mfma_f32_16x16x32_bf16 v[74:77], v[142:145], v[222:225], v[74:77]
	v_mfma_f32_16x16x32_bf16 v[126:129], v[138:141], v[202:205], v[126:129]
	v_mfma_f32_16x16x32_bf16 v[122:125], v[162:165], v[202:205], v[122:125]
	v_mfma_f32_16x16x32_bf16 v[110:113], v[138:141], v[210:213], v[110:113]
	v_mfma_f32_16x16x32_bf16 v[106:109], v[162:165], v[210:213], v[106:109]
	v_mfma_f32_16x16x32_bf16 v[94:97], v[138:141], v[218:221], v[94:97]
	v_mfma_f32_16x16x32_bf16 v[90:93], v[162:165], v[218:221], v[90:93]
	v_mfma_f32_16x16x32_bf16 v[78:81], v[138:141], v[226:229], v[78:81]
	v_mfma_f32_16x16x32_bf16 v[74:77], v[162:165], v[226:229], v[74:77]
	v_mfma_f32_16x16x32_bf16 v[118:121], v[166:169], v[198:201], v[118:121]
	v_mfma_f32_16x16x32_bf16 v[114:117], v[190:193], v[198:201], v[114:117]
	v_mfma_f32_16x16x32_bf16 v[102:105], v[166:169], v[206:209], v[102:105]
	v_mfma_f32_16x16x32_bf16 v[98:101], v[190:193], v[206:209], v[98:101]
	v_mfma_f32_16x16x32_bf16 v[86:89], v[166:169], v[214:217], v[86:89]
	v_mfma_f32_16x16x32_bf16 v[82:85], v[190:193], v[214:217], v[82:85]
	v_mfma_f32_16x16x32_bf16 v[70:73], v[166:169], v[222:225], v[70:73]
	v_mfma_f32_16x16x32_bf16 v[66:69], v[190:193], v[222:225], v[66:69]
	v_mfma_f32_16x16x32_bf16 v[118:121], v[186:189], v[202:205], v[118:121]
	v_mfma_f32_16x16x32_bf16 v[114:117], v[194:197], v[202:205], v[114:117]
	v_mfma_f32_16x16x32_bf16 v[102:105], v[186:189], v[210:213], v[102:105]
	v_mfma_f32_16x16x32_bf16 v[98:101], v[194:197], v[210:213], v[98:101]
	v_mfma_f32_16x16x32_bf16 v[86:89], v[186:189], v[218:221], v[86:89]
	v_mfma_f32_16x16x32_bf16 v[82:85], v[194:197], v[218:221], v[82:85]
	v_mfma_f32_16x16x32_bf16 v[70:73], v[186:189], v[226:229], v[70:73]
	v_mfma_f32_16x16x32_bf16 v[66:69], v[194:197], v[226:229], v[66:69]
	s_barrier
; #define PG8_STAGE(bufoff, gbase, RR, ld) do { _Pragma("unroll") for (int _i = 0; _i < 2; ++_i) \
;         __builtin_amdgcn_global_load_lds((const unsigned*)((const char*)(gbase) + (RR)[_i] * (ld) + C2[_i]), (LAS unsigned*)(lds + (bufoff) + ldsw + _i * 8192), 16, 0, 0); } while (0)
; #define PG8_LDA(dst, b, h) do { _Pragma("unroll") for (int m = 0; m < 4; ++m) _Pragma("unroll") for (int k = 0; k < 2; ++k) dst[m][k] = *(const LAS bf16x8*)(lds + PG8_SA(b, h) + aoff + m * 2048 + k * 1024); } while (0)
; #define PG8_MMA(ai, bj, At, Bt) do { __builtin_amdgcn_s_setprio(1); _Pragma("unroll") for (int m = 0; m < 4; ++m) _Pragma("unroll") for (int n = 0; n < 2; ++n) _Pragma("unroll") for (int k = 0; k < 2; ++k) \
;         acc[ai][bj][m][n] = __builtin_amdgcn_mfma_f32_16x16x32_bf16(Bt[n][k], At[m][k], acc[ai][bj][m][n], 0, 0, 0); __builtin_amdgcn_s_setprio(0); } while (0)
; #define PG8_WAIT_V(n) asm volatile("s_waitcnt vmcnt(" #n ")" ::: "memory")
; #define PG8_WAIT_L(n) asm volatile("s_waitcnt lgkmcnt(" #n ")" ::: "memory")
; #define PG8_BAR __builtin_amdgcn_s_barrier()
; #define PG8_SCHED __builtin_amdgcn_sched_barrier(0)
; template <class Sched, class Epi>
; __device__ __forceinline__ void gemm_run(LAS unsigned char* lds, const Sched& S, const Epi& E) {
;     ...
;             PG8_LDA(At, 1, 1); PG8_STAGE(PG8_SB(1, 0), b3, RB, lb2); PG8_STAGE(PG8_SB(1, 1), b3 + (size_t)HALF * lb2, RB, lb2); PG8_STAGE(PG8_SA(1, 0), a3, RA, la2);
;             PG8_WAIT_V(8); PG8_WAIT_L(0); PG8_BAR; PG8_MMA(1, 0, At, B0); PG8_MMA(1, 1, At, B1); PG8_BAR; PG8_SCHED;
;         }
;         if (wr == 0) PG8_BAR;
	s_add_i32 s0, s0, s81
	v_lshl_add_u64 v[170:171], v[170:171], 0, s[8:9]
	s_mov_b32 m0, s0
	ds_read_b128 v[198:201], v181 offset:49152
	ds_read_b128 v[202:205], v181 offset:50176
	ds_read_b128 v[206:209], v181 offset:51200
	ds_read_b128 v[210:213], v181 offset:52224
	ds_read_b128 v[214:217], v181 offset:53248
	ds_read_b128 v[218:221], v181 offset:54272
	ds_read_b128 v[222:225], v181 offset:55296
	ds_read_b128 v[226:229], v181 offset:56320
	global_load_lds_dwordx4 v[170:171], off
	v_lshl_add_u64 v[170:171], v[232:233], 0, s[8:9]
	s_add_i32 m0, s0, 0x2000
	s_add_i32 s0, s44, s81
	global_load_lds_dwordx4 v[170:171], off
	v_lshl_add_u64 v[170:171], v[234:235], 0, s[8:9]
	s_mov_b32 m0, s0
	s_nop 0
	global_load_lds_dwordx4 v[170:171], off
	v_lshl_add_u64 v[170:171], v[230:231], 0, s[8:9]
	s_add_i32 m0, s0, 0x2000
	s_nop 0
	global_load_lds_dwordx4 v[170:171], off
	v_lshl_add_u64 v[170:171], v[236:237], 0, s[8:9]
	s_mov_b32 m0, s93
	s_nop 0
	global_load_lds_dwordx4 v[170:171], off
	v_lshl_add_u64 v[170:171], v[240:241], 0, s[8:9]
	s_mov_b32 m0, s94
	s_nop 0
	global_load_lds_dwordx4 v[170:171], off
	s_waitcnt vmcnt(8)
	s_waitcnt lgkmcnt(0)
	s_barrier
	s_waitcnt lgkmcnt(0)
	v_mfma_f32_16x16x32_bf16 v[62:65], v[134:137], v[198:201], v[62:65]
	v_mfma_f32_16x16x32_bf16 v[58:61], v[142:145], v[198:201], v[58:61]
	v_mfma_f32_16x16x32_bf16 v[46:49], v[134:137], v[206:209], v[46:49]
	v_mfma_f32_16x16x32_bf16 v[42:45], v[142:145], v[206:209], v[42:45]
	v_mfma_f32_16x16x32_bf16 v[30:33], v[134:137], v[214:217], v[30:33]
	v_mfma_f32_16x16x32_bf16 v[26:29], v[142:145], v[214:217], v[26:29]
	v_mfma_f32_16x16x32_bf16 v[14:17], v[134:137], v[222:225], v[14:17]
	v_mfma_f32_16x16x32_bf16 v[10:13], v[142:145], v[222:225], v[10:13]
	v_mfma_f32_16x16x32_bf16 v[62:65], v[138:141], v[202:205], v[62:65]
	v_mfma_f32_16x16x32_bf16 v[58:61], v[162:165], v[202:205], v[58:61]
	v_mfma_f32_16x16x32_bf16 v[46:49], v[138:141], v[210:213], v[46:49]
	v_mfma_f32_16x16x32_bf16 v[42:45], v[162:165], v[210:213], v[42:45]
	v_mfma_f32_16x16x32_bf16 v[30:33], v[138:141], v[218:221], v[30:33]
	v_mfma_f32_16x16x32_bf16 v[26:29], v[162:165], v[218:221], v[26:29]
	v_mfma_f32_16x16x32_bf16 v[14:17], v[138:141], v[226:229], v[14:17]
	v_mfma_f32_16x16x32_bf16 v[10:13], v[162:165], v[226:229], v[10:13]
	v_mfma_f32_16x16x32_bf16 v[54:57], v[166:169], v[198:201], v[54:57]
	v_mfma_f32_16x16x32_bf16 v[50:53], v[190:193], v[198:201], v[50:53]
	v_mfma_f32_16x16x32_bf16 v[38:41], v[166:169], v[206:209], v[38:41]
	v_mfma_f32_16x16x32_bf16 v[34:37], v[190:193], v[206:209], v[34:37]
	v_mfma_f32_16x16x32_bf16 v[22:25], v[166:169], v[214:217], v[22:25]
	v_mfma_f32_16x16x32_bf16 v[18:21], v[190:193], v[214:217], v[18:21]
	v_mfma_f32_16x16x32_bf16 v[6:9], v[166:169], v[222:225], v[6:9]
	v_mfma_f32_16x16x32_bf16 v[2:5], v[190:193], v[222:225], v[2:5]
	v_mfma_f32_16x16x32_bf16 v[54:57], v[186:189], v[202:205], v[54:57]
	v_mfma_f32_16x16x32_bf16 v[50:53], v[194:197], v[202:205], v[50:53]
	v_mfma_f32_16x16x32_bf16 v[38:41], v[186:189], v[210:213], v[38:41]
	v_mfma_f32_16x16x32_bf16 v[34:37], v[194:197], v[210:213], v[34:37]
	v_mfma_f32_16x16x32_bf16 v[22:25], v[186:189], v[218:221], v[22:25]
	v_mfma_f32_16x16x32_bf16 v[18:21], v[194:197], v[218:221], v[18:21]
	v_mfma_f32_16x16x32_bf16 v[6:9], v[186:189], v[226:229], v[6:9]
	v_mfma_f32_16x16x32_bf16 v[2:5], v[194:197], v[226:229], v[2:5]
	s_barrier
	s_add_u32 s64, s64, 0x100
	s_addc_u32 s65, s65, 0
	s_cmp_ge_i32 s41, s5
	s_mov_b32 s0, s41
	s_cbranch_scc0 .LBB0_440
	s_and_b64 vcc, exec, s[10:11]
	s_cbranch_vccz .LBB0_443
	s_barrier

; #define PG8_STAGE(bufoff, gbase, RR, ld) do { _Pragma("unroll") for (int _i = 0; _i < 2; ++_i) \
;         __builtin_amdgcn_global_load_lds((const unsigned*)((const char*)(gbase) + (RR)[_i] * (ld) + C2[_i]), (LAS unsigned*)(lds + (bufoff) + ldsw + _i * 8192), 16, 0, 0); } while (0)
; #define PG8_LDA(dst, b, h) do { _Pragma("unroll") for (int m = 0; m < 4; ++m) _Pragma("unroll") for (int k = 0; k < 2; ++k) dst[m][k] = *(const LAS bf16x8*)(lds + PG8_SA(b, h) + aoff + m * 2048 + k * 1024); } while (0)
; #define PG8_LDB(dst, b, h) do { _Pragma("unroll") for (int n = 0; n < 2; ++n) _Pragma("unroll") for (int k = 0; k < 2; ++k) dst[n][k] = *(const LAS bf16x8*)(lds + PG8_SB(b, h) + boff + n * 2048 + k * 1024); } while (0)
; #define PG8_MMA(ai, bj, At, Bt) do { __builtin_amdgcn_s_setprio(1); _Pragma("unroll") for (int m = 0; m < 4; ++m) _Pragma("unroll") for (int n = 0; n < 2; ++n) _Pragma("unroll") for (int k = 0; k < 2; ++k) \
;         acc[ai][bj][m][n] = __builtin_amdgcn_mfma_f32_16x16x32_bf16(Bt[n][k], At[m][k], acc[ai][bj][m][n], 0, 0, 0); __builtin_amdgcn_s_setprio(0); } while (0)
; #define PG8_WAIT_V(n) asm volatile("s_waitcnt vmcnt(" #n ")" ::: "memory")
; #define PG8_WAIT_L(n) asm volatile("s_waitcnt lgkmcnt(" #n ")" ::: "memory")
; #define PG8_BAR __builtin_amdgcn_s_barrier()
; #define PG8_SCHED __builtin_amdgcn_sched_barrier(0)
; template <class Sched, class Epi>
; __device__ __forceinline__ void gemm_run(LAS unsigned char* lds, const Sched& S, const Epi& E) {
;     ...
;         for (int t = 0; t < nt; t += 2) {
;             const bool last = (t == nt - 2);
;             const char* a1 = cA + (size_t)(t + 1) * kstep;
;             const char* a2 = last ? nA : cA + (size_t)(t + 2) * kstep; const char* b2 = last ? nB : cB + (size_t)(t + 2) * kstep;
;             const unsigned la2 = last ? nlda : lda, lb2 = last ? nldb : ldb;
;             const char* a3 = a2 + kstep; const char* b3 = b2 + kstep;
;             PG8_LDB(B0, 0, 0); PG8_LDB(B1, 0, 1); PG8_SCHED; PG8_LDA(At, 0, 0); PG8_STAGE(PG8_SA(1, 1), a1 + (size_t)HALF * lda, RA, lda);
;             PG8_WAIT_V(8); PG8_WAIT_L(0); PG8_BAR; PG8_MMA(0, 0, At, B0); PG8_MMA(0, 1, At, B1); PG8_BAR; PG8_SCHED;
;             PG8_LDA(At, 0, 1); PG8_STAGE(PG8_SB(0, 0), b2, RB, lb2); PG8_STAGE(PG8_SB(0, 1), b2 + (size_t)HALF * lb2, RB, lb2); PG8_STAGE(PG8_SA(0, 0), a2, RA, la2);
.LBB0_700:
	ds_read_b128 v[166:169], v160
	ds_read_b128 v[170:173], v160 offset:1024
	ds_read_b128 v[174:177], v160 offset:2048
	ds_read_b128 v[178:181], v160 offset:3072
	ds_read_b128 v[182:185], v161
	ds_read_b128 v[186:189], v161 offset:1024
	ds_read_b128 v[190:193], v161 offset:2048
	ds_read_b128 v[194:197], v161 offset:3072
	s_add_u32 s22, s18, s20
	s_addc_u32 s23, s19, s21
	s_add_u32 s22, s22, 0x100
	s_addc_u32 s23, s23, 0
	s_add_u32 s41, s38, s20
	s_addc_u32 s42, s39, s21
	s_cmpk_eq_i32 s20, 0x200
	s_cselect_b32 s29, s13, s23
	s_cselect_b32 s28, s12, s22
	s_cselect_b32 s23, s15, s42
	s_cselect_b32 s22, s14, s41
	s_mov_b32 m0, s58
	v_lshl_add_u64 v[230:231], v[146:147], 0, s[20:21]
	ds_read_b128 v[198:201], v162
	ds_read_b128 v[202:205], v162 offset:1024
	ds_read_b128 v[206:209], v162 offset:2048
	ds_read_b128 v[210:213], v162 offset:3072
	ds_read_b128 v[214:217], v162 offset:4096
	ds_read_b128 v[218:221], v162 offset:5120
	ds_read_b128 v[222:225], v162 offset:6144
	ds_read_b128 v[226:229], v162 offset:7168
	global_load_lds_dwordx4 v[230:231], off
	v_lshl_add_u64 v[230:231], v[148:149], 0, s[20:21]
	s_mov_b32 m0, s59
	s_nop 0
	global_load_lds_dwordx4 v[230:231], off
	s_waitcnt vmcnt(8)
	s_waitcnt lgkmcnt(0)
	s_barrier
	s_waitcnt lgkmcnt(0)
	v_mfma_f32_16x16x32_bf16 v[126:129], v[166:169], v[198:201], v[126:129]
	v_mfma_f32_16x16x32_bf16 v[122:125], v[174:177], v[198:201], v[122:125]
	v_mfma_f32_16x16x32_bf16 v[110:113], v[166:169], v[206:209], v[110:113]
	v_mfma_f32_16x16x32_bf16 v[106:109], v[174:177], v[206:209], v[106:109]
	v_mfma_f32_16x16x32_bf16 v[94:97], v[166:169], v[214:217], v[94:97]
	v_mfma_f32_16x16x32_bf16 v[90:93], v[174:177], v[214:217], v[90:93]
	v_mfma_f32_16x16x32_bf16 v[78:81], v[166:169], v[222:225], v[78:81]
	v_mfma_f32_16x16x32_bf16 v[74:77], v[174:177], v[222:225], v[74:77]
	v_mfma_f32_16x16x32_bf16 v[126:129], v[170:173], v[202:205], v[126:129]
	v_mfma_f32_16x16x32_bf16 v[122:125], v[178:181], v[202:205], v[122:125]
	v_mfma_f32_16x16x32_bf16 v[110:113], v[170:173], v[210:213], v[110:113]
	v_mfma_f32_16x16x32_bf16 v[106:109], v[178:181], v[210:213], v[106:109]
	v_mfma_f32_16x16x32_bf16 v[94:97], v[170:173], v[218:221], v[94:97]
	v_mfma_f32_16x16x32_bf16 v[90:93], v[178:181], v[218:221], v[90:93]
	v_mfma_f32_16x16x32_bf16 v[78:81], v[170:173], v[226:229], v[78:81]
	v_mfma_f32_16x16x32_bf16 v[74:77], v[178:181], v[226:229], v[74:77]
	v_mfma_f32_16x16x32_bf16 v[118:121], v[182:185], v[198:201], v[118:121]
	v_mfma_f32_16x16x32_bf16 v[114:117], v[190:193], v[198:201], v[114:117]
	v_mfma_f32_16x16x32_bf16 v[102:105], v[182:185], v[206:209], v[102:105]
	v_mfma_f32_16x16x32_bf16 v[98:101], v[190:193], v[206:209], v[98:101]
	v_mfma_f32_16x16x32_bf16 v[86:89], v[182:185], v[214:217], v[86:89]
	v_mfma_f32_16x16x32_bf16 v[82:85], v[190:193], v[214:217], v[82:85]
	v_mfma_f32_16x16x32_bf16 v[70:73], v[182:185], v[222:225], v[70:73]
	v_mfma_f32_16x16x32_bf16 v[66:69], v[190:193], v[222:225], v[66:69]
	v_mfma_f32_16x16x32_bf16 v[118:121], v[186:189], v[202:205], v[118:121]
	v_mfma_f32_16x16x32_bf16 v[114:117], v[194:197], v[202:205], v[114:117]
	v_mfma_f32_16x16x32_bf16 v[102:105], v[186:189], v[210:213], v[102:105]
	v_mfma_f32_16x16x32_bf16 v[98:101], v[194:197], v[210:213], v[98:101]
	v_mfma_f32_16x16x32_bf16 v[86:89], v[186:189], v[218:221], v[86:89]
	v_mfma_f32_16x16x32_bf16 v[82:85], v[194:197], v[218:221], v[82:85]
	v_mfma_f32_16x16x32_bf16 v[70:73], v[186:189], v[226:229], v[70:73]
	v_mfma_f32_16x16x32_bf16 v[66:69], v[194:197], v[226:229], v[66:69]
	s_barrier
	v_lshl_add_u64 v[230:231], s[22:23], 0, v[132:133]
	s_add_u32 s42, s22, 0x18000
	s_mov_b32 m0, s60
	v_lshl_add_u64 v[230:231], v[230:231], 0, v[130:131]
	v_lshl_add_u64 v[232:233], s[22:23], 0, v[136:137]
	s_addc_u32 s43, s23, 0
	ds_read_b128 v[198:201], v162 offset:16384
	ds_read_b128 v[202:205], v162 offset:17408
	ds_read_b128 v[206:209], v162 offset:18432
	ds_read_b128 v[210:213], v162 offset:19456
	ds_read_b128 v[214:217], v162 offset:20480
	ds_read_b128 v[218:221], v162 offset:21504
	ds_read_b128 v[222:225], v162 offset:22528
	ds_read_b128 v[226:229], v162 offset:23552
	global_load_lds_dwordx4 v[230:231], off
	v_lshl_add_u64 v[232:233], v[232:233], 0, v[130:131]
	s_mov_b32 m0, s61
	v_lshl_add_u64 v[234:235], s[42:43], 0, v[132:133]
	global_load_lds_dwordx4 v[232:233], off
	v_lshl_add_u64 v[234:235], v[234:235], 0, v[130:131]
	s_mov_b32 m0, s62
	v_lshl_add_u64 v[236:237], s[28:29], 0, v[140:141]
	global_load_lds_dwordx4 v[234:235], off
	v_lshl_add_u64 v[234:235], s[42:43], 0, v[136:137]
	v_lshl_add_u64 v[234:235], v[234:235], 0, v[130:131]
	s_mov_b32 m0, s63
	v_lshl_add_u64 v[236:237], v[236:237], 0, v[130:131]
	global_load_lds_dwordx4 v[234:235], off
	v_lshl_add_u64 v[234:235], s[28:29], 0, v[138:139]
	v_lshl_add_u64 v[234:235], v[234:235], 0, v[130:131]
	s_mov_b32 m0, s35
	s_nop 0
	global_load_lds_dwordx4 v[234:235], off
	s_mov_b32 m0, s36
	s_nop 0
	global_load_lds_dwordx4 v[236:237], off
	s_waitcnt vmcnt(8)
	s_waitcnt lgkmcnt(0)
	s_barrier
; #define PG8_STAGE(bufoff, gbase, RR, ld) do { _Pragma("unroll") for (int _i = 0; _i < 2; ++_i) \
;         __builtin_amdgcn_global_load_lds((const unsigned*)((const char*)(gbase) + (RR)[_i] * (ld) + C2[_i]), (LAS unsigned*)(lds + (bufoff) + ldsw + _i * 8192), 16, 0, 0); } while (0)
; #define PG8_LDA(dst, b, h) do { _Pragma("unroll") for (int m = 0; m < 4; ++m) _Pragma("unroll") for (int k = 0; k < 2; ++k) dst[m][k] = *(const LAS bf16x8*)(lds + PG8_SA(b, h) + aoff + m * 2048 + k * 1024); } while (0)
; #define PG8_LDB(dst, b, h) do { _Pragma("unroll") for (int n = 0; n < 2; ++n) _Pragma("unroll") for (int k = 0; k < 2; ++k) dst[n][k] = *(const LAS bf16x8*)(lds + PG8_SB(b, h) + boff + n * 2048 + k * 1024); } while (0)
; #define PG8_MMA(ai, bj, At, Bt) do { __builtin_amdgcn_s_setprio(1); _Pragma("unroll") for (int m = 0; m < 4; ++m) _Pragma("unroll") for (int n = 0; n < 2; ++n) _Pragma("unroll") for (int k = 0; k < 2; ++k) \
;         acc[ai][bj][m][n] = __builtin_amdgcn_mfma_f32_16x16x32_bf16(Bt[n][k], At[m][k], acc[ai][bj][m][n], 0, 0, 0); __builtin_amdgcn_s_setprio(0); } while (0)
; #define PG8_WAIT_V(n) asm volatile("s_waitcnt vmcnt(" #n ")" ::: "memory")
; #define PG8_WAIT_L(n) asm volatile("s_waitcnt lgkmcnt(" #n ")" ::: "memory")
; #define PG8_BAR __builtin_amdgcn_s_barrier()
; #define PG8_SCHED __builtin_amdgcn_sched_barrier(0)
; template <class Sched, class Epi>
; __device__ __forceinline__ void gemm_run(LAS unsigned char* lds, const Sched& S, const Epi& E) {
;     ...
;             PG8_WAIT_V(8); PG8_WAIT_L(0); PG8_BAR; PG8_MMA(1, 0, At, B0); PG8_MMA(1, 1, At, B1); PG8_BAR; PG8_SCHED;
;             PG8_LDB(B0, 1, 0); PG8_LDB(B1, 1, 1); PG8_SCHED; PG8_LDA(At, 1, 0); PG8_STAGE(PG8_SA(0, 1), a2 + (size_t)HALF * la2, RA, la2);
;             PG8_WAIT_V(8); PG8_WAIT_L(0); PG8_BAR; PG8_MMA(0, 0, At, B0); PG8_MMA(0, 1, At, B1); PG8_BAR; PG8_SCHED;
	s_waitcnt lgkmcnt(0)
	v_mfma_f32_16x16x32_bf16 v[62:65], v[166:169], v[198:201], v[62:65]
	v_mfma_f32_16x16x32_bf16 v[58:61], v[174:177], v[198:201], v[58:61]
	v_mfma_f32_16x16x32_bf16 v[46:49], v[166:169], v[206:209], v[46:49]
	v_mfma_f32_16x16x32_bf16 v[42:45], v[174:177], v[206:209], v[42:45]
	v_mfma_f32_16x16x32_bf16 v[30:33], v[166:169], v[214:217], v[30:33]
	v_mfma_f32_16x16x32_bf16 v[26:29], v[174:177], v[214:217], v[26:29]
	v_mfma_f32_16x16x32_bf16 v[14:17], v[166:169], v[222:225], v[14:17]
	v_mfma_f32_16x16x32_bf16 v[10:13], v[174:177], v[222:225], v[10:13]
	v_mfma_f32_16x16x32_bf16 v[62:65], v[170:173], v[202:205], v[62:65]
	v_mfma_f32_16x16x32_bf16 v[58:61], v[178:181], v[202:205], v[58:61]
	v_mfma_f32_16x16x32_bf16 v[46:49], v[170:173], v[210:213], v[46:49]
	v_mfma_f32_16x16x32_bf16 v[42:45], v[178:181], v[210:213], v[42:45]
	v_mfma_f32_16x16x32_bf16 v[30:33], v[170:173], v[218:221], v[30:33]
	v_mfma_f32_16x16x32_bf16 v[26:29], v[178:181], v[218:221], v[26:29]
	v_mfma_f32_16x16x32_bf16 v[14:17], v[170:173], v[226:229], v[14:17]
	v_mfma_f32_16x16x32_bf16 v[10:13], v[178:181], v[226:229], v[10:13]
	v_mfma_f32_16x16x32_bf16 v[54:57], v[182:185], v[198:201], v[54:57]
	v_mfma_f32_16x16x32_bf16 v[50:53], v[190:193], v[198:201], v[50:53]
	v_mfma_f32_16x16x32_bf16 v[38:41], v[182:185], v[206:209], v[38:41]
	v_mfma_f32_16x16x32_bf16 v[34:37], v[190:193], v[206:209], v[34:37]
	v_mfma_f32_16x16x32_bf16 v[22:25], v[182:185], v[214:217], v[22:25]
	v_mfma_f32_16x16x32_bf16 v[18:21], v[190:193], v[214:217], v[18:21]
	v_mfma_f32_16x16x32_bf16 v[6:9], v[182:185], v[222:225], v[6:9]
	v_mfma_f32_16x16x32_bf16 v[2:5], v[190:193], v[222:225], v[2:5]
	v_mfma_f32_16x16x32_bf16 v[54:57], v[186:189], v[202:205], v[54:57]
	v_mfma_f32_16x16x32_bf16 v[50:53], v[194:197], v[202:205], v[50:53]
	v_mfma_f32_16x16x32_bf16 v[38:41], v[186:189], v[210:213], v[38:41]
	v_mfma_f32_16x16x32_bf16 v[34:37], v[194:197], v[210:213], v[34:37]
	v_mfma_f32_16x16x32_bf16 v[22:25], v[186:189], v[218:221], v[22:25]
	v_mfma_f32_16x16x32_bf16 v[18:21], v[194:197], v[218:221], v[18:21]
	v_mfma_f32_16x16x32_bf16 v[6:9], v[186:189], v[226:229], v[6:9]
	v_mfma_f32_16x16x32_bf16 v[2:5], v[194:197], v[226:229], v[2:5]
	s_barrier
	ds_read_b128 v[166:169], v163
	ds_read_b128 v[170:173], v163 offset:1024
	ds_read_b128 v[174:177], v163 offset:2048
	ds_read_b128 v[178:181], v163 offset:3072
	ds_read_b128 v[182:185], v164
	ds_read_b128 v[186:189], v164 offset:1024
	ds_read_b128 v[190:193], v164 offset:2048
	ds_read_b128 v[194:197], v164 offset:3072
	s_add_u32 s28, s28, 0x18000
	s_addc_u32 s29, s29, 0
	v_lshl_add_u64 v[238:239], s[28:29], 0, v[138:139]
	s_mov_b32 m0, s37
	v_lshl_add_u64 v[238:239], v[238:239], 0, v[130:131]
	ds_read_b128 v[198:201], v162 offset:32768
	ds_read_b128 v[202:205], v162 offset:33792
	ds_read_b128 v[206:209], v162 offset:34816
	ds_read_b128 v[210:213], v162 offset:35840
	ds_read_b128 v[214:217], v162 offset:36864
	ds_read_b128 v[218:221], v162 offset:37888
	ds_read_b128 v[222:225], v162 offset:38912
	ds_read_b128 v[226:229], v162 offset:39936
	global_load_lds_dwordx4 v[238:239], off
	v_lshl_add_u64 v[238:239], s[28:29], 0, v[140:141]
	v_lshl_add_u64 v[238:239], v[238:239], 0, v[130:131]
	s_mov_b32 m0, s54
	s_nop 0
	global_load_lds_dwordx4 v[238:239], off
	s_waitcnt vmcnt(8)
	s_waitcnt lgkmcnt(0)
	s_barrier
	s_waitcnt lgkmcnt(0)
	v_mfma_f32_16x16x32_bf16 v[126:129], v[166:169], v[198:201], v[126:129]
	v_mfma_f32_16x16x32_bf16 v[122:125], v[174:177], v[198:201], v[122:125]
	v_mfma_f32_16x16x32_bf16 v[110:113], v[166:169], v[206:209], v[110:113]
	v_mfma_f32_16x16x32_bf16 v[106:109], v[174:177], v[206:209], v[106:109]
	v_mfma_f32_16x16x32_bf16 v[94:97], v[166:169], v[214:217], v[94:97]
	v_mfma_f32_16x16x32_bf16 v[90:93], v[174:177], v[214:217], v[90:93]
	v_mfma_f32_16x16x32_bf16 v[78:81], v[166:169], v[222:225], v[78:81]
	v_mfma_f32_16x16x32_bf16 v[74:77], v[174:177], v[222:225], v[74:77]
	v_mfma_f32_16x16x32_bf16 v[126:129], v[170:173], v[202:205], v[126:129]
	v_mfma_f32_16x16x32_bf16 v[122:125], v[178:181], v[202:205], v[122:125]
	v_mfma_f32_16x16x32_bf16 v[110:113], v[170:173], v[210:213], v[110:113]
	v_mfma_f32_16x16x32_bf16 v[106:109], v[178:181], v[210:213], v[106:109]
	v_mfma_f32_16x16x32_bf16 v[94:97], v[170:173], v[218:221], v[94:97]
	v_mfma_f32_16x16x32_bf16 v[90:93], v[178:181], v[218:221], v[90:93]
	v_mfma_f32_16x16x32_bf16 v[78:81], v[170:173], v[226:229], v[78:81]
	v_mfma_f32_16x16x32_bf16 v[74:77], v[178:181], v[226:229], v[74:77]
	v_mfma_f32_16x16x32_bf16 v[118:121], v[182:185], v[198:201], v[118:121]
	v_mfma_f32_16x16x32_bf16 v[114:117], v[190:193], v[198:201], v[114:117]
	v_mfma_f32_16x16x32_bf16 v[102:105], v[182:185], v[206:209], v[102:105]
	v_mfma_f32_16x16x32_bf16 v[98:101], v[190:193], v[206:209], v[98:101]
	v_mfma_f32_16x16x32_bf16 v[86:89], v[182:185], v[214:217], v[86:89]
	v_mfma_f32_16x16x32_bf16 v[82:85], v[190:193], v[214:217], v[82:85]
	v_mfma_f32_16x16x32_bf16 v[70:73], v[182:185], v[222:225], v[70:73]
	v_mfma_f32_16x16x32_bf16 v[66:69], v[190:193], v[222:225], v[66:69]
	v_mfma_f32_16x16x32_bf16 v[118:121], v[186:189], v[202:205], v[118:121]
	v_mfma_f32_16x16x32_bf16 v[114:117], v[194:197], v[202:205], v[114:117]
	v_mfma_f32_16x16x32_bf16 v[102:105], v[186:189], v[210:213], v[102:105]
	v_mfma_f32_16x16x32_bf16 v[98:101], v[194:197], v[210:213], v[98:101]
	v_mfma_f32_16x16x32_bf16 v[86:89], v[186:189], v[218:221], v[86:89]
	v_mfma_f32_16x16x32_bf16 v[82:85], v[194:197], v[218:221], v[82:85]
	v_mfma_f32_16x16x32_bf16 v[70:73], v[186:189], v[226:229], v[70:73]
	v_mfma_f32_16x16x32_bf16 v[66:69], v[194:197], v[226:229], v[66:69]
	s_barrier
; #define PG8_STAGE(bufoff, gbase, RR, ld) do { _Pragma("unroll") for (int _i = 0; _i < 2; ++_i) \
;         __builtin_amdgcn_global_load_lds((const unsigned*)((const char*)(gbase) + (RR)[_i] * (ld) + C2[_i]), (LAS unsigned*)(lds + (bufoff) + ldsw + _i * 8192), 16, 0, 0); } while (0)
; #define PG8_LDA(dst, b, h) do { _Pragma("unroll") for (int m = 0; m < 4; ++m) _Pragma("unroll") for (int k = 0; k < 2; ++k) dst[m][k] = *(const LAS bf16x8*)(lds + PG8_SA(b, h) + aoff + m * 2048 + k * 1024); } while (0)
; #define PG8_MMA(ai, bj, At, Bt) do { __builtin_amdgcn_s_setprio(1); _Pragma("unroll") for (int m = 0; m < 4; ++m) _Pragma("unroll") for (int n = 0; n < 2; ++n) _Pragma("unroll") for (int k = 0; k < 2; ++k) \
;         acc[ai][bj][m][n] = __builtin_amdgcn_mfma_f32_16x16x32_bf16(Bt[n][k], At[m][k], acc[ai][bj][m][n], 0, 0, 0); __builtin_amdgcn_s_setprio(0); } while (0)
; #define PG8_WAIT_V(n) asm volatile("s_waitcnt vmcnt(" #n ")" ::: "memory")
; #define PG8_WAIT_L(n) asm volatile("s_waitcnt lgkmcnt(" #n ")" ::: "memory")
; #define PG8_BAR __builtin_amdgcn_s_barrier()
; #define PG8_SCHED __builtin_amdgcn_sched_barrier(0)
; template <class Sched, class Epi>
; __device__ __forceinline__ void gemm_run(LAS unsigned char* lds, const Sched& S, const Epi& E) {
;     ...
;             PG8_LDA(At, 1, 1); PG8_STAGE(PG8_SB(1, 0), b3, RB, lb2); PG8_STAGE(PG8_SB(1, 1), b3 + (size_t)HALF * lb2, RB, lb2); PG8_STAGE(PG8_SA(1, 0), a3, RA, la2);
;             PG8_WAIT_V(8); PG8_WAIT_L(0); PG8_BAR; PG8_MMA(1, 0, At, B0); PG8_MMA(1, 1, At, B1); PG8_BAR; PG8_SCHED;
;         }
;         if (wr == 0) PG8_BAR;
	s_mov_b32 m0, s64
	v_lshl_add_u64 v[230:231], v[230:231], 0, s[6:7]
	s_add_u32 s22, s22, 0x18080
	ds_read_b128 v[198:201], v162 offset:49152
	ds_read_b128 v[202:205], v162 offset:50176
	ds_read_b128 v[206:209], v162 offset:51200
	ds_read_b128 v[210:213], v162 offset:52224
	ds_read_b128 v[214:217], v162 offset:53248
	ds_read_b128 v[218:221], v162 offset:54272
	ds_read_b128 v[222:225], v162 offset:55296
	ds_read_b128 v[226:229], v162 offset:56320
	global_load_lds_dwordx4 v[230:231], off
	v_lshl_add_u64 v[230:231], v[232:233], 0, s[6:7]
	s_mov_b32 m0, s65
	s_addc_u32 s23, s23, 0
	global_load_lds_dwordx4 v[230:231], off
	v_lshl_add_u64 v[230:231], s[22:23], 0, v[132:133]
	v_lshl_add_u64 v[230:231], v[230:231], 0, v[130:131]
	s_mov_b32 m0, s66
	s_nop 0
	global_load_lds_dwordx4 v[230:231], off
	v_lshl_add_u64 v[230:231], s[22:23], 0, v[136:137]
	v_lshl_add_u64 v[230:231], v[230:231], 0, v[130:131]
	s_mov_b32 m0, s67
	s_nop 0
	global_load_lds_dwordx4 v[230:231], off
	v_lshl_add_u64 v[230:231], v[234:235], 0, s[6:7]
	s_mov_b32 m0, s56
	s_nop 0
	global_load_lds_dwordx4 v[230:231], off
	v_lshl_add_u64 v[230:231], v[236:237], 0, s[6:7]
	s_mov_b32 m0, s57
	s_nop 0
	global_load_lds_dwordx4 v[230:231], off
	s_waitcnt vmcnt(8)
	s_waitcnt lgkmcnt(0)
	s_barrier
	s_waitcnt lgkmcnt(0)
	v_mfma_f32_16x16x32_bf16 v[62:65], v[166:169], v[198:201], v[62:65]
	v_mfma_f32_16x16x32_bf16 v[58:61], v[174:177], v[198:201], v[58:61]
	v_mfma_f32_16x16x32_bf16 v[46:49], v[166:169], v[206:209], v[46:49]
	v_mfma_f32_16x16x32_bf16 v[42:45], v[174:177], v[206:209], v[42:45]
	v_mfma_f32_16x16x32_bf16 v[30:33], v[166:169], v[214:217], v[30:33]
	v_mfma_f32_16x16x32_bf16 v[26:29], v[174:177], v[214:217], v[26:29]
	v_mfma_f32_16x16x32_bf16 v[14:17], v[166:169], v[222:225], v[14:17]
	v_mfma_f32_16x16x32_bf16 v[10:13], v[174:177], v[222:225], v[10:13]
	v_mfma_f32_16x16x32_bf16 v[62:65], v[170:173], v[202:205], v[62:65]
	v_mfma_f32_16x16x32_bf16 v[58:61], v[178:181], v[202:205], v[58:61]
	v_mfma_f32_16x16x32_bf16 v[46:49], v[170:173], v[210:213], v[46:49]
	v_mfma_f32_16x16x32_bf16 v[42:45], v[178:181], v[210:213], v[42:45]
	v_mfma_f32_16x16x32_bf16 v[30:33], v[170:173], v[218:221], v[30:33]
	v_mfma_f32_16x16x32_bf16 v[26:29], v[178:181], v[218:221], v[26:29]
	v_mfma_f32_16x16x32_bf16 v[14:17], v[170:173], v[226:229], v[14:17]
	v_mfma_f32_16x16x32_bf16 v[10:13], v[178:181], v[226:229], v[10:13]
	v_mfma_f32_16x16x32_bf16 v[54:57], v[182:185], v[198:201], v[54:57]
	v_mfma_f32_16x16x32_bf16 v[50:53], v[190:193], v[198:201], v[50:53]
	v_mfma_f32_16x16x32_bf16 v[38:41], v[182:185], v[206:209], v[38:41]
	v_mfma_f32_16x16x32_bf16 v[34:37], v[190:193], v[206:209], v[34:37]
	v_mfma_f32_16x16x32_bf16 v[22:25], v[182:185], v[214:217], v[22:25]
	v_mfma_f32_16x16x32_bf16 v[18:21], v[190:193], v[214:217], v[18:21]
	v_mfma_f32_16x16x32_bf16 v[6:9], v[182:185], v[222:225], v[6:9]
	v_mfma_f32_16x16x32_bf16 v[2:5], v[190:193], v[222:225], v[2:5]
	v_mfma_f32_16x16x32_bf16 v[54:57], v[186:189], v[202:205], v[54:57]
	v_mfma_f32_16x16x32_bf16 v[50:53], v[194:197], v[202:205], v[50:53]
	v_mfma_f32_16x16x32_bf16 v[38:41], v[186:189], v[210:213], v[38:41]
	v_mfma_f32_16x16x32_bf16 v[34:37], v[194:197], v[210:213], v[34:37]
	v_mfma_f32_16x16x32_bf16 v[22:25], v[186:189], v[218:221], v[22:25]
	v_mfma_f32_16x16x32_bf16 v[18:21], v[194:197], v[218:221], v[18:21]
	v_mfma_f32_16x16x32_bf16 v[6:9], v[186:189], v[226:229], v[6:9]
	v_mfma_f32_16x16x32_bf16 v[2:5], v[194:197], v[226:229], v[2:5]
	s_barrier
	s_add_i32 s40, s40, 2
	s_add_u32 s20, s20, 0x100
	s_addc_u32 s21, s21, 0
	s_cmp_gt_u32 s40, 3
	s_cbranch_scc0 .LBB0_700
	s_and_b64 vcc, exec, s[8:9]
	s_cbranch_vccz .LBB0_703
	s_barrier

; #define PG8_STAGE(bufoff, gbase, RR, ld) do { _Pragma("unroll") for (int _i = 0; _i < 2; ++_i) \
;         __builtin_amdgcn_global_load_lds((const unsigned*)((const char*)(gbase) + (RR)[_i] * (ld) + C2[_i]), (LAS unsigned*)(lds + (bufoff) + ldsw + _i * 8192), 16, 0, 0); } while (0)
; #define PG8_LDA(dst, b, h) do { _Pragma("unroll") for (int m = 0; m < 4; ++m) _Pragma("unroll") for (int k = 0; k < 2; ++k) dst[m][k] = *(const LAS bf16x8*)(lds + PG8_SA(b, h) + aoff + m * 2048 + k * 1024); } while (0)
; #define PG8_LDB(dst, b, h) do { _Pragma("unroll") for (int n = 0; n < 2; ++n) _Pragma("unroll") for (int k = 0; k < 2; ++k) dst[n][k] = *(const LAS bf16x8*)(lds + PG8_SB(b, h) + boff + n * 2048 + k * 1024); } while (0)
; #define PG8_MMA(ai, bj, At, Bt) do { __builtin_amdgcn_s_setprio(1); _Pragma("unroll") for (int m = 0; m < 4; ++m) _Pragma("unroll") for (int n = 0; n < 2; ++n) _Pragma("unroll") for (int k = 0; k < 2; ++k) \
;         acc[ai][bj][m][n] = __builtin_amdgcn_mfma_f32_16x16x32_bf16(Bt[n][k], At[m][k], acc[ai][bj][m][n], 0, 0, 0); __builtin_amdgcn_s_setprio(0); } while (0)
; #define PG8_WAIT_V(n) asm volatile("s_waitcnt vmcnt(" #n ")" ::: "memory")
; #define PG8_WAIT_L(n) asm volatile("s_waitcnt lgkmcnt(" #n ")" ::: "memory")
; template <class Sched, class Epi>
; __device__ __forceinline__ void gemm_run(LAS unsigned char* lds, const Sched& S, const Epi& E) {
;     ...
;         for (int t = 0; t < nt; t += 2) {
;             const bool last = (t == nt - 2);
;             const char* a1 = cA + (size_t)(t + 1) * kstep;
;             const char* a2 = last ? nA : cA + (size_t)(t + 2) * kstep; const char* b2 = last ? nB : cB + (size_t)(t + 2) * kstep;
;             const unsigned la2 = last ? nlda : lda, lb2 = last ? nldb : ldb;
;             const char* a3 = a2 + kstep; const char* b3 = b2 + kstep;
;             PG8_LDB(B0, 0, 0); PG8_LDB(B1, 0, 1); PG8_SCHED; PG8_LDA(At, 0, 0); PG8_STAGE(PG8_SA(1, 1), a1 + (size_t)HALF * lda, RA, lda);
;             PG8_WAIT_V(8); PG8_WAIT_L(0); PG8_BAR; PG8_MMA(0, 0, At, B0); PG8_MMA(0, 1, At, B1); PG8_BAR; PG8_SCHED;
;             PG8_LDA(At, 0, 1); PG8_STAGE(PG8_SB(0, 0), b2, RB, lb2); PG8_STAGE(PG8_SB(0, 1), b2 + (size_t)HALF * lb2, RB, lb2); PG8_STAGE(PG8_SA(0, 0), a2, RA, la2);
;             PG8_WAIT_V(8); PG8_WAIT_L(0); PG8_BAR; PG8_MMA(1, 0, At, B0); PG8_MMA(1, 1, At, B1); PG8_BAR; PG8_SCHED;
.LBB0_806:
	ds_read_b128 v[134:137], v193
	ds_read_b128 v[138:141], v193 offset:1024
	ds_read_b128 v[142:145], v193 offset:2048
	ds_read_b128 v[152:155], v193 offset:3072
	ds_read_b128 v[156:159], v194
	ds_read_b128 v[160:163], v194 offset:1024
	ds_read_b128 v[164:167], v194 offset:2048
	ds_read_b128 v[168:171], v194 offset:3072
	s_add_i32 s47, s6, 2
	s_add_u32 s48, s54, s58
	s_addc_u32 s49, s55, s59
	s_add_u32 s48, s48, 0x100
	s_addc_u32 s49, s49, 0
	s_add_u32 s50, s45, s58
	s_addc_u32 s51, s46, s59
	s_cmp_eq_u32 s44, s6
	s_cselect_b32 s6, s39, s82
	s_cselect_b32 s61, s31, s49
	s_cselect_b32 s60, s30, s48
	s_cselect_b32 s62, s80, s56
	s_cselect_b32 s49, s41, s51
	s_cselect_b32 s48, s40, s50
	v_lshl_add_u64 v[216:217], v[130:131], 0, s[58:59]
	s_add_i32 m0, s43, 0xc000
	ds_read_b128 v[172:175], v195
	ds_read_b128 v[176:179], v195 offset:1024
	ds_read_b128 v[180:183], v195 offset:2048
	ds_read_b128 v[196:199], v195 offset:3072
	ds_read_b128 v[200:203], v195 offset:4096
	ds_read_b128 v[204:207], v195 offset:5120
	ds_read_b128 v[208:211], v195 offset:6144
	ds_read_b128 v[212:215], v195 offset:7168
	global_load_lds_dwordx4 v[216:217], off
	v_lshl_add_u64 v[216:217], v[132:133], 0, s[58:59]
	s_add_i32 m0, s43, 0xe000
	s_nop 0
	global_load_lds_dwordx4 v[216:217], off
	s_waitcnt vmcnt(8)
	s_waitcnt lgkmcnt(0)
	s_barrier
	s_waitcnt lgkmcnt(0)
	v_mfma_f32_16x16x32_bf16 v[126:129], v[134:137], v[172:175], v[126:129]
	v_mfma_f32_16x16x32_bf16 v[118:121], v[142:145], v[172:175], v[118:121]
	v_mfma_f32_16x16x32_bf16 v[110:113], v[134:137], v[180:183], v[110:113]
	v_mfma_f32_16x16x32_bf16 v[102:105], v[142:145], v[180:183], v[102:105]
	v_mfma_f32_16x16x32_bf16 v[94:97], v[134:137], v[200:203], v[94:97]
	v_mfma_f32_16x16x32_bf16 v[86:89], v[142:145], v[200:203], v[86:89]
	v_mfma_f32_16x16x32_bf16 v[78:81], v[134:137], v[208:211], v[78:81]
	v_mfma_f32_16x16x32_bf16 v[70:73], v[142:145], v[208:211], v[70:73]
	v_mfma_f32_16x16x32_bf16 v[126:129], v[138:141], v[176:179], v[126:129]
	v_mfma_f32_16x16x32_bf16 v[118:121], v[152:155], v[176:179], v[118:121]
	v_mfma_f32_16x16x32_bf16 v[110:113], v[138:141], v[196:199], v[110:113]
	v_mfma_f32_16x16x32_bf16 v[102:105], v[152:155], v[196:199], v[102:105]
	v_mfma_f32_16x16x32_bf16 v[94:97], v[138:141], v[204:207], v[94:97]
	v_mfma_f32_16x16x32_bf16 v[86:89], v[152:155], v[204:207], v[86:89]
	v_mfma_f32_16x16x32_bf16 v[78:81], v[138:141], v[212:215], v[78:81]
	v_mfma_f32_16x16x32_bf16 v[70:73], v[152:155], v[212:215], v[70:73]
	v_mfma_f32_16x16x32_bf16 v[122:125], v[156:159], v[172:175], v[122:125]
	v_mfma_f32_16x16x32_bf16 v[114:117], v[164:167], v[172:175], v[114:117]
	v_mfma_f32_16x16x32_bf16 v[106:109], v[156:159], v[180:183], v[106:109]
	v_mfma_f32_16x16x32_bf16 v[98:101], v[164:167], v[180:183], v[98:101]
	v_mfma_f32_16x16x32_bf16 v[90:93], v[156:159], v[200:203], v[90:93]
	v_mfma_f32_16x16x32_bf16 v[82:85], v[164:167], v[200:203], v[82:85]
	v_mfma_f32_16x16x32_bf16 v[74:77], v[156:159], v[208:211], v[74:77]
	v_mfma_f32_16x16x32_bf16 v[66:69], v[164:167], v[208:211], v[66:69]
	v_mfma_f32_16x16x32_bf16 v[122:125], v[160:163], v[176:179], v[122:125]
	v_mfma_f32_16x16x32_bf16 v[114:117], v[168:171], v[176:179], v[114:117]
	v_mfma_f32_16x16x32_bf16 v[106:109], v[160:163], v[196:199], v[106:109]
	v_mfma_f32_16x16x32_bf16 v[98:101], v[168:171], v[196:199], v[98:101]
	v_mfma_f32_16x16x32_bf16 v[90:93], v[160:163], v[204:207], v[90:93]
	v_mfma_f32_16x16x32_bf16 v[82:85], v[168:171], v[204:207], v[82:85]
	v_mfma_f32_16x16x32_bf16 v[74:77], v[160:163], v[212:215], v[74:77]
	v_mfma_f32_16x16x32_bf16 v[66:69], v[168:171], v[212:215], v[66:69]
	s_barrier
	v_mul_lo_u32 v148, s6, v185
	v_lshl_add_u64 v[216:217], s[48:49], 0, v[148:149]
	s_add_i32 s50, s74, s3
	v_lshl_add_u64 v[216:217], v[216:217], 0, v[146:147]
	s_mov_b32 m0, s50
	ds_read_b128 v[172:175], v195 offset:16384
	ds_read_b128 v[176:179], v195 offset:17408
	ds_read_b128 v[180:183], v195 offset:18432
	ds_read_b128 v[196:199], v195 offset:19456
	ds_read_b128 v[200:203], v195 offset:20480
	ds_read_b128 v[204:207], v195 offset:21504
	ds_read_b128 v[208:211], v195 offset:22528
	ds_read_b128 v[212:215], v195 offset:23552
	global_load_lds_dwordx4 v[216:217], off
	v_mul_lo_u32 v218, s6, v187
	v_mov_b32_e32 v219, v149
	s_add_i32 m0, s50, 0x2000
	s_lshl_b64 s[50:51], s[6:7], 7
	v_lshl_add_u64 v[220:221], s[48:49], 0, v[218:219]
	s_add_u32 s48, s48, s50
	s_addc_u32 s49, s49, s51
	v_lshl_add_u64 v[220:221], v[220:221], 0, v[146:147]
	v_lshl_add_u64 v[222:223], s[48:49], 0, v[148:149]
	s_add_i32 s6, s75, s3
	global_load_lds_dwordx4 v[220:221], off
	v_lshl_add_u64 v[222:223], v[222:223], 0, v[146:147]
	s_mov_b32 m0, s6
	v_lshl_add_u64 v[218:219], s[48:49], 0, v[218:219]
	v_mul_lo_u32 v148, s62, v184
	global_load_lds_dwordx4 v[222:223], off
	v_lshl_add_u64 v[218:219], v[218:219], 0, v[146:147]
	s_add_i32 m0, s6, 0x2000
	v_lshl_add_u64 v[224:225], s[60:61], 0, v[148:149]
	v_mul_lo_u32 v226, s62, v186
	v_mov_b32_e32 v227, v149
	global_load_lds_dwordx4 v[218:219], off
	v_lshl_add_u64 v[224:225], v[224:225], 0, v[146:147]
	s_mov_b32 m0, s43
	v_lshl_add_u64 v[228:229], s[60:61], 0, v[226:227]
	global_load_lds_dwordx4 v[224:225], off
	v_lshl_add_u64 v[228:229], v[228:229], 0, v[146:147]
	s_mov_b32 m0, s65
	s_nop 0
	global_load_lds_dwordx4 v[228:229], off
	s_waitcnt vmcnt(8)
	s_waitcnt lgkmcnt(0)
	s_barrier
; #define PG8_STAGE(bufoff, gbase, RR, ld) do { _Pragma("unroll") for (int _i = 0; _i < 2; ++_i) \
;         __builtin_amdgcn_global_load_lds((const unsigned*)((const char*)(gbase) + (RR)[_i] * (ld) + C2[_i]), (LAS unsigned*)(lds + (bufoff) + ldsw + _i * 8192), 16, 0, 0); } while (0)
; #define PG8_LDA(dst, b, h) do { _Pragma("unroll") for (int m = 0; m < 4; ++m) _Pragma("unroll") for (int k = 0; k < 2; ++k) dst[m][k] = *(const LAS bf16x8*)(lds + PG8_SA(b, h) + aoff + m * 2048 + k * 1024); } while (0)
; #define PG8_LDB(dst, b, h) do { _Pragma("unroll") for (int n = 0; n < 2; ++n) _Pragma("unroll") for (int k = 0; k < 2; ++k) dst[n][k] = *(const LAS bf16x8*)(lds + PG8_SB(b, h) + boff + n * 2048 + k * 1024); } while (0)
; #define PG8_MMA(ai, bj, At, Bt) do { __builtin_amdgcn_s_setprio(1); _Pragma("unroll") for (int m = 0; m < 4; ++m) _Pragma("unroll") for (int n = 0; n < 2; ++n) _Pragma("unroll") for (int k = 0; k < 2; ++k) \
;         acc[ai][bj][m][n] = __builtin_amdgcn_mfma_f32_16x16x32_bf16(Bt[n][k], At[m][k], acc[ai][bj][m][n], 0, 0, 0); __builtin_amdgcn_s_setprio(0); } while (0)
; #define PG8_WAIT_V(n) asm volatile("s_waitcnt vmcnt(" #n ")" ::: "memory")
; #define PG8_WAIT_L(n) asm volatile("s_waitcnt lgkmcnt(" #n ")" ::: "memory")
; #define PG8_BAR __builtin_amdgcn_s_barrier()
; #define PG8_SCHED __builtin_amdgcn_sched_barrier(0)
; template <class Sched, class Epi>
; __device__ __forceinline__ void gemm_run(LAS unsigned char* lds, const Sched& S, const Epi& E) {
;     ...
;             PG8_WAIT_V(8); PG8_WAIT_L(0); PG8_BAR; PG8_MMA(1, 0, At, B0); PG8_MMA(1, 1, At, B1); PG8_BAR; PG8_SCHED;
;             PG8_LDB(B0, 1, 0); PG8_LDB(B1, 1, 1); PG8_SCHED; PG8_LDA(At, 1, 0); PG8_STAGE(PG8_SA(0, 1), a2 + (size_t)HALF * la2, RA, la2);
;             PG8_WAIT_V(8); PG8_WAIT_L(0); PG8_BAR; PG8_MMA(0, 0, At, B0); PG8_MMA(0, 1, At, B1); PG8_BAR; PG8_SCHED;
	s_waitcnt lgkmcnt(0)
	v_mfma_f32_16x16x32_bf16 v[62:65], v[134:137], v[172:175], v[62:65]
	v_mfma_f32_16x16x32_bf16 v[54:57], v[142:145], v[172:175], v[54:57]
	v_mfma_f32_16x16x32_bf16 v[46:49], v[134:137], v[180:183], v[46:49]
	v_mfma_f32_16x16x32_bf16 v[38:41], v[142:145], v[180:183], v[38:41]
	v_mfma_f32_16x16x32_bf16 v[30:33], v[134:137], v[200:203], v[30:33]
	v_mfma_f32_16x16x32_bf16 v[22:25], v[142:145], v[200:203], v[22:25]
	v_mfma_f32_16x16x32_bf16 v[14:17], v[134:137], v[208:211], v[14:17]
	v_mfma_f32_16x16x32_bf16 v[6:9], v[142:145], v[208:211], v[6:9]
	v_mfma_f32_16x16x32_bf16 v[62:65], v[138:141], v[176:179], v[62:65]
	v_mfma_f32_16x16x32_bf16 v[54:57], v[152:155], v[176:179], v[54:57]
	v_mfma_f32_16x16x32_bf16 v[46:49], v[138:141], v[196:199], v[46:49]
	v_mfma_f32_16x16x32_bf16 v[38:41], v[152:155], v[196:199], v[38:41]
	v_mfma_f32_16x16x32_bf16 v[30:33], v[138:141], v[204:207], v[30:33]
	v_mfma_f32_16x16x32_bf16 v[22:25], v[152:155], v[204:207], v[22:25]
	v_mfma_f32_16x16x32_bf16 v[14:17], v[138:141], v[212:215], v[14:17]
	v_mfma_f32_16x16x32_bf16 v[6:9], v[152:155], v[212:215], v[6:9]
	v_mfma_f32_16x16x32_bf16 v[58:61], v[156:159], v[172:175], v[58:61]
	v_mfma_f32_16x16x32_bf16 v[50:53], v[164:167], v[172:175], v[50:53]
	v_mfma_f32_16x16x32_bf16 v[42:45], v[156:159], v[180:183], v[42:45]
	v_mfma_f32_16x16x32_bf16 v[34:37], v[164:167], v[180:183], v[34:37]
	v_mfma_f32_16x16x32_bf16 v[26:29], v[156:159], v[200:203], v[26:29]
	v_mfma_f32_16x16x32_bf16 v[18:21], v[164:167], v[200:203], v[18:21]
	v_mfma_f32_16x16x32_bf16 v[10:13], v[156:159], v[208:211], v[10:13]
	v_mfma_f32_16x16x32_bf16 v[2:5], v[164:167], v[208:211], v[2:5]
	v_mfma_f32_16x16x32_bf16 v[58:61], v[160:163], v[176:179], v[58:61]
	v_mfma_f32_16x16x32_bf16 v[50:53], v[168:171], v[176:179], v[50:53]
	v_mfma_f32_16x16x32_bf16 v[42:45], v[160:163], v[196:199], v[42:45]
	v_mfma_f32_16x16x32_bf16 v[34:37], v[168:171], v[196:199], v[34:37]
	v_mfma_f32_16x16x32_bf16 v[26:29], v[160:163], v[204:207], v[26:29]
	v_mfma_f32_16x16x32_bf16 v[18:21], v[168:171], v[204:207], v[18:21]
	v_mfma_f32_16x16x32_bf16 v[10:13], v[160:163], v[212:215], v[10:13]
	v_mfma_f32_16x16x32_bf16 v[2:5], v[168:171], v[212:215], v[2:5]
	s_barrier
	s_add_i32 s6, 0, 0x18000
	s_add_i32 s50, 0, 0x1c000
	v_add_u32_e32 v152, s6, v189
	v_add_u32_e32 v168, s50, v189
	ds_read_b128 v[134:137], v152
	ds_read_b128 v[138:141], v152 offset:1024
	ds_read_b128 v[142:145], v152 offset:2048
	ds_read_b128 v[152:155], v152 offset:3072
	ds_read_b128 v[156:159], v168
	ds_read_b128 v[160:163], v168 offset:1024
	ds_read_b128 v[164:167], v168 offset:2048
	ds_read_b128 v[168:171], v168 offset:3072
	s_mov_b32 s63, s7
	s_lshl_b64 s[48:49], s[62:63], 7
	s_add_u32 s48, s60, s48
	s_addc_u32 s49, s61, s49
	v_lshl_add_u64 v[230:231], s[48:49], 0, v[148:149]
	s_mov_b32 m0, s66
	v_lshl_add_u64 v[230:231], v[230:231], 0, v[146:147]
	v_lshl_add_u64 v[226:227], s[48:49], 0, v[226:227]
	ds_read_b128 v[172:175], v195 offset:32768
	ds_read_b128 v[176:179], v195 offset:33792
	ds_read_b128 v[180:183], v195 offset:34816
	ds_read_b128 v[196:199], v195 offset:35840
	ds_read_b128 v[200:203], v195 offset:36864
	ds_read_b128 v[204:207], v195 offset:37888
	ds_read_b128 v[208:211], v195 offset:38912
	ds_read_b128 v[212:215], v195 offset:39936
	global_load_lds_dwordx4 v[230:231], off
	v_lshl_add_u64 v[226:227], v[226:227], 0, v[146:147]
	s_mov_b32 m0, s67
	s_nop 0
	global_load_lds_dwordx4 v[226:227], off
	s_waitcnt vmcnt(8)
	s_waitcnt lgkmcnt(0)
	s_barrier
	s_waitcnt lgkmcnt(0)
	v_mfma_f32_16x16x32_bf16 v[126:129], v[134:137], v[172:175], v[126:129]
	v_mfma_f32_16x16x32_bf16 v[118:121], v[142:145], v[172:175], v[118:121]
	v_mfma_f32_16x16x32_bf16 v[110:113], v[134:137], v[180:183], v[110:113]
	v_mfma_f32_16x16x32_bf16 v[102:105], v[142:145], v[180:183], v[102:105]
	v_mfma_f32_16x16x32_bf16 v[94:97], v[134:137], v[200:203], v[94:97]
	v_mfma_f32_16x16x32_bf16 v[86:89], v[142:145], v[200:203], v[86:89]
	v_mfma_f32_16x16x32_bf16 v[78:81], v[134:137], v[208:211], v[78:81]
	v_mfma_f32_16x16x32_bf16 v[70:73], v[142:145], v[208:211], v[70:73]
	v_mfma_f32_16x16x32_bf16 v[126:129], v[138:141], v[176:179], v[126:129]
	v_mfma_f32_16x16x32_bf16 v[118:121], v[152:155], v[176:179], v[118:121]
	v_mfma_f32_16x16x32_bf16 v[110:113], v[138:141], v[196:199], v[110:113]
	v_mfma_f32_16x16x32_bf16 v[102:105], v[152:155], v[196:199], v[102:105]
	v_mfma_f32_16x16x32_bf16 v[94:97], v[138:141], v[204:207], v[94:97]
	v_mfma_f32_16x16x32_bf16 v[86:89], v[152:155], v[204:207], v[86:89]
	v_mfma_f32_16x16x32_bf16 v[78:81], v[138:141], v[212:215], v[78:81]
	v_mfma_f32_16x16x32_bf16 v[70:73], v[152:155], v[212:215], v[70:73]
	v_mfma_f32_16x16x32_bf16 v[122:125], v[156:159], v[172:175], v[122:125]
	v_mfma_f32_16x16x32_bf16 v[114:117], v[164:167], v[172:175], v[114:117]
	v_mfma_f32_16x16x32_bf16 v[106:109], v[156:159], v[180:183], v[106:109]
	v_mfma_f32_16x16x32_bf16 v[98:101], v[164:167], v[180:183], v[98:101]
	v_mfma_f32_16x16x32_bf16 v[90:93], v[156:159], v[200:203], v[90:93]
	v_mfma_f32_16x16x32_bf16 v[82:85], v[164:167], v[200:203], v[82:85]
	v_mfma_f32_16x16x32_bf16 v[74:77], v[156:159], v[208:211], v[74:77]
	v_mfma_f32_16x16x32_bf16 v[66:69], v[164:167], v[208:211], v[66:69]
	v_mfma_f32_16x16x32_bf16 v[122:125], v[160:163], v[176:179], v[122:125]
	v_mfma_f32_16x16x32_bf16 v[114:117], v[168:171], v[176:179], v[114:117]
	v_mfma_f32_16x16x32_bf16 v[106:109], v[160:163], v[196:199], v[106:109]
	v_mfma_f32_16x16x32_bf16 v[98:101], v[168:171], v[196:199], v[98:101]
	v_mfma_f32_16x16x32_bf16 v[90:93], v[160:163], v[204:207], v[90:93]
	v_mfma_f32_16x16x32_bf16 v[82:85], v[168:171], v[204:207], v[82:85]
	v_mfma_f32_16x16x32_bf16 v[74:77], v[160:163], v[212:215], v[74:77]
	v_mfma_f32_16x16x32_bf16 v[66:69], v[168:171], v[212:215], v[66:69]
	s_barrier
; #define PG8_STAGE(bufoff, gbase, RR, ld) do { _Pragma("unroll") for (int _i = 0; _i < 2; ++_i) \
;         __builtin_amdgcn_global_load_lds((const unsigned*)((const char*)(gbase) + (RR)[_i] * (ld) + C2[_i]), (LAS unsigned*)(lds + (bufoff) + ldsw + _i * 8192), 16, 0, 0); } while (0)
; #define PG8_LDA(dst, b, h) do { _Pragma("unroll") for (int m = 0; m < 4; ++m) _Pragma("unroll") for (int k = 0; k < 2; ++k) dst[m][k] = *(const LAS bf16x8*)(lds + PG8_SA(b, h) + aoff + m * 2048 + k * 1024); } while (0)
; #define PG8_MMA(ai, bj, At, Bt) do { __builtin_amdgcn_s_setprio(1); _Pragma("unroll") for (int m = 0; m < 4; ++m) _Pragma("unroll") for (int n = 0; n < 2; ++n) _Pragma("unroll") for (int k = 0; k < 2; ++k) \
;         acc[ai][bj][m][n] = __builtin_amdgcn_mfma_f32_16x16x32_bf16(Bt[n][k], At[m][k], acc[ai][bj][m][n], 0, 0, 0); __builtin_amdgcn_s_setprio(0); } while (0)
; #define PG8_WAIT_V(n) asm volatile("s_waitcnt vmcnt(" #n ")" ::: "memory")
; #define PG8_WAIT_L(n) asm volatile("s_waitcnt lgkmcnt(" #n ")" ::: "memory")
; #define PG8_BAR __builtin_amdgcn_s_barrier()
; #define PG8_SCHED __builtin_amdgcn_sched_barrier(0)
; template <class Sched, class Epi>
; __device__ __forceinline__ void gemm_run(LAS unsigned char* lds, const Sched& S, const Epi& E) {
;     ...
;             PG8_LDA(At, 1, 1); PG8_STAGE(PG8_SB(1, 0), b3, RB, lb2); PG8_STAGE(PG8_SB(1, 1), b3 + (size_t)HALF * lb2, RB, lb2); PG8_STAGE(PG8_SA(1, 0), a3, RA, la2);
;             PG8_WAIT_V(8); PG8_WAIT_L(0); PG8_BAR; PG8_MMA(1, 0, At, B0); PG8_MMA(1, 1, At, B1); PG8_BAR; PG8_SCHED;
;         }
;         if (wr == 0) PG8_BAR;
	s_add_i32 s6, s6, s3
	v_lshl_add_u64 v[216:217], v[216:217], 0, s[8:9]
	s_mov_b32 m0, s6
	ds_read_b128 v[172:175], v195 offset:49152
	ds_read_b128 v[176:179], v195 offset:50176
	ds_read_b128 v[180:183], v195 offset:51200
	ds_read_b128 v[196:199], v195 offset:52224
	ds_read_b128 v[200:203], v195 offset:53248
	ds_read_b128 v[204:207], v195 offset:54272
	ds_read_b128 v[208:211], v195 offset:55296
	ds_read_b128 v[212:215], v195 offset:56320
	global_load_lds_dwordx4 v[216:217], off
	v_lshl_add_u64 v[216:217], v[220:221], 0, s[8:9]
	s_add_i32 m0, s6, 0x2000
	s_add_i32 s6, s50, s3
	global_load_lds_dwordx4 v[216:217], off
	v_lshl_add_u64 v[216:217], v[222:223], 0, s[8:9]
	s_mov_b32 m0, s6
	s_nop 0
	global_load_lds_dwordx4 v[216:217], off
	v_lshl_add_u64 v[216:217], v[218:219], 0, s[8:9]
	s_add_i32 m0, s6, 0x2000
	s_nop 0
	global_load_lds_dwordx4 v[216:217], off
	v_lshl_add_u64 v[216:217], v[224:225], 0, s[8:9]
	s_mov_b32 m0, s68
	s_nop 0
	global_load_lds_dwordx4 v[216:217], off
	v_lshl_add_u64 v[216:217], v[228:229], 0, s[8:9]
	s_mov_b32 m0, s69
	s_nop 0
	global_load_lds_dwordx4 v[216:217], off
	s_waitcnt vmcnt(8)
	s_waitcnt lgkmcnt(0)
	s_barrier
	s_waitcnt lgkmcnt(0)
	v_mfma_f32_16x16x32_bf16 v[62:65], v[134:137], v[172:175], v[62:65]
	v_mfma_f32_16x16x32_bf16 v[54:57], v[142:145], v[172:175], v[54:57]
	v_mfma_f32_16x16x32_bf16 v[46:49], v[134:137], v[180:183], v[46:49]
	v_mfma_f32_16x16x32_bf16 v[38:41], v[142:145], v[180:183], v[38:41]
	v_mfma_f32_16x16x32_bf16 v[30:33], v[134:137], v[200:203], v[30:33]
	v_mfma_f32_16x16x32_bf16 v[22:25], v[142:145], v[200:203], v[22:25]
	v_mfma_f32_16x16x32_bf16 v[14:17], v[134:137], v[208:211], v[14:17]
	v_mfma_f32_16x16x32_bf16 v[6:9], v[142:145], v[208:211], v[6:9]
	v_mfma_f32_16x16x32_bf16 v[62:65], v[138:141], v[176:179], v[62:65]
	v_mfma_f32_16x16x32_bf16 v[54:57], v[152:155], v[176:179], v[54:57]
	v_mfma_f32_16x16x32_bf16 v[46:49], v[138:141], v[196:199], v[46:49]
	v_mfma_f32_16x16x32_bf16 v[38:41], v[152:155], v[196:199], v[38:41]
	v_mfma_f32_16x16x32_bf16 v[30:33], v[138:141], v[204:207], v[30:33]
	v_mfma_f32_16x16x32_bf16 v[22:25], v[152:155], v[204:207], v[22:25]
	v_mfma_f32_16x16x32_bf16 v[14:17], v[138:141], v[212:215], v[14:17]
	v_mfma_f32_16x16x32_bf16 v[6:9], v[152:155], v[212:215], v[6:9]
	v_mfma_f32_16x16x32_bf16 v[58:61], v[156:159], v[172:175], v[58:61]
	v_mfma_f32_16x16x32_bf16 v[50:53], v[164:167], v[172:175], v[50:53]
	v_mfma_f32_16x16x32_bf16 v[42:45], v[156:159], v[180:183], v[42:45]
	v_mfma_f32_16x16x32_bf16 v[34:37], v[164:167], v[180:183], v[34:37]
	v_mfma_f32_16x16x32_bf16 v[26:29], v[156:159], v[200:203], v[26:29]
	v_mfma_f32_16x16x32_bf16 v[18:21], v[164:167], v[200:203], v[18:21]
	v_mfma_f32_16x16x32_bf16 v[10:13], v[156:159], v[208:211], v[10:13]
	v_mfma_f32_16x16x32_bf16 v[2:5], v[164:167], v[208:211], v[2:5]
	v_mfma_f32_16x16x32_bf16 v[58:61], v[160:163], v[176:179], v[58:61]
	v_mfma_f32_16x16x32_bf16 v[50:53], v[168:171], v[176:179], v[50:53]
	v_mfma_f32_16x16x32_bf16 v[42:45], v[160:163], v[196:199], v[42:45]
	v_mfma_f32_16x16x32_bf16 v[34:37], v[168:171], v[196:199], v[34:37]
	v_mfma_f32_16x16x32_bf16 v[26:29], v[160:163], v[204:207], v[26:29]
	v_mfma_f32_16x16x32_bf16 v[18:21], v[168:171], v[204:207], v[18:21]
	v_mfma_f32_16x16x32_bf16 v[10:13], v[160:163], v[212:215], v[10:13]
	v_mfma_f32_16x16x32_bf16 v[2:5], v[168:171], v[212:215], v[2:5]
	s_barrier
	s_add_u32 s58, s58, 0x100
	s_addc_u32 s59, s59, 0
	s_cmp_ge_i32 s47, s81
	s_mov_b32 s6, s47
	s_cbranch_scc0 .LBB0_806
	s_and_b64 vcc, exec, s[10:11]
	s_cbranch_vccz .LBB0_809
	s_barrier

; #define PG8_STAGE(bufoff, gbase, RR, ld) do { _Pragma("unroll") for (int _i = 0; _i < 2; ++_i) \
;         __builtin_amdgcn_global_load_lds((const unsigned*)((const char*)(gbase) + (RR)[_i] * (ld) + C2[_i]), (LAS unsigned*)(lds + (bufoff) + ldsw + _i * 8192), 16, 0, 0); } while (0)
; #define PG8_LDA(dst, b, h) do { _Pragma("unroll") for (int m = 0; m < 4; ++m) _Pragma("unroll") for (int k = 0; k < 2; ++k) dst[m][k] = *(const LAS bf16x8*)(lds + PG8_SA(b, h) + aoff + m * 2048 + k * 1024); } while (0)
; #define PG8_LDB(dst, b, h) do { _Pragma("unroll") for (int n = 0; n < 2; ++n) _Pragma("unroll") for (int k = 0; k < 2; ++k) dst[n][k] = *(const LAS bf16x8*)(lds + PG8_SB(b, h) + boff + n * 2048 + k * 1024); } while (0)
; #define PG8_MMA(ai, bj, At, Bt) do { __builtin_amdgcn_s_setprio(1); _Pragma("unroll") for (int m = 0; m < 4; ++m) _Pragma("unroll") for (int n = 0; n < 2; ++n) _Pragma("unroll") for (int k = 0; k < 2; ++k) \
;         acc[ai][bj][m][n] = __builtin_amdgcn_mfma_f32_16x16x32_bf16(Bt[n][k], At[m][k], acc[ai][bj][m][n], 0, 0, 0); __builtin_amdgcn_s_setprio(0); } while (0)
; #define PG8_WAIT_V(n) asm volatile("s_waitcnt vmcnt(" #n ")" ::: "memory")
; #define PG8_WAIT_L(n) asm volatile("s_waitcnt lgkmcnt(" #n ")" ::: "memory")
; #define PG8_BAR __builtin_amdgcn_s_barrier()
; #define PG8_SCHED __builtin_amdgcn_sched_barrier(0)
; template <class Sched, class Epi>
; __device__ __forceinline__ void gemm_run(LAS unsigned char* lds, const Sched& S, const Epi& E) {
;     ...
;             PG8_LDB(B0, 0, 0); PG8_LDB(B1, 0, 1); PG8_SCHED; PG8_LDA(At, 0, 0); PG8_STAGE(PG8_SA(1, 1), a1 + (size_t)HALF * lda, RA, lda);
;             PG8_WAIT_V(8); PG8_WAIT_L(0); PG8_BAR; PG8_MMA(0, 0, At, B0); PG8_MMA(0, 1, At, B1); PG8_BAR; PG8_SCHED;
;             PG8_LDA(At, 0, 1); PG8_STAGE(PG8_SB(0, 0), b2, RB, lb2); PG8_STAGE(PG8_SB(0, 1), b2 + (size_t)HALF * lb2, RB, lb2); PG8_STAGE(PG8_SA(0, 0), a2, RA, la2);
;             PG8_WAIT_V(8); PG8_WAIT_L(0); PG8_BAR; PG8_MMA(1, 0, At, B0); PG8_MMA(1, 1, At, B1); PG8_BAR; PG8_SCHED;
.LBB0_894:
	ds_read_b128 v[134:137], v191
	ds_read_b128 v[138:141], v191 offset:1024
	ds_read_b128 v[142:145], v191 offset:2048
	ds_read_b128 v[146:149], v191 offset:3072
	ds_read_b128 v[150:153], v192
	ds_read_b128 v[172:175], v192 offset:1024
	ds_read_b128 v[176:179], v192 offset:2048
	ds_read_b128 v[180:183], v192 offset:3072
	s_add_u32 s40, s36, s38
	s_addc_u32 s41, s37, s39
	s_add_u32 s40, s40, 0x100
	s_addc_u32 s41, s41, 0
	s_add_u32 s45, s19, s38
	s_addc_u32 s46, s31, s39
	s_cmpk_eq_i32 s38, 0xf00
	s_cselect_b32 s43, s21, s41
	s_cselect_b32 s42, s20, s40
	s_cselect_b32 s41, s29, s46
	s_cselect_b32 s40, s28, s45
	v_lshl_add_u64 v[224:225], v[130:131], 0, s[38:39]
	s_add_i32 m0, s33, 0xc000
	ds_read_b128 v[184:187], v193
	ds_read_b128 v[196:199], v193 offset:1024
	ds_read_b128 v[200:203], v193 offset:2048
	ds_read_b128 v[204:207], v193 offset:3072
	ds_read_b128 v[208:211], v193 offset:4096
	ds_read_b128 v[212:215], v193 offset:5120
	ds_read_b128 v[216:219], v193 offset:6144
	ds_read_b128 v[220:223], v193 offset:7168
	global_load_lds_dwordx4 v[224:225], off
	v_lshl_add_u64 v[224:225], v[132:133], 0, s[38:39]
	s_add_i32 m0, s33, 0xe000
	s_nop 0
	global_load_lds_dwordx4 v[224:225], off
	s_waitcnt vmcnt(8)
	s_waitcnt lgkmcnt(0)
	s_barrier
	s_waitcnt lgkmcnt(0)
	v_mfma_f32_16x16x32_bf16 v[126:129], v[134:137], v[184:187], v[126:129]
	v_mfma_f32_16x16x32_bf16 v[122:125], v[142:145], v[184:187], v[122:125]
	v_mfma_f32_16x16x32_bf16 v[110:113], v[134:137], v[200:203], v[110:113]
	v_mfma_f32_16x16x32_bf16 v[106:109], v[142:145], v[200:203], v[106:109]
	v_mfma_f32_16x16x32_bf16 v[94:97], v[134:137], v[208:211], v[94:97]
	v_mfma_f32_16x16x32_bf16 v[90:93], v[142:145], v[208:211], v[90:93]
	v_mfma_f32_16x16x32_bf16 v[78:81], v[134:137], v[216:219], v[78:81]
	v_mfma_f32_16x16x32_bf16 v[74:77], v[142:145], v[216:219], v[74:77]
	v_mfma_f32_16x16x32_bf16 v[126:129], v[138:141], v[196:199], v[126:129]
	v_mfma_f32_16x16x32_bf16 v[122:125], v[146:149], v[196:199], v[122:125]
	v_mfma_f32_16x16x32_bf16 v[110:113], v[138:141], v[204:207], v[110:113]
	v_mfma_f32_16x16x32_bf16 v[106:109], v[146:149], v[204:207], v[106:109]
	v_mfma_f32_16x16x32_bf16 v[94:97], v[138:141], v[212:215], v[94:97]
	v_mfma_f32_16x16x32_bf16 v[90:93], v[146:149], v[212:215], v[90:93]
	v_mfma_f32_16x16x32_bf16 v[78:81], v[138:141], v[220:223], v[78:81]
	v_mfma_f32_16x16x32_bf16 v[74:77], v[146:149], v[220:223], v[74:77]
	v_mfma_f32_16x16x32_bf16 v[118:121], v[150:153], v[184:187], v[118:121]
	v_mfma_f32_16x16x32_bf16 v[114:117], v[176:179], v[184:187], v[114:117]
	v_mfma_f32_16x16x32_bf16 v[102:105], v[150:153], v[200:203], v[102:105]
	v_mfma_f32_16x16x32_bf16 v[98:101], v[176:179], v[200:203], v[98:101]
	v_mfma_f32_16x16x32_bf16 v[86:89], v[150:153], v[208:211], v[86:89]
	v_mfma_f32_16x16x32_bf16 v[82:85], v[176:179], v[208:211], v[82:85]
	v_mfma_f32_16x16x32_bf16 v[70:73], v[150:153], v[216:219], v[70:73]
	v_mfma_f32_16x16x32_bf16 v[66:69], v[176:179], v[216:219], v[66:69]
	v_mfma_f32_16x16x32_bf16 v[118:121], v[172:175], v[196:199], v[118:121]
	v_mfma_f32_16x16x32_bf16 v[114:117], v[180:183], v[196:199], v[114:117]
	v_mfma_f32_16x16x32_bf16 v[102:105], v[172:175], v[204:207], v[102:105]
	v_mfma_f32_16x16x32_bf16 v[98:101], v[180:183], v[204:207], v[98:101]
	v_mfma_f32_16x16x32_bf16 v[86:89], v[172:175], v[212:215], v[86:89]
	v_mfma_f32_16x16x32_bf16 v[82:85], v[180:183], v[212:215], v[82:85]
	v_mfma_f32_16x16x32_bf16 v[70:73], v[172:175], v[220:223], v[70:73]
	v_mfma_f32_16x16x32_bf16 v[66:69], v[180:183], v[220:223], v[66:69]
	s_barrier
	v_lshl_add_u64 v[224:225], s[40:41], 0, v[156:157]
	s_add_i32 s45, s61, s3
	v_lshl_add_u64 v[224:225], v[224:225], 0, v[154:155]
	s_mov_b32 m0, s45
	ds_read_b128 v[184:187], v193 offset:16384
	ds_read_b128 v[196:199], v193 offset:17408
	ds_read_b128 v[200:203], v193 offset:18432
	ds_read_b128 v[204:207], v193 offset:19456
	ds_read_b128 v[208:211], v193 offset:20480
	ds_read_b128 v[212:215], v193 offset:21504
	ds_read_b128 v[216:219], v193 offset:22528
	ds_read_b128 v[220:223], v193 offset:23552
	global_load_lds_dwordx4 v[224:225], off
	s_add_i32 m0, s45, 0x2000
	s_add_u32 s46, s40, 0x80000
	v_lshl_add_u64 v[226:227], s[40:41], 0, v[160:161]
	s_addc_u32 s47, s41, 0
	v_lshl_add_u64 v[226:227], v[226:227], 0, v[154:155]
	v_lshl_add_u64 v[228:229], s[46:47], 0, v[156:157]
	s_add_i32 s45, s62, s3
	global_load_lds_dwordx4 v[226:227], off
	v_lshl_add_u64 v[228:229], v[228:229], 0, v[154:155]
	s_mov_b32 m0, s45
	v_lshl_add_u64 v[230:231], s[42:43], 0, v[164:165]
	global_load_lds_dwordx4 v[228:229], off
	v_lshl_add_u64 v[228:229], s[46:47], 0, v[160:161]
	v_lshl_add_u64 v[228:229], v[228:229], 0, v[154:155]
	s_add_i32 m0, s45, 0x2000
	v_lshl_add_u64 v[230:231], v[230:231], 0, v[154:155]
	global_load_lds_dwordx4 v[228:229], off
	v_lshl_add_u64 v[228:229], s[42:43], 0, v[162:163]
	v_lshl_add_u64 v[228:229], v[228:229], 0, v[154:155]
	s_mov_b32 m0, s33
	s_nop 0
	global_load_lds_dwordx4 v[228:229], off
	s_mov_b32 m0, s35
	s_nop 0
	global_load_lds_dwordx4 v[230:231], off
	s_waitcnt vmcnt(8)
	s_waitcnt lgkmcnt(0)
	s_barrier
; #define PG8_STAGE(bufoff, gbase, RR, ld) do { _Pragma("unroll") for (int _i = 0; _i < 2; ++_i) \
;         __builtin_amdgcn_global_load_lds((const unsigned*)((const char*)(gbase) + (RR)[_i] * (ld) + C2[_i]), (LAS unsigned*)(lds + (bufoff) + ldsw + _i * 8192), 16, 0, 0); } while (0)
; #define PG8_LDA(dst, b, h) do { _Pragma("unroll") for (int m = 0; m < 4; ++m) _Pragma("unroll") for (int k = 0; k < 2; ++k) dst[m][k] = *(const LAS bf16x8*)(lds + PG8_SA(b, h) + aoff + m * 2048 + k * 1024); } while (0)
; #define PG8_LDB(dst, b, h) do { _Pragma("unroll") for (int n = 0; n < 2; ++n) _Pragma("unroll") for (int k = 0; k < 2; ++k) dst[n][k] = *(const LAS bf16x8*)(lds + PG8_SB(b, h) + boff + n * 2048 + k * 1024); } while (0)
; #define PG8_MMA(ai, bj, At, Bt) do { __builtin_amdgcn_s_setprio(1); _Pragma("unroll") for (int m = 0; m < 4; ++m) _Pragma("unroll") for (int n = 0; n < 2; ++n) _Pragma("unroll") for (int k = 0; k < 2; ++k) \
;         acc[ai][bj][m][n] = __builtin_amdgcn_mfma_f32_16x16x32_bf16(Bt[n][k], At[m][k], acc[ai][bj][m][n], 0, 0, 0); __builtin_amdgcn_s_setprio(0); } while (0)
; #define PG8_WAIT_V(n) asm volatile("s_waitcnt vmcnt(" #n ")" ::: "memory")
; #define PG8_WAIT_L(n) asm volatile("s_waitcnt lgkmcnt(" #n ")" ::: "memory")
; #define PG8_BAR __builtin_amdgcn_s_barrier()
; #define PG8_SCHED __builtin_amdgcn_sched_barrier(0)
; template <class Sched, class Epi>
; __device__ __forceinline__ void gemm_run(LAS unsigned char* lds, const Sched& S, const Epi& E) {
;     ...
;             PG8_WAIT_V(8); PG8_WAIT_L(0); PG8_BAR; PG8_MMA(1, 0, At, B0); PG8_MMA(1, 1, At, B1); PG8_BAR; PG8_SCHED;
;             PG8_LDB(B0, 1, 0); PG8_LDB(B1, 1, 1); PG8_SCHED; PG8_LDA(At, 1, 0); PG8_STAGE(PG8_SA(0, 1), a2 + (size_t)HALF * la2, RA, la2);
;             PG8_WAIT_V(8); PG8_WAIT_L(0); PG8_BAR; PG8_MMA(0, 0, At, B0); PG8_MMA(0, 1, At, B1); PG8_BAR; PG8_SCHED;
	s_waitcnt lgkmcnt(0)
	v_mfma_f32_16x16x32_bf16 v[62:65], v[134:137], v[184:187], v[62:65]
	v_mfma_f32_16x16x32_bf16 v[58:61], v[142:145], v[184:187], v[58:61]
	v_mfma_f32_16x16x32_bf16 v[46:49], v[134:137], v[200:203], v[46:49]
	v_mfma_f32_16x16x32_bf16 v[42:45], v[142:145], v[200:203], v[42:45]
	v_mfma_f32_16x16x32_bf16 v[30:33], v[134:137], v[208:211], v[30:33]
	v_mfma_f32_16x16x32_bf16 v[26:29], v[142:145], v[208:211], v[26:29]
	v_mfma_f32_16x16x32_bf16 v[14:17], v[134:137], v[216:219], v[14:17]
	v_mfma_f32_16x16x32_bf16 v[10:13], v[142:145], v[216:219], v[10:13]
	v_mfma_f32_16x16x32_bf16 v[62:65], v[138:141], v[196:199], v[62:65]
	v_mfma_f32_16x16x32_bf16 v[58:61], v[146:149], v[196:199], v[58:61]
	v_mfma_f32_16x16x32_bf16 v[46:49], v[138:141], v[204:207], v[46:49]
	v_mfma_f32_16x16x32_bf16 v[42:45], v[146:149], v[204:207], v[42:45]
	v_mfma_f32_16x16x32_bf16 v[30:33], v[138:141], v[212:215], v[30:33]
	v_mfma_f32_16x16x32_bf16 v[26:29], v[146:149], v[212:215], v[26:29]
	v_mfma_f32_16x16x32_bf16 v[14:17], v[138:141], v[220:223], v[14:17]
	v_mfma_f32_16x16x32_bf16 v[10:13], v[146:149], v[220:223], v[10:13]
	v_mfma_f32_16x16x32_bf16 v[54:57], v[150:153], v[184:187], v[54:57]
	v_mfma_f32_16x16x32_bf16 v[50:53], v[176:179], v[184:187], v[50:53]
	v_mfma_f32_16x16x32_bf16 v[38:41], v[150:153], v[200:203], v[38:41]
	v_mfma_f32_16x16x32_bf16 v[34:37], v[176:179], v[200:203], v[34:37]
	v_mfma_f32_16x16x32_bf16 v[22:25], v[150:153], v[208:211], v[22:25]
	v_mfma_f32_16x16x32_bf16 v[18:21], v[176:179], v[208:211], v[18:21]
	v_mfma_f32_16x16x32_bf16 v[6:9], v[150:153], v[216:219], v[6:9]
	v_mfma_f32_16x16x32_bf16 v[2:5], v[176:179], v[216:219], v[2:5]
	v_mfma_f32_16x16x32_bf16 v[54:57], v[172:175], v[196:199], v[54:57]
	v_mfma_f32_16x16x32_bf16 v[50:53], v[180:183], v[196:199], v[50:53]
	v_mfma_f32_16x16x32_bf16 v[38:41], v[172:175], v[204:207], v[38:41]
	v_mfma_f32_16x16x32_bf16 v[34:37], v[180:183], v[204:207], v[34:37]
	v_mfma_f32_16x16x32_bf16 v[22:25], v[172:175], v[212:215], v[22:25]
	v_mfma_f32_16x16x32_bf16 v[18:21], v[180:183], v[212:215], v[18:21]
	v_mfma_f32_16x16x32_bf16 v[6:9], v[172:175], v[220:223], v[6:9]
	v_mfma_f32_16x16x32_bf16 v[2:5], v[180:183], v[220:223], v[2:5]
	s_barrier
	s_add_i32 s45, 0, 0x18000
	s_add_i32 s46, 0, 0x1c000
	v_add_u32_e32 v146, s45, v190
	v_add_u32_e32 v180, s46, v190
	ds_read_b128 v[134:137], v146
	ds_read_b128 v[138:141], v146 offset:1024
	ds_read_b128 v[142:145], v146 offset:2048
	ds_read_b128 v[146:149], v146 offset:3072
	ds_read_b128 v[150:153], v180
	ds_read_b128 v[172:175], v180 offset:1024
	ds_read_b128 v[176:179], v180 offset:2048
	ds_read_b128 v[180:183], v180 offset:3072
	s_add_u32 s42, s42, 0x80000
	s_addc_u32 s43, s43, 0
	v_lshl_add_u64 v[232:233], s[42:43], 0, v[162:163]
	s_mov_b32 m0, s52
	v_lshl_add_u64 v[232:233], v[232:233], 0, v[154:155]
	ds_read_b128 v[184:187], v193 offset:32768
	ds_read_b128 v[196:199], v193 offset:33792
	ds_read_b128 v[200:203], v193 offset:34816
	ds_read_b128 v[204:207], v193 offset:35840
	ds_read_b128 v[208:211], v193 offset:36864
	ds_read_b128 v[212:215], v193 offset:37888
	ds_read_b128 v[216:219], v193 offset:38912
	ds_read_b128 v[220:223], v193 offset:39936
	global_load_lds_dwordx4 v[232:233], off
	v_lshl_add_u64 v[232:233], s[42:43], 0, v[164:165]
	v_lshl_add_u64 v[232:233], v[232:233], 0, v[154:155]
	s_mov_b32 m0, s53
	s_nop 0
	global_load_lds_dwordx4 v[232:233], off
	s_waitcnt vmcnt(8)
	s_waitcnt lgkmcnt(0)
	s_barrier
	s_waitcnt lgkmcnt(0)
	v_mfma_f32_16x16x32_bf16 v[126:129], v[134:137], v[184:187], v[126:129]
	v_mfma_f32_16x16x32_bf16 v[122:125], v[142:145], v[184:187], v[122:125]
	v_mfma_f32_16x16x32_bf16 v[110:113], v[134:137], v[200:203], v[110:113]
	v_mfma_f32_16x16x32_bf16 v[106:109], v[142:145], v[200:203], v[106:109]
	v_mfma_f32_16x16x32_bf16 v[94:97], v[134:137], v[208:211], v[94:97]
	v_mfma_f32_16x16x32_bf16 v[90:93], v[142:145], v[208:211], v[90:93]
	v_mfma_f32_16x16x32_bf16 v[78:81], v[134:137], v[216:219], v[78:81]
	v_mfma_f32_16x16x32_bf16 v[74:77], v[142:145], v[216:219], v[74:77]
	v_mfma_f32_16x16x32_bf16 v[126:129], v[138:141], v[196:199], v[126:129]
	v_mfma_f32_16x16x32_bf16 v[122:125], v[146:149], v[196:199], v[122:125]
	v_mfma_f32_16x16x32_bf16 v[110:113], v[138:141], v[204:207], v[110:113]
	v_mfma_f32_16x16x32_bf16 v[106:109], v[146:149], v[204:207], v[106:109]
	v_mfma_f32_16x16x32_bf16 v[94:97], v[138:141], v[212:215], v[94:97]
	v_mfma_f32_16x16x32_bf16 v[90:93], v[146:149], v[212:215], v[90:93]
	v_mfma_f32_16x16x32_bf16 v[78:81], v[138:141], v[220:223], v[78:81]
	v_mfma_f32_16x16x32_bf16 v[74:77], v[146:149], v[220:223], v[74:77]
	v_mfma_f32_16x16x32_bf16 v[118:121], v[150:153], v[184:187], v[118:121]
	v_mfma_f32_16x16x32_bf16 v[114:117], v[176:179], v[184:187], v[114:117]
	v_mfma_f32_16x16x32_bf16 v[102:105], v[150:153], v[200:203], v[102:105]
	v_mfma_f32_16x16x32_bf16 v[98:101], v[176:179], v[200:203], v[98:101]
	v_mfma_f32_16x16x32_bf16 v[86:89], v[150:153], v[208:211], v[86:89]
	v_mfma_f32_16x16x32_bf16 v[82:85], v[176:179], v[208:211], v[82:85]
	v_mfma_f32_16x16x32_bf16 v[70:73], v[150:153], v[216:219], v[70:73]
	v_mfma_f32_16x16x32_bf16 v[66:69], v[176:179], v[216:219], v[66:69]
	v_mfma_f32_16x16x32_bf16 v[118:121], v[172:175], v[196:199], v[118:121]
	v_mfma_f32_16x16x32_bf16 v[114:117], v[180:183], v[196:199], v[114:117]
	v_mfma_f32_16x16x32_bf16 v[102:105], v[172:175], v[204:207], v[102:105]
	v_mfma_f32_16x16x32_bf16 v[98:101], v[180:183], v[204:207], v[98:101]
	v_mfma_f32_16x16x32_bf16 v[86:89], v[172:175], v[212:215], v[86:89]
	v_mfma_f32_16x16x32_bf16 v[82:85], v[180:183], v[212:215], v[82:85]
	v_mfma_f32_16x16x32_bf16 v[70:73], v[172:175], v[220:223], v[70:73]
	v_mfma_f32_16x16x32_bf16 v[66:69], v[180:183], v[220:223], v[66:69]
	s_barrier
; #define PG8_STAGE(bufoff, gbase, RR, ld) do { _Pragma("unroll") for (int _i = 0; _i < 2; ++_i) \
;         __builtin_amdgcn_global_load_lds((const unsigned*)((const char*)(gbase) + (RR)[_i] * (ld) + C2[_i]), (LAS unsigned*)(lds + (bufoff) + ldsw + _i * 8192), 16, 0, 0); } while (0)
; #define PG8_LDA(dst, b, h) do { _Pragma("unroll") for (int m = 0; m < 4; ++m) _Pragma("unroll") for (int k = 0; k < 2; ++k) dst[m][k] = *(const LAS bf16x8*)(lds + PG8_SA(b, h) + aoff + m * 2048 + k * 1024); } while (0)
; #define PG8_MMA(ai, bj, At, Bt) do { __builtin_amdgcn_s_setprio(1); _Pragma("unroll") for (int m = 0; m < 4; ++m) _Pragma("unroll") for (int n = 0; n < 2; ++n) _Pragma("unroll") for (int k = 0; k < 2; ++k) \
;         acc[ai][bj][m][n] = __builtin_amdgcn_mfma_f32_16x16x32_bf16(Bt[n][k], At[m][k], acc[ai][bj][m][n], 0, 0, 0); __builtin_amdgcn_s_setprio(0); } while (0)
; #define PG8_WAIT_V(n) asm volatile("s_waitcnt vmcnt(" #n ")" ::: "memory")
; #define PG8_WAIT_L(n) asm volatile("s_waitcnt lgkmcnt(" #n ")" ::: "memory")
; #define PG8_BAR __builtin_amdgcn_s_barrier()
; #define PG8_SCHED __builtin_amdgcn_sched_barrier(0)
; template <class Sched, class Epi>
; __device__ __forceinline__ void gemm_run(LAS unsigned char* lds, const Sched& S, const Epi& E) {
;     ...
;             PG8_LDA(At, 1, 1); PG8_STAGE(PG8_SB(1, 0), b3, RB, lb2); PG8_STAGE(PG8_SB(1, 1), b3 + (size_t)HALF * lb2, RB, lb2); PG8_STAGE(PG8_SA(1, 0), a3, RA, la2);
;             PG8_WAIT_V(8); PG8_WAIT_L(0); PG8_BAR; PG8_MMA(1, 0, At, B0); PG8_MMA(1, 1, At, B1); PG8_BAR; PG8_SCHED;
;         }
;         if (wr == 0) PG8_BAR;
	s_add_i32 s42, s45, s3
	v_lshl_add_u64 v[224:225], v[224:225], 0, s[10:11]
	s_mov_b32 m0, s42
	ds_read_b128 v[184:187], v193 offset:49152
	ds_read_b128 v[196:199], v193 offset:50176
	ds_read_b128 v[200:203], v193 offset:51200
	ds_read_b128 v[204:207], v193 offset:52224
	ds_read_b128 v[208:211], v193 offset:53248
	ds_read_b128 v[212:215], v193 offset:54272
	ds_read_b128 v[216:219], v193 offset:55296
	ds_read_b128 v[220:223], v193 offset:56320
	global_load_lds_dwordx4 v[224:225], off
	s_add_i32 m0, s42, 0x2000
	s_add_u32 s40, s40, 0x80080
	v_lshl_add_u64 v[224:225], v[226:227], 0, s[10:11]
	s_addc_u32 s41, s41, 0
	global_load_lds_dwordx4 v[224:225], off
	v_lshl_add_u64 v[224:225], s[40:41], 0, v[156:157]
	s_add_i32 s42, s46, s3
	v_lshl_add_u64 v[224:225], v[224:225], 0, v[154:155]
	s_mov_b32 m0, s42
	s_nop 0
	global_load_lds_dwordx4 v[224:225], off
	v_lshl_add_u64 v[224:225], s[40:41], 0, v[160:161]
	v_lshl_add_u64 v[224:225], v[224:225], 0, v[154:155]
	s_add_i32 m0, s42, 0x2000
	s_nop 0
	global_load_lds_dwordx4 v[224:225], off
	v_lshl_add_u64 v[224:225], v[228:229], 0, s[10:11]
	s_mov_b32 m0, s55
	s_nop 0
	global_load_lds_dwordx4 v[224:225], off
	v_lshl_add_u64 v[224:225], v[230:231], 0, s[10:11]
	s_mov_b32 m0, s56
	s_nop 0
	global_load_lds_dwordx4 v[224:225], off
	s_waitcnt vmcnt(8)
	s_waitcnt lgkmcnt(0)
	s_barrier
	s_waitcnt lgkmcnt(0)
	v_mfma_f32_16x16x32_bf16 v[62:65], v[134:137], v[184:187], v[62:65]
	v_mfma_f32_16x16x32_bf16 v[58:61], v[142:145], v[184:187], v[58:61]
	v_mfma_f32_16x16x32_bf16 v[46:49], v[134:137], v[200:203], v[46:49]
	v_mfma_f32_16x16x32_bf16 v[42:45], v[142:145], v[200:203], v[42:45]
	v_mfma_f32_16x16x32_bf16 v[30:33], v[134:137], v[208:211], v[30:33]
	v_mfma_f32_16x16x32_bf16 v[26:29], v[142:145], v[208:211], v[26:29]
	v_mfma_f32_16x16x32_bf16 v[14:17], v[134:137], v[216:219], v[14:17]
	v_mfma_f32_16x16x32_bf16 v[10:13], v[142:145], v[216:219], v[10:13]
	v_mfma_f32_16x16x32_bf16 v[62:65], v[138:141], v[196:199], v[62:65]
	v_mfma_f32_16x16x32_bf16 v[58:61], v[146:149], v[196:199], v[58:61]
	v_mfma_f32_16x16x32_bf16 v[46:49], v[138:141], v[204:207], v[46:49]
	v_mfma_f32_16x16x32_bf16 v[42:45], v[146:149], v[204:207], v[42:45]
	v_mfma_f32_16x16x32_bf16 v[30:33], v[138:141], v[212:215], v[30:33]
	v_mfma_f32_16x16x32_bf16 v[26:29], v[146:149], v[212:215], v[26:29]
	v_mfma_f32_16x16x32_bf16 v[14:17], v[138:141], v[220:223], v[14:17]
	v_mfma_f32_16x16x32_bf16 v[10:13], v[146:149], v[220:223], v[10:13]
	v_mfma_f32_16x16x32_bf16 v[54:57], v[150:153], v[184:187], v[54:57]
	v_mfma_f32_16x16x32_bf16 v[50:53], v[176:179], v[184:187], v[50:53]
	v_mfma_f32_16x16x32_bf16 v[38:41], v[150:153], v[200:203], v[38:41]
	v_mfma_f32_16x16x32_bf16 v[34:37], v[176:179], v[200:203], v[34:37]
	v_mfma_f32_16x16x32_bf16 v[22:25], v[150:153], v[208:211], v[22:25]
	v_mfma_f32_16x16x32_bf16 v[18:21], v[176:179], v[208:211], v[18:21]
	v_mfma_f32_16x16x32_bf16 v[6:9], v[150:153], v[216:219], v[6:9]
	v_mfma_f32_16x16x32_bf16 v[2:5], v[176:179], v[216:219], v[2:5]
	v_mfma_f32_16x16x32_bf16 v[54:57], v[172:175], v[196:199], v[54:57]
	v_mfma_f32_16x16x32_bf16 v[50:53], v[180:183], v[196:199], v[50:53]
	v_mfma_f32_16x16x32_bf16 v[38:41], v[172:175], v[204:207], v[38:41]
	v_mfma_f32_16x16x32_bf16 v[34:37], v[180:183], v[204:207], v[34:37]
	v_mfma_f32_16x16x32_bf16 v[22:25], v[172:175], v[212:215], v[22:25]
	v_mfma_f32_16x16x32_bf16 v[18:21], v[180:183], v[212:215], v[18:21]
	v_mfma_f32_16x16x32_bf16 v[6:9], v[172:175], v[220:223], v[6:9]
	v_mfma_f32_16x16x32_bf16 v[2:5], v[180:183], v[220:223], v[2:5]
	s_barrier
	s_add_i32 s44, s44, 2
	s_add_u32 s38, s38, 0x100
	s_addc_u32 s39, s39, 0
	s_cmp_gt_u32 s44, 29
	s_cbranch_scc0 .LBB0_894
	s_and_b64 vcc, exec, s[12:13]
	s_cbranch_vccz .LBB0_897
	s_barrier

; #define PG8_STAGE(bufoff, gbase, RR, ld) do { _Pragma("unroll") for (int _i = 0; _i < 2; ++_i) \
;         __builtin_amdgcn_global_load_lds((const unsigned*)((const char*)(gbase) + (RR)[_i] * (ld) + C2[_i]), (LAS unsigned*)(lds + (bufoff) + ldsw + _i * 8192), 16, 0, 0); } while (0)
; #define PG8_LDA(dst, b, h) do { _Pragma("unroll") for (int m = 0; m < 4; ++m) _Pragma("unroll") for (int k = 0; k < 2; ++k) dst[m][k] = *(const LAS bf16x8*)(lds + PG8_SA(b, h) + aoff + m * 2048 + k * 1024); } while (0)
; #define PG8_LDB(dst, b, h) do { _Pragma("unroll") for (int n = 0; n < 2; ++n) _Pragma("unroll") for (int k = 0; k < 2; ++k) dst[n][k] = *(const LAS bf16x8*)(lds + PG8_SB(b, h) + boff + n * 2048 + k * 1024); } while (0)
; #define PG8_MMA(ai, bj, At, Bt) do { __builtin_amdgcn_s_setprio(1); _Pragma("unroll") for (int m = 0; m < 4; ++m) _Pragma("unroll") for (int n = 0; n < 2; ++n) _Pragma("unroll") for (int k = 0; k < 2; ++k) \
;         acc[ai][bj][m][n] = __builtin_amdgcn_mfma_f32_16x16x32_bf16(Bt[n][k], At[m][k], acc[ai][bj][m][n], 0, 0, 0); __builtin_amdgcn_s_setprio(0); } while (0)
; #define PG8_WAIT_V(n) asm volatile("s_waitcnt vmcnt(" #n ")" ::: "memory")
; #define PG8_WAIT_L(n) asm volatile("s_waitcnt lgkmcnt(" #n ")" ::: "memory")
; #define PG8_BAR __builtin_amdgcn_s_barrier()
; #define PG8_SCHED __builtin_amdgcn_sched_barrier(0)
; template <class Sched, class Epi>
; __device__ __forceinline__ void gemm_run(LAS unsigned char* lds, const Sched& S, const Epi& E) {
;     ...
;             PG8_LDB(B0, 0, 0); PG8_LDB(B1, 0, 1); PG8_SCHED; PG8_LDA(At, 0, 0); PG8_STAGE(PG8_SA(1, 1), a1 + (size_t)HALF * lda, RA, lda);
;             PG8_WAIT_V(8); PG8_WAIT_L(0); PG8_BAR; PG8_MMA(0, 0, At, B0); PG8_MMA(0, 1, At, B1); PG8_BAR; PG8_SCHED;
;             PG8_LDA(At, 0, 1); PG8_STAGE(PG8_SB(0, 0), b2, RB, lb2); PG8_STAGE(PG8_SB(0, 1), b2 + (size_t)HALF * lb2, RB, lb2); PG8_STAGE(PG8_SA(0, 0), a2, RA, la2);
;             PG8_WAIT_V(8); PG8_WAIT_L(0); PG8_BAR; PG8_MMA(1, 0, At, B0); PG8_MMA(1, 1, At, B1); PG8_BAR; PG8_SCHED;
.LBB0_999:
	ds_read_b128 v[156:159], v152
	ds_read_b128 v[160:163], v152 offset:1024
	ds_read_b128 v[164:167], v152 offset:2048
	ds_read_b128 v[168:171], v152 offset:3072
	ds_read_b128 v[172:175], v153
	ds_read_b128 v[176:179], v153 offset:1024
	ds_read_b128 v[180:183], v153 offset:2048
	ds_read_b128 v[184:187], v153 offset:3072
	s_add_u32 s36, s28, s30
	s_addc_u32 s37, s29, s31
	s_add_u32 s36, s36, 0x100
	s_addc_u32 s37, s37, 0
	s_add_u32 s56, s15, s30
	s_addc_u32 s57, s54, s31
	s_cmpk_eq_i32 s30, 0xf00
	s_cselect_b32 s39, s17, s37
	s_cselect_b32 s38, s16, s36
	s_cselect_b32 s37, s21, s57
	s_cselect_b32 s36, s20, s56
	v_lshl_add_u64 v[220:221], v[146:147], 0, s[30:31]
	s_add_i32 m0, s42, 0xc000
	ds_read_b128 v[188:191], v154
	ds_read_b128 v[192:195], v154 offset:1024
	ds_read_b128 v[196:199], v154 offset:2048
	ds_read_b128 v[200:203], v154 offset:3072
	ds_read_b128 v[204:207], v154 offset:4096
	ds_read_b128 v[208:211], v154 offset:5120
	ds_read_b128 v[212:215], v154 offset:6144
	ds_read_b128 v[216:219], v154 offset:7168
	global_load_lds_dwordx4 v[220:221], off
	v_lshl_add_u64 v[220:221], v[148:149], 0, s[30:31]
	s_add_i32 m0, s42, 0xe000
	s_nop 0
	global_load_lds_dwordx4 v[220:221], off
	s_waitcnt vmcnt(8)
	s_waitcnt lgkmcnt(0)
	s_barrier
	s_waitcnt lgkmcnt(0)
	v_mfma_f32_16x16x32_bf16 v[126:129], v[156:159], v[188:191], v[126:129]
	v_mfma_f32_16x16x32_bf16 v[122:125], v[164:167], v[188:191], v[122:125]
	v_mfma_f32_16x16x32_bf16 v[110:113], v[156:159], v[196:199], v[110:113]
	v_mfma_f32_16x16x32_bf16 v[106:109], v[164:167], v[196:199], v[106:109]
	v_mfma_f32_16x16x32_bf16 v[94:97], v[156:159], v[204:207], v[94:97]
	v_mfma_f32_16x16x32_bf16 v[90:93], v[164:167], v[204:207], v[90:93]
	v_mfma_f32_16x16x32_bf16 v[78:81], v[156:159], v[212:215], v[78:81]
	v_mfma_f32_16x16x32_bf16 v[74:77], v[164:167], v[212:215], v[74:77]
	v_mfma_f32_16x16x32_bf16 v[126:129], v[160:163], v[192:195], v[126:129]
	v_mfma_f32_16x16x32_bf16 v[122:125], v[168:171], v[192:195], v[122:125]
	v_mfma_f32_16x16x32_bf16 v[110:113], v[160:163], v[200:203], v[110:113]
	v_mfma_f32_16x16x32_bf16 v[106:109], v[168:171], v[200:203], v[106:109]
	v_mfma_f32_16x16x32_bf16 v[94:97], v[160:163], v[208:211], v[94:97]
	v_mfma_f32_16x16x32_bf16 v[90:93], v[168:171], v[208:211], v[90:93]
	v_mfma_f32_16x16x32_bf16 v[78:81], v[160:163], v[216:219], v[78:81]
	v_mfma_f32_16x16x32_bf16 v[74:77], v[168:171], v[216:219], v[74:77]
	v_mfma_f32_16x16x32_bf16 v[118:121], v[172:175], v[188:191], v[118:121]
	v_mfma_f32_16x16x32_bf16 v[114:117], v[180:183], v[188:191], v[114:117]
	v_mfma_f32_16x16x32_bf16 v[102:105], v[172:175], v[196:199], v[102:105]
	v_mfma_f32_16x16x32_bf16 v[98:101], v[180:183], v[196:199], v[98:101]
	v_mfma_f32_16x16x32_bf16 v[86:89], v[172:175], v[204:207], v[86:89]
	v_mfma_f32_16x16x32_bf16 v[82:85], v[180:183], v[204:207], v[82:85]
	v_mfma_f32_16x16x32_bf16 v[70:73], v[172:175], v[212:215], v[70:73]
	v_mfma_f32_16x16x32_bf16 v[66:69], v[180:183], v[212:215], v[66:69]
	v_mfma_f32_16x16x32_bf16 v[118:121], v[176:179], v[192:195], v[118:121]
	v_mfma_f32_16x16x32_bf16 v[114:117], v[184:187], v[192:195], v[114:117]
	v_mfma_f32_16x16x32_bf16 v[102:105], v[176:179], v[200:203], v[102:105]
	v_mfma_f32_16x16x32_bf16 v[98:101], v[184:187], v[200:203], v[98:101]
	v_mfma_f32_16x16x32_bf16 v[86:89], v[176:179], v[208:211], v[86:89]
	v_mfma_f32_16x16x32_bf16 v[82:85], v[184:187], v[208:211], v[82:85]
	v_mfma_f32_16x16x32_bf16 v[70:73], v[176:179], v[216:219], v[70:73]
	v_mfma_f32_16x16x32_bf16 v[66:69], v[184:187], v[216:219], v[66:69]
	s_barrier
	v_lshl_add_u64 v[220:221], s[36:37], 0, v[132:133]
	s_add_i32 s56, s49, s3
	v_lshl_add_u64 v[220:221], v[220:221], 0, v[130:131]
	s_mov_b32 m0, s56
	ds_read_b128 v[188:191], v154 offset:16384
	ds_read_b128 v[192:195], v154 offset:17408
	ds_read_b128 v[196:199], v154 offset:18432
	ds_read_b128 v[200:203], v154 offset:19456
	ds_read_b128 v[204:207], v154 offset:20480
	ds_read_b128 v[208:211], v154 offset:21504
	ds_read_b128 v[212:215], v154 offset:22528
	ds_read_b128 v[216:219], v154 offset:23552
	global_load_lds_dwordx4 v[220:221], off
	s_add_i32 m0, s56, 0x2000
	s_add_u32 s56, s36, 0x80000
	v_lshl_add_u64 v[222:223], s[36:37], 0, v[136:137]
	s_addc_u32 s57, s37, 0
	v_lshl_add_u64 v[222:223], v[222:223], 0, v[130:131]
	v_lshl_add_u64 v[224:225], s[56:57], 0, v[132:133]
	s_add_i32 s58, s50, s3
	global_load_lds_dwordx4 v[222:223], off
	v_lshl_add_u64 v[224:225], v[224:225], 0, v[130:131]
	s_mov_b32 m0, s58
	v_lshl_add_u64 v[226:227], s[38:39], 0, v[140:141]
	global_load_lds_dwordx4 v[224:225], off
	v_lshl_add_u64 v[224:225], s[56:57], 0, v[136:137]
	v_lshl_add_u64 v[224:225], v[224:225], 0, v[130:131]
	s_add_i32 m0, s58, 0x2000
	v_lshl_add_u64 v[226:227], v[226:227], 0, v[130:131]
	global_load_lds_dwordx4 v[224:225], off
	v_lshl_add_u64 v[224:225], s[38:39], 0, v[138:139]
	v_lshl_add_u64 v[224:225], v[224:225], 0, v[130:131]
	s_mov_b32 m0, s42
	s_nop 0
	global_load_lds_dwordx4 v[224:225], off
	s_mov_b32 m0, s43
	s_nop 0
	global_load_lds_dwordx4 v[226:227], off
	s_waitcnt vmcnt(8)
	s_waitcnt lgkmcnt(0)
	s_barrier
; #define PG8_STAGE(bufoff, gbase, RR, ld) do { _Pragma("unroll") for (int _i = 0; _i < 2; ++_i) \
;         __builtin_amdgcn_global_load_lds((const unsigned*)((const char*)(gbase) + (RR)[_i] * (ld) + C2[_i]), (LAS unsigned*)(lds + (bufoff) + ldsw + _i * 8192), 16, 0, 0); } while (0)
; #define PG8_LDA(dst, b, h) do { _Pragma("unroll") for (int m = 0; m < 4; ++m) _Pragma("unroll") for (int k = 0; k < 2; ++k) dst[m][k] = *(const LAS bf16x8*)(lds + PG8_SA(b, h) + aoff + m * 2048 + k * 1024); } while (0)
; #define PG8_LDB(dst, b, h) do { _Pragma("unroll") for (int n = 0; n < 2; ++n) _Pragma("unroll") for (int k = 0; k < 2; ++k) dst[n][k] = *(const LAS bf16x8*)(lds + PG8_SB(b, h) + boff + n * 2048 + k * 1024); } while (0)
; #define PG8_MMA(ai, bj, At, Bt) do { __builtin_amdgcn_s_setprio(1); _Pragma("unroll") for (int m = 0; m < 4; ++m) _Pragma("unroll") for (int n = 0; n < 2; ++n) _Pragma("unroll") for (int k = 0; k < 2; ++k) \
;         acc[ai][bj][m][n] = __builtin_amdgcn_mfma_f32_16x16x32_bf16(Bt[n][k], At[m][k], acc[ai][bj][m][n], 0, 0, 0); __builtin_amdgcn_s_setprio(0); } while (0)
; #define PG8_WAIT_V(n) asm volatile("s_waitcnt vmcnt(" #n ")" ::: "memory")
; #define PG8_WAIT_L(n) asm volatile("s_waitcnt lgkmcnt(" #n ")" ::: "memory")
; #define PG8_BAR __builtin_amdgcn_s_barrier()
; #define PG8_SCHED __builtin_amdgcn_sched_barrier(0)
; template <class Sched, class Epi>
; __device__ __forceinline__ void gemm_run(LAS unsigned char* lds, const Sched& S, const Epi& E) {
;     ...
;             PG8_WAIT_V(8); PG8_WAIT_L(0); PG8_BAR; PG8_MMA(1, 0, At, B0); PG8_MMA(1, 1, At, B1); PG8_BAR; PG8_SCHED;
;             PG8_LDB(B0, 1, 0); PG8_LDB(B1, 1, 1); PG8_SCHED; PG8_LDA(At, 1, 0); PG8_STAGE(PG8_SA(0, 1), a2 + (size_t)HALF * la2, RA, la2);
;             PG8_WAIT_V(8); PG8_WAIT_L(0); PG8_BAR; PG8_MMA(0, 0, At, B0); PG8_MMA(0, 1, At, B1); PG8_BAR; PG8_SCHED;
	s_waitcnt lgkmcnt(0)
	v_mfma_f32_16x16x32_bf16 v[62:65], v[156:159], v[188:191], v[62:65]
	v_mfma_f32_16x16x32_bf16 v[58:61], v[164:167], v[188:191], v[58:61]
	v_mfma_f32_16x16x32_bf16 v[46:49], v[156:159], v[196:199], v[46:49]
	v_mfma_f32_16x16x32_bf16 v[42:45], v[164:167], v[196:199], v[42:45]
	v_mfma_f32_16x16x32_bf16 v[30:33], v[156:159], v[204:207], v[30:33]
	v_mfma_f32_16x16x32_bf16 v[26:29], v[164:167], v[204:207], v[26:29]
	v_mfma_f32_16x16x32_bf16 v[14:17], v[156:159], v[212:215], v[14:17]
	v_mfma_f32_16x16x32_bf16 v[10:13], v[164:167], v[212:215], v[10:13]
	v_mfma_f32_16x16x32_bf16 v[62:65], v[160:163], v[192:195], v[62:65]
	v_mfma_f32_16x16x32_bf16 v[58:61], v[168:171], v[192:195], v[58:61]
	v_mfma_f32_16x16x32_bf16 v[46:49], v[160:163], v[200:203], v[46:49]
	v_mfma_f32_16x16x32_bf16 v[42:45], v[168:171], v[200:203], v[42:45]
	v_mfma_f32_16x16x32_bf16 v[30:33], v[160:163], v[208:211], v[30:33]
	v_mfma_f32_16x16x32_bf16 v[26:29], v[168:171], v[208:211], v[26:29]
	v_mfma_f32_16x16x32_bf16 v[14:17], v[160:163], v[216:219], v[14:17]
	v_mfma_f32_16x16x32_bf16 v[10:13], v[168:171], v[216:219], v[10:13]
	v_mfma_f32_16x16x32_bf16 v[54:57], v[172:175], v[188:191], v[54:57]
	v_mfma_f32_16x16x32_bf16 v[50:53], v[180:183], v[188:191], v[50:53]
	v_mfma_f32_16x16x32_bf16 v[38:41], v[172:175], v[196:199], v[38:41]
	v_mfma_f32_16x16x32_bf16 v[34:37], v[180:183], v[196:199], v[34:37]
	v_mfma_f32_16x16x32_bf16 v[22:25], v[172:175], v[204:207], v[22:25]
	v_mfma_f32_16x16x32_bf16 v[18:21], v[180:183], v[204:207], v[18:21]
	v_mfma_f32_16x16x32_bf16 v[6:9], v[172:175], v[212:215], v[6:9]
	v_mfma_f32_16x16x32_bf16 v[2:5], v[180:183], v[212:215], v[2:5]
	v_mfma_f32_16x16x32_bf16 v[54:57], v[176:179], v[192:195], v[54:57]
	v_mfma_f32_16x16x32_bf16 v[50:53], v[184:187], v[192:195], v[50:53]
	v_mfma_f32_16x16x32_bf16 v[38:41], v[176:179], v[200:203], v[38:41]
	v_mfma_f32_16x16x32_bf16 v[34:37], v[184:187], v[200:203], v[34:37]
	v_mfma_f32_16x16x32_bf16 v[22:25], v[176:179], v[208:211], v[22:25]
	v_mfma_f32_16x16x32_bf16 v[18:21], v[184:187], v[208:211], v[18:21]
	v_mfma_f32_16x16x32_bf16 v[6:9], v[176:179], v[216:219], v[6:9]
	v_mfma_f32_16x16x32_bf16 v[2:5], v[184:187], v[216:219], v[2:5]
	s_barrier
	s_add_i32 s56, 0, 0x18000
	s_add_i32 s57, 0, 0x1c000
	v_add_u32_e32 v168, s56, v151
	v_add_u32_e32 v184, s57, v151
	ds_read_b128 v[156:159], v168
	ds_read_b128 v[160:163], v168 offset:1024
	ds_read_b128 v[164:167], v168 offset:2048
	ds_read_b128 v[168:171], v168 offset:3072
	ds_read_b128 v[172:175], v184
	ds_read_b128 v[176:179], v184 offset:1024
	ds_read_b128 v[180:183], v184 offset:2048
	ds_read_b128 v[184:187], v184 offset:3072
	s_add_u32 s38, s38, 0x80000
	s_addc_u32 s39, s39, 0
	v_lshl_add_u64 v[228:229], s[38:39], 0, v[138:139]
	s_mov_b32 m0, s44
	v_lshl_add_u64 v[228:229], v[228:229], 0, v[130:131]
	ds_read_b128 v[188:191], v154 offset:32768
	ds_read_b128 v[192:195], v154 offset:33792
	ds_read_b128 v[196:199], v154 offset:34816
	ds_read_b128 v[200:203], v154 offset:35840
	ds_read_b128 v[204:207], v154 offset:36864
	ds_read_b128 v[208:211], v154 offset:37888
	ds_read_b128 v[212:215], v154 offset:38912
	ds_read_b128 v[216:219], v154 offset:39936
	global_load_lds_dwordx4 v[228:229], off
	v_lshl_add_u64 v[228:229], s[38:39], 0, v[140:141]
	v_lshl_add_u64 v[228:229], v[228:229], 0, v[130:131]
	s_mov_b32 m0, s45
	s_nop 0
	global_load_lds_dwordx4 v[228:229], off
	s_waitcnt vmcnt(8)
	s_waitcnt lgkmcnt(0)
	s_barrier
	s_waitcnt lgkmcnt(0)
	v_mfma_f32_16x16x32_bf16 v[126:129], v[156:159], v[188:191], v[126:129]
	v_mfma_f32_16x16x32_bf16 v[122:125], v[164:167], v[188:191], v[122:125]
	v_mfma_f32_16x16x32_bf16 v[110:113], v[156:159], v[196:199], v[110:113]
	v_mfma_f32_16x16x32_bf16 v[106:109], v[164:167], v[196:199], v[106:109]
	v_mfma_f32_16x16x32_bf16 v[94:97], v[156:159], v[204:207], v[94:97]
	v_mfma_f32_16x16x32_bf16 v[90:93], v[164:167], v[204:207], v[90:93]
	v_mfma_f32_16x16x32_bf16 v[78:81], v[156:159], v[212:215], v[78:81]
	v_mfma_f32_16x16x32_bf16 v[74:77], v[164:167], v[212:215], v[74:77]
	v_mfma_f32_16x16x32_bf16 v[126:129], v[160:163], v[192:195], v[126:129]
	v_mfma_f32_16x16x32_bf16 v[122:125], v[168:171], v[192:195], v[122:125]
	v_mfma_f32_16x16x32_bf16 v[110:113], v[160:163], v[200:203], v[110:113]
	v_mfma_f32_16x16x32_bf16 v[106:109], v[168:171], v[200:203], v[106:109]
	v_mfma_f32_16x16x32_bf16 v[94:97], v[160:163], v[208:211], v[94:97]
	v_mfma_f32_16x16x32_bf16 v[90:93], v[168:171], v[208:211], v[90:93]
	v_mfma_f32_16x16x32_bf16 v[78:81], v[160:163], v[216:219], v[78:81]
	v_mfma_f32_16x16x32_bf16 v[74:77], v[168:171], v[216:219], v[74:77]
	v_mfma_f32_16x16x32_bf16 v[118:121], v[172:175], v[188:191], v[118:121]
	v_mfma_f32_16x16x32_bf16 v[114:117], v[180:183], v[188:191], v[114:117]
	v_mfma_f32_16x16x32_bf16 v[102:105], v[172:175], v[196:199], v[102:105]
	v_mfma_f32_16x16x32_bf16 v[98:101], v[180:183], v[196:199], v[98:101]
	v_mfma_f32_16x16x32_bf16 v[86:89], v[172:175], v[204:207], v[86:89]
	v_mfma_f32_16x16x32_bf16 v[82:85], v[180:183], v[204:207], v[82:85]
	v_mfma_f32_16x16x32_bf16 v[70:73], v[172:175], v[212:215], v[70:73]
	v_mfma_f32_16x16x32_bf16 v[66:69], v[180:183], v[212:215], v[66:69]
	v_mfma_f32_16x16x32_bf16 v[118:121], v[176:179], v[192:195], v[118:121]
	v_mfma_f32_16x16x32_bf16 v[114:117], v[184:187], v[192:195], v[114:117]
	v_mfma_f32_16x16x32_bf16 v[102:105], v[176:179], v[200:203], v[102:105]
	v_mfma_f32_16x16x32_bf16 v[98:101], v[184:187], v[200:203], v[98:101]
	v_mfma_f32_16x16x32_bf16 v[86:89], v[176:179], v[208:211], v[86:89]
	v_mfma_f32_16x16x32_bf16 v[82:85], v[184:187], v[208:211], v[82:85]
	v_mfma_f32_16x16x32_bf16 v[70:73], v[176:179], v[216:219], v[70:73]
	v_mfma_f32_16x16x32_bf16 v[66:69], v[184:187], v[216:219], v[66:69]
	s_barrier
; #define PG8_STAGE(bufoff, gbase, RR, ld) do { _Pragma("unroll") for (int _i = 0; _i < 2; ++_i) \
;         __builtin_amdgcn_global_load_lds((const unsigned*)((const char*)(gbase) + (RR)[_i] * (ld) + C2[_i]), (LAS unsigned*)(lds + (bufoff) + ldsw + _i * 8192), 16, 0, 0); } while (0)
; #define PG8_LDA(dst, b, h) do { _Pragma("unroll") for (int m = 0; m < 4; ++m) _Pragma("unroll") for (int k = 0; k < 2; ++k) dst[m][k] = *(const LAS bf16x8*)(lds + PG8_SA(b, h) + aoff + m * 2048 + k * 1024); } while (0)
; #define PG8_MMA(ai, bj, At, Bt) do { __builtin_amdgcn_s_setprio(1); _Pragma("unroll") for (int m = 0; m < 4; ++m) _Pragma("unroll") for (int n = 0; n < 2; ++n) _Pragma("unroll") for (int k = 0; k < 2; ++k) \
;         acc[ai][bj][m][n] = __builtin_amdgcn_mfma_f32_16x16x32_bf16(Bt[n][k], At[m][k], acc[ai][bj][m][n], 0, 0, 0); __builtin_amdgcn_s_setprio(0); } while (0)
; #define PG8_WAIT_V(n) asm volatile("s_waitcnt vmcnt(" #n ")" ::: "memory")
; #define PG8_WAIT_L(n) asm volatile("s_waitcnt lgkmcnt(" #n ")" ::: "memory")
; #define PG8_BAR __builtin_amdgcn_s_barrier()
; #define PG8_SCHED __builtin_amdgcn_sched_barrier(0)
; template <class Sched, class Epi>
; __device__ __forceinline__ void gemm_run(LAS unsigned char* lds, const Sched& S, const Epi& E) {
;     ...
;             PG8_LDA(At, 1, 1); PG8_STAGE(PG8_SB(1, 0), b3, RB, lb2); PG8_STAGE(PG8_SB(1, 1), b3 + (size_t)HALF * lb2, RB, lb2); PG8_STAGE(PG8_SA(1, 0), a3, RA, la2);
;             PG8_WAIT_V(8); PG8_WAIT_L(0); PG8_BAR; PG8_MMA(1, 0, At, B0); PG8_MMA(1, 1, At, B1); PG8_BAR; PG8_SCHED;
;         }
;         if (wr == 0) PG8_BAR;
	s_add_i32 s38, s56, s3
	v_lshl_add_u64 v[220:221], v[220:221], 0, s[6:7]
	s_mov_b32 m0, s38
	ds_read_b128 v[188:191], v154 offset:49152
	ds_read_b128 v[192:195], v154 offset:50176
	ds_read_b128 v[196:199], v154 offset:51200
	ds_read_b128 v[200:203], v154 offset:52224
	ds_read_b128 v[204:207], v154 offset:53248
	ds_read_b128 v[208:211], v154 offset:54272
	ds_read_b128 v[212:215], v154 offset:55296
	ds_read_b128 v[216:219], v154 offset:56320
	global_load_lds_dwordx4 v[220:221], off
	s_add_i32 m0, s38, 0x2000
	s_add_u32 s36, s36, 0x80080
	v_lshl_add_u64 v[220:221], v[222:223], 0, s[6:7]
	s_addc_u32 s37, s37, 0
	global_load_lds_dwordx4 v[220:221], off
	v_lshl_add_u64 v[220:221], s[36:37], 0, v[132:133]
	s_add_i32 s38, s57, s3
	v_lshl_add_u64 v[220:221], v[220:221], 0, v[130:131]
	s_mov_b32 m0, s38
	s_nop 0
	global_load_lds_dwordx4 v[220:221], off
	v_lshl_add_u64 v[220:221], s[36:37], 0, v[136:137]
	v_lshl_add_u64 v[220:221], v[220:221], 0, v[130:131]
	s_add_i32 m0, s38, 0x2000
	s_nop 0
	global_load_lds_dwordx4 v[220:221], off
	v_lshl_add_u64 v[220:221], v[224:225], 0, s[6:7]
	s_mov_b32 m0, s47
	s_nop 0
	global_load_lds_dwordx4 v[220:221], off
	v_lshl_add_u64 v[220:221], v[226:227], 0, s[6:7]
	s_mov_b32 m0, s48
	s_nop 0
	global_load_lds_dwordx4 v[220:221], off
	s_waitcnt vmcnt(8)
	s_waitcnt lgkmcnt(0)
	s_barrier
	s_waitcnt lgkmcnt(0)
	v_mfma_f32_16x16x32_bf16 v[62:65], v[156:159], v[188:191], v[62:65]
	v_mfma_f32_16x16x32_bf16 v[58:61], v[164:167], v[188:191], v[58:61]
	v_mfma_f32_16x16x32_bf16 v[46:49], v[156:159], v[196:199], v[46:49]
	v_mfma_f32_16x16x32_bf16 v[42:45], v[164:167], v[196:199], v[42:45]
	v_mfma_f32_16x16x32_bf16 v[30:33], v[156:159], v[204:207], v[30:33]
	v_mfma_f32_16x16x32_bf16 v[26:29], v[164:167], v[204:207], v[26:29]
	v_mfma_f32_16x16x32_bf16 v[14:17], v[156:159], v[212:215], v[14:17]
	v_mfma_f32_16x16x32_bf16 v[10:13], v[164:167], v[212:215], v[10:13]
	v_mfma_f32_16x16x32_bf16 v[62:65], v[160:163], v[192:195], v[62:65]
	v_mfma_f32_16x16x32_bf16 v[58:61], v[168:171], v[192:195], v[58:61]
	v_mfma_f32_16x16x32_bf16 v[46:49], v[160:163], v[200:203], v[46:49]
	v_mfma_f32_16x16x32_bf16 v[42:45], v[168:171], v[200:203], v[42:45]
	v_mfma_f32_16x16x32_bf16 v[30:33], v[160:163], v[208:211], v[30:33]
	v_mfma_f32_16x16x32_bf16 v[26:29], v[168:171], v[208:211], v[26:29]
	v_mfma_f32_16x16x32_bf16 v[14:17], v[160:163], v[216:219], v[14:17]
	v_mfma_f32_16x16x32_bf16 v[10:13], v[168:171], v[216:219], v[10:13]
	v_mfma_f32_16x16x32_bf16 v[54:57], v[172:175], v[188:191], v[54:57]
	v_mfma_f32_16x16x32_bf16 v[50:53], v[180:183], v[188:191], v[50:53]
	v_mfma_f32_16x16x32_bf16 v[38:41], v[172:175], v[196:199], v[38:41]
	v_mfma_f32_16x16x32_bf16 v[34:37], v[180:183], v[196:199], v[34:37]
	v_mfma_f32_16x16x32_bf16 v[22:25], v[172:175], v[204:207], v[22:25]
	v_mfma_f32_16x16x32_bf16 v[18:21], v[180:183], v[204:207], v[18:21]
	v_mfma_f32_16x16x32_bf16 v[6:9], v[172:175], v[212:215], v[6:9]
	v_mfma_f32_16x16x32_bf16 v[2:5], v[180:183], v[212:215], v[2:5]
	v_mfma_f32_16x16x32_bf16 v[54:57], v[176:179], v[192:195], v[54:57]
	v_mfma_f32_16x16x32_bf16 v[50:53], v[184:187], v[192:195], v[50:53]
	v_mfma_f32_16x16x32_bf16 v[38:41], v[176:179], v[200:203], v[38:41]
	v_mfma_f32_16x16x32_bf16 v[34:37], v[184:187], v[200:203], v[34:37]
	v_mfma_f32_16x16x32_bf16 v[22:25], v[176:179], v[208:211], v[22:25]
	v_mfma_f32_16x16x32_bf16 v[18:21], v[184:187], v[208:211], v[18:21]
	v_mfma_f32_16x16x32_bf16 v[6:9], v[176:179], v[216:219], v[6:9]
	v_mfma_f32_16x16x32_bf16 v[2:5], v[184:187], v[216:219], v[2:5]
	s_barrier
	s_add_i32 s55, s55, 2
	s_add_u32 s30, s30, 0x100
	s_addc_u32 s31, s31, 0
	s_cmp_gt_u32 s55, 29
	s_cbranch_scc0 .LBB0_999
	s_and_b64 vcc, exec, s[8:9]
	s_cbranch_vccz .LBB0_1002
	s_barrier

; #define PG8_STAGE(bufoff, gbase, RR, ld) do { _Pragma("unroll") for (int _i = 0; _i < 2; ++_i) \
;         __builtin_amdgcn_global_load_lds((const unsigned*)((const char*)(gbase) + (RR)[_i] * (ld) + C2[_i]), (LAS unsigned*)(lds + (bufoff) + ldsw + _i * 8192), 16, 0, 0); } while (0)
; #define PG8_LDA(dst, b, h) do { _Pragma("unroll") for (int m = 0; m < 4; ++m) _Pragma("unroll") for (int k = 0; k < 2; ++k) dst[m][k] = *(const LAS bf16x8*)(lds + PG8_SA(b, h) + aoff + m * 2048 + k * 1024); } while (0)
; #define PG8_LDB(dst, b, h) do { _Pragma("unroll") for (int n = 0; n < 2; ++n) _Pragma("unroll") for (int k = 0; k < 2; ++k) dst[n][k] = *(const LAS bf16x8*)(lds + PG8_SB(b, h) + boff + n * 2048 + k * 1024); } while (0)
; #define PG8_MMA(ai, bj, At, Bt) do { __builtin_amdgcn_s_setprio(1); _Pragma("unroll") for (int m = 0; m < 4; ++m) _Pragma("unroll") for (int n = 0; n < 2; ++n) _Pragma("unroll") for (int k = 0; k < 2; ++k) \
;         acc[ai][bj][m][n] = __builtin_amdgcn_mfma_f32_16x16x32_bf16(Bt[n][k], At[m][k], acc[ai][bj][m][n], 0, 0, 0); __builtin_amdgcn_s_setprio(0); } while (0)
; #define PG8_WAIT_V(n) asm volatile("s_waitcnt vmcnt(" #n ")" ::: "memory")
; #define PG8_WAIT_L(n) asm volatile("s_waitcnt lgkmcnt(" #n ")" ::: "memory")
; #define PG8_BAR __builtin_amdgcn_s_barrier()
; #define PG8_SCHED __builtin_amdgcn_sched_barrier(0)
; template <class Sched, class Epi>
; __device__ __forceinline__ void gemm_run(LAS unsigned char* lds, const Sched& S, const Epi& E) {
;     ...
;             PG8_LDB(B0, 0, 0); PG8_LDB(B1, 0, 1); PG8_SCHED; PG8_LDA(At, 0, 0); PG8_STAGE(PG8_SA(1, 1), a1 + (size_t)HALF * lda, RA, lda);
;             PG8_WAIT_V(8); PG8_WAIT_L(0); PG8_BAR; PG8_MMA(0, 0, At, B0); PG8_MMA(0, 1, At, B1); PG8_BAR; PG8_SCHED;
;             PG8_LDA(At, 0, 1); PG8_STAGE(PG8_SB(0, 0), b2, RB, lb2); PG8_STAGE(PG8_SB(0, 1), b2 + (size_t)HALF * lb2, RB, lb2); PG8_STAGE(PG8_SA(0, 0), a2, RA, la2);
;             PG8_WAIT_V(8); PG8_WAIT_L(0); PG8_BAR; PG8_MMA(1, 0, At, B0); PG8_MMA(1, 1, At, B1); PG8_BAR; PG8_SCHED;
.LBB0_1068:
	v_add_u32_e32 v151, s50, v149
	ds_read_b128 v[152:155], v151
	ds_read_b128 v[156:159], v151 offset:1024
	ds_read_b128 v[160:163], v151 offset:2048
	ds_read_b128 v[164:167], v151 offset:3072
	v_add_u32_e32 v151, s51, v149
	s_add_u32 s30, s20, s28
	ds_read_b128 v[168:171], v151
	ds_read_b128 v[172:175], v151 offset:1024
	ds_read_b128 v[176:179], v151 offset:2048
	ds_read_b128 v[180:183], v151 offset:3072
	s_addc_u32 s31, s21, s29
	s_add_u32 s30, s30, 0x100
	s_addc_u32 s31, s31, 0
	s_add_u32 s68, s65, s28
	s_addc_u32 s69, s66, s29
	s_cmpk_eq_i32 s28, 0x2b00
	s_cselect_b32 s37, s17, s31
	s_cselect_b32 s36, s16, s30
	s_cselect_b32 s31, s19, s69
	s_cselect_b32 s30, s18, s68
	s_mov_b32 m0, s52
	v_lshl_add_u64 v[184:185], v[144:145], 0, s[28:29]
	ds_read_b128 v[190:193], v150
	ds_read_b128 v[194:197], v150 offset:1024
	ds_read_b128 v[198:201], v150 offset:2048
	ds_read_b128 v[202:205], v150 offset:3072
	ds_read_b128 v[206:209], v150 offset:4096
	ds_read_b128 v[210:213], v150 offset:5120
	ds_read_b128 v[214:217], v150 offset:6144
	ds_read_b128 v[218:221], v150 offset:7168
	global_load_lds_dwordx4 v[184:185], off
	v_lshl_add_u64 v[184:185], v[146:147], 0, s[28:29]
	s_mov_b32 m0, s53
	s_nop 0
	global_load_lds_dwordx4 v[184:185], off
	s_waitcnt vmcnt(8)
	s_waitcnt lgkmcnt(0)
	s_barrier
	s_waitcnt lgkmcnt(0)
	v_mfma_f32_16x16x32_bf16 v[126:129], v[152:155], v[190:193], v[126:129]
	v_mfma_f32_16x16x32_bf16 v[122:125], v[160:163], v[190:193], v[122:125]
	v_mfma_f32_16x16x32_bf16 v[110:113], v[152:155], v[198:201], v[110:113]
	v_mfma_f32_16x16x32_bf16 v[106:109], v[160:163], v[198:201], v[106:109]
	v_mfma_f32_16x16x32_bf16 v[94:97], v[152:155], v[206:209], v[94:97]
	v_mfma_f32_16x16x32_bf16 v[90:93], v[160:163], v[206:209], v[90:93]
	v_mfma_f32_16x16x32_bf16 v[78:81], v[152:155], v[214:217], v[78:81]
	v_mfma_f32_16x16x32_bf16 v[74:77], v[160:163], v[214:217], v[74:77]
	v_mfma_f32_16x16x32_bf16 v[126:129], v[156:159], v[194:197], v[126:129]
	v_mfma_f32_16x16x32_bf16 v[122:125], v[164:167], v[194:197], v[122:125]
	v_mfma_f32_16x16x32_bf16 v[110:113], v[156:159], v[202:205], v[110:113]
	v_mfma_f32_16x16x32_bf16 v[106:109], v[164:167], v[202:205], v[106:109]
	v_mfma_f32_16x16x32_bf16 v[94:97], v[156:159], v[210:213], v[94:97]
	v_mfma_f32_16x16x32_bf16 v[90:93], v[164:167], v[210:213], v[90:93]
	v_mfma_f32_16x16x32_bf16 v[78:81], v[156:159], v[218:221], v[78:81]
	v_mfma_f32_16x16x32_bf16 v[74:77], v[164:167], v[218:221], v[74:77]
	v_mfma_f32_16x16x32_bf16 v[118:121], v[168:171], v[190:193], v[118:121]
	v_mfma_f32_16x16x32_bf16 v[114:117], v[176:179], v[190:193], v[114:117]
	v_mfma_f32_16x16x32_bf16 v[102:105], v[168:171], v[198:201], v[102:105]
	v_mfma_f32_16x16x32_bf16 v[98:101], v[176:179], v[198:201], v[98:101]
	v_mfma_f32_16x16x32_bf16 v[86:89], v[168:171], v[206:209], v[86:89]
	v_mfma_f32_16x16x32_bf16 v[82:85], v[176:179], v[206:209], v[82:85]
	v_mfma_f32_16x16x32_bf16 v[70:73], v[168:171], v[214:217], v[70:73]
	v_mfma_f32_16x16x32_bf16 v[66:69], v[176:179], v[214:217], v[66:69]
	v_mfma_f32_16x16x32_bf16 v[118:121], v[172:175], v[194:197], v[118:121]
	v_mfma_f32_16x16x32_bf16 v[114:117], v[180:183], v[194:197], v[114:117]
	v_mfma_f32_16x16x32_bf16 v[102:105], v[172:175], v[202:205], v[102:105]
	v_mfma_f32_16x16x32_bf16 v[98:101], v[180:183], v[202:205], v[98:101]
	v_mfma_f32_16x16x32_bf16 v[86:89], v[172:175], v[210:213], v[86:89]
	v_mfma_f32_16x16x32_bf16 v[82:85], v[180:183], v[210:213], v[82:85]
	v_mfma_f32_16x16x32_bf16 v[70:73], v[172:175], v[218:221], v[70:73]
	v_mfma_f32_16x16x32_bf16 v[66:69], v[180:183], v[218:221], v[66:69]
	s_barrier
	v_lshl_add_u64 v[184:185], s[30:31], 0, v[132:133]
	s_add_u32 s68, s30, 0x160000
	s_mov_b32 m0, s54
	v_lshl_add_u64 v[184:185], v[184:185], 0, v[130:131]
	v_lshl_add_u64 v[222:223], s[30:31], 0, v[134:135]
	s_addc_u32 s69, s31, 0
	ds_read_b128 v[190:193], v150 offset:16384
	ds_read_b128 v[194:197], v150 offset:17408
	ds_read_b128 v[198:201], v150 offset:18432
	ds_read_b128 v[202:205], v150 offset:19456
	ds_read_b128 v[206:209], v150 offset:20480
	ds_read_b128 v[210:213], v150 offset:21504
	ds_read_b128 v[214:217], v150 offset:22528
	ds_read_b128 v[218:221], v150 offset:23552
	global_load_lds_dwordx4 v[184:185], off
	v_lshl_add_u64 v[222:223], v[222:223], 0, v[130:131]
	s_mov_b32 m0, s55
	v_lshl_add_u64 v[224:225], s[68:69], 0, v[132:133]
	global_load_lds_dwordx4 v[222:223], off
	v_lshl_add_u64 v[224:225], v[224:225], 0, v[130:131]
	s_mov_b32 m0, s56
	v_lshl_add_u64 v[226:227], s[36:37], 0, v[138:139]
	global_load_lds_dwordx4 v[224:225], off
	v_lshl_add_u64 v[224:225], s[68:69], 0, v[134:135]
	v_lshl_add_u64 v[224:225], v[224:225], 0, v[130:131]
	s_mov_b32 m0, s57
	v_lshl_add_u64 v[226:227], v[226:227], 0, v[130:131]
	global_load_lds_dwordx4 v[224:225], off
	v_lshl_add_u64 v[224:225], s[36:37], 0, v[136:137]
	v_lshl_add_u64 v[224:225], v[224:225], 0, v[130:131]
	s_mov_b32 m0, s42
	s_nop 0
	global_load_lds_dwordx4 v[224:225], off
	s_mov_b32 m0, s43
	s_nop 0
	global_load_lds_dwordx4 v[226:227], off
	s_waitcnt vmcnt(8)
	s_waitcnt lgkmcnt(0)
	s_barrier
; #define PG8_STAGE(bufoff, gbase, RR, ld) do { _Pragma("unroll") for (int _i = 0; _i < 2; ++_i) \
;         __builtin_amdgcn_global_load_lds((const unsigned*)((const char*)(gbase) + (RR)[_i] * (ld) + C2[_i]), (LAS unsigned*)(lds + (bufoff) + ldsw + _i * 8192), 16, 0, 0); } while (0)
; #define PG8_LDA(dst, b, h) do { _Pragma("unroll") for (int m = 0; m < 4; ++m) _Pragma("unroll") for (int k = 0; k < 2; ++k) dst[m][k] = *(const LAS bf16x8*)(lds + PG8_SA(b, h) + aoff + m * 2048 + k * 1024); } while (0)
; #define PG8_LDB(dst, b, h) do { _Pragma("unroll") for (int n = 0; n < 2; ++n) _Pragma("unroll") for (int k = 0; k < 2; ++k) dst[n][k] = *(const LAS bf16x8*)(lds + PG8_SB(b, h) + boff + n * 2048 + k * 1024); } while (0)
; #define PG8_MMA(ai, bj, At, Bt) do { __builtin_amdgcn_s_setprio(1); _Pragma("unroll") for (int m = 0; m < 4; ++m) _Pragma("unroll") for (int n = 0; n < 2; ++n) _Pragma("unroll") for (int k = 0; k < 2; ++k) \
;         acc[ai][bj][m][n] = __builtin_amdgcn_mfma_f32_16x16x32_bf16(Bt[n][k], At[m][k], acc[ai][bj][m][n], 0, 0, 0); __builtin_amdgcn_s_setprio(0); } while (0)
; #define PG8_WAIT_V(n) asm volatile("s_waitcnt vmcnt(" #n ")" ::: "memory")
; #define PG8_WAIT_L(n) asm volatile("s_waitcnt lgkmcnt(" #n ")" ::: "memory")
; #define PG8_BAR __builtin_amdgcn_s_barrier()
; #define PG8_SCHED __builtin_amdgcn_sched_barrier(0)
; template <class Sched, class Epi>
; __device__ __forceinline__ void gemm_run(LAS unsigned char* lds, const Sched& S, const Epi& E) {
;     ...
;             PG8_WAIT_V(8); PG8_WAIT_L(0); PG8_BAR; PG8_MMA(1, 0, At, B0); PG8_MMA(1, 1, At, B1); PG8_BAR; PG8_SCHED;
;             PG8_LDB(B0, 1, 0); PG8_LDB(B1, 1, 1); PG8_SCHED; PG8_LDA(At, 1, 0); PG8_STAGE(PG8_SA(0, 1), a2 + (size_t)HALF * la2, RA, la2);
;             PG8_WAIT_V(8); PG8_WAIT_L(0); PG8_BAR; PG8_MMA(0, 0, At, B0); PG8_MMA(0, 1, At, B1); PG8_BAR; PG8_SCHED;
	s_waitcnt lgkmcnt(0)
	v_mfma_f32_16x16x32_bf16 v[62:65], v[152:155], v[190:193], v[62:65]
	v_mfma_f32_16x16x32_bf16 v[58:61], v[160:163], v[190:193], v[58:61]
	v_mfma_f32_16x16x32_bf16 v[46:49], v[152:155], v[198:201], v[46:49]
	v_mfma_f32_16x16x32_bf16 v[42:45], v[160:163], v[198:201], v[42:45]
	v_mfma_f32_16x16x32_bf16 v[30:33], v[152:155], v[206:209], v[30:33]
	v_mfma_f32_16x16x32_bf16 v[26:29], v[160:163], v[206:209], v[26:29]
	v_mfma_f32_16x16x32_bf16 v[14:17], v[152:155], v[214:217], v[14:17]
	v_mfma_f32_16x16x32_bf16 v[10:13], v[160:163], v[214:217], v[10:13]
	v_mfma_f32_16x16x32_bf16 v[62:65], v[156:159], v[194:197], v[62:65]
	v_mfma_f32_16x16x32_bf16 v[58:61], v[164:167], v[194:197], v[58:61]
	v_mfma_f32_16x16x32_bf16 v[46:49], v[156:159], v[202:205], v[46:49]
	v_mfma_f32_16x16x32_bf16 v[42:45], v[164:167], v[202:205], v[42:45]
	v_mfma_f32_16x16x32_bf16 v[30:33], v[156:159], v[210:213], v[30:33]
	v_mfma_f32_16x16x32_bf16 v[26:29], v[164:167], v[210:213], v[26:29]
	v_mfma_f32_16x16x32_bf16 v[14:17], v[156:159], v[218:221], v[14:17]
	v_mfma_f32_16x16x32_bf16 v[10:13], v[164:167], v[218:221], v[10:13]
	v_mfma_f32_16x16x32_bf16 v[54:57], v[168:171], v[190:193], v[54:57]
	v_mfma_f32_16x16x32_bf16 v[50:53], v[176:179], v[190:193], v[50:53]
	v_mfma_f32_16x16x32_bf16 v[38:41], v[168:171], v[198:201], v[38:41]
	v_mfma_f32_16x16x32_bf16 v[34:37], v[176:179], v[198:201], v[34:37]
	v_mfma_f32_16x16x32_bf16 v[22:25], v[168:171], v[206:209], v[22:25]
	v_mfma_f32_16x16x32_bf16 v[18:21], v[176:179], v[206:209], v[18:21]
	v_mfma_f32_16x16x32_bf16 v[6:9], v[168:171], v[214:217], v[6:9]
	v_mfma_f32_16x16x32_bf16 v[2:5], v[176:179], v[214:217], v[2:5]
	v_mfma_f32_16x16x32_bf16 v[54:57], v[172:175], v[194:197], v[54:57]
	v_mfma_f32_16x16x32_bf16 v[50:53], v[180:183], v[194:197], v[50:53]
	v_mfma_f32_16x16x32_bf16 v[38:41], v[172:175], v[202:205], v[38:41]
	v_mfma_f32_16x16x32_bf16 v[34:37], v[180:183], v[202:205], v[34:37]
	v_mfma_f32_16x16x32_bf16 v[22:25], v[172:175], v[210:213], v[22:25]
	v_mfma_f32_16x16x32_bf16 v[18:21], v[180:183], v[210:213], v[18:21]
	v_mfma_f32_16x16x32_bf16 v[6:9], v[172:175], v[218:221], v[6:9]
	v_mfma_f32_16x16x32_bf16 v[2:5], v[180:183], v[218:221], v[2:5]
	s_barrier
	v_add_u32_e32 v151, s58, v149
	ds_read_b128 v[152:155], v151
	ds_read_b128 v[156:159], v151 offset:1024
	ds_read_b128 v[160:163], v151 offset:2048
	ds_read_b128 v[164:167], v151 offset:3072
	v_add_u32_e32 v151, s59, v149
	ds_read_b128 v[168:171], v151
	ds_read_b128 v[172:175], v151 offset:1024
	ds_read_b128 v[176:179], v151 offset:2048
	ds_read_b128 v[180:183], v151 offset:3072
	s_add_u32 s36, s36, 0x160000
	s_addc_u32 s37, s37, 0
	v_lshl_add_u64 v[228:229], s[36:37], 0, v[136:137]
	s_mov_b32 m0, s44
	v_lshl_add_u64 v[228:229], v[228:229], 0, v[130:131]
	ds_read_b128 v[190:193], v150 offset:32768
	ds_read_b128 v[194:197], v150 offset:33792
	ds_read_b128 v[198:201], v150 offset:34816
	ds_read_b128 v[202:205], v150 offset:35840
	ds_read_b128 v[206:209], v150 offset:36864
	ds_read_b128 v[210:213], v150 offset:37888
	ds_read_b128 v[214:217], v150 offset:38912
	ds_read_b128 v[218:221], v150 offset:39936
	global_load_lds_dwordx4 v[228:229], off
	v_lshl_add_u64 v[228:229], s[36:37], 0, v[138:139]
	v_lshl_add_u64 v[228:229], v[228:229], 0, v[130:131]
	s_mov_b32 m0, s45
	s_nop 0
	global_load_lds_dwordx4 v[228:229], off
	s_waitcnt vmcnt(8)
	s_waitcnt lgkmcnt(0)
	s_barrier
	s_waitcnt lgkmcnt(0)
	v_mfma_f32_16x16x32_bf16 v[126:129], v[152:155], v[190:193], v[126:129]
	v_mfma_f32_16x16x32_bf16 v[122:125], v[160:163], v[190:193], v[122:125]
	v_mfma_f32_16x16x32_bf16 v[110:113], v[152:155], v[198:201], v[110:113]
	v_mfma_f32_16x16x32_bf16 v[106:109], v[160:163], v[198:201], v[106:109]
	v_mfma_f32_16x16x32_bf16 v[94:97], v[152:155], v[206:209], v[94:97]
	v_mfma_f32_16x16x32_bf16 v[90:93], v[160:163], v[206:209], v[90:93]
	v_mfma_f32_16x16x32_bf16 v[78:81], v[152:155], v[214:217], v[78:81]
	v_mfma_f32_16x16x32_bf16 v[74:77], v[160:163], v[214:217], v[74:77]
	v_mfma_f32_16x16x32_bf16 v[126:129], v[156:159], v[194:197], v[126:129]
	v_mfma_f32_16x16x32_bf16 v[122:125], v[164:167], v[194:197], v[122:125]
	v_mfma_f32_16x16x32_bf16 v[110:113], v[156:159], v[202:205], v[110:113]
	v_mfma_f32_16x16x32_bf16 v[106:109], v[164:167], v[202:205], v[106:109]
	v_mfma_f32_16x16x32_bf16 v[94:97], v[156:159], v[210:213], v[94:97]
	v_mfma_f32_16x16x32_bf16 v[90:93], v[164:167], v[210:213], v[90:93]
	v_mfma_f32_16x16x32_bf16 v[78:81], v[156:159], v[218:221], v[78:81]
	v_mfma_f32_16x16x32_bf16 v[74:77], v[164:167], v[218:221], v[74:77]
	v_mfma_f32_16x16x32_bf16 v[118:121], v[168:171], v[190:193], v[118:121]
	v_mfma_f32_16x16x32_bf16 v[114:117], v[176:179], v[190:193], v[114:117]
	v_mfma_f32_16x16x32_bf16 v[102:105], v[168:171], v[198:201], v[102:105]
	v_mfma_f32_16x16x32_bf16 v[98:101], v[176:179], v[198:201], v[98:101]
	v_mfma_f32_16x16x32_bf16 v[86:89], v[168:171], v[206:209], v[86:89]
	v_mfma_f32_16x16x32_bf16 v[82:85], v[176:179], v[206:209], v[82:85]
	v_mfma_f32_16x16x32_bf16 v[70:73], v[168:171], v[214:217], v[70:73]
	v_mfma_f32_16x16x32_bf16 v[66:69], v[176:179], v[214:217], v[66:69]
	v_mfma_f32_16x16x32_bf16 v[118:121], v[172:175], v[194:197], v[118:121]
	v_mfma_f32_16x16x32_bf16 v[114:117], v[180:183], v[194:197], v[114:117]
	v_mfma_f32_16x16x32_bf16 v[102:105], v[172:175], v[202:205], v[102:105]
	v_mfma_f32_16x16x32_bf16 v[98:101], v[180:183], v[202:205], v[98:101]
	v_mfma_f32_16x16x32_bf16 v[86:89], v[172:175], v[210:213], v[86:89]
	v_mfma_f32_16x16x32_bf16 v[82:85], v[180:183], v[210:213], v[82:85]
	v_mfma_f32_16x16x32_bf16 v[70:73], v[172:175], v[218:221], v[70:73]
	v_mfma_f32_16x16x32_bf16 v[66:69], v[180:183], v[218:221], v[66:69]
	s_barrier
; #define PG8_STAGE(bufoff, gbase, RR, ld) do { _Pragma("unroll") for (int _i = 0; _i < 2; ++_i) \
;         __builtin_amdgcn_global_load_lds((const unsigned*)((const char*)(gbase) + (RR)[_i] * (ld) + C2[_i]), (LAS unsigned*)(lds + (bufoff) + ldsw + _i * 8192), 16, 0, 0); } while (0)
; #define PG8_LDA(dst, b, h) do { _Pragma("unroll") for (int m = 0; m < 4; ++m) _Pragma("unroll") for (int k = 0; k < 2; ++k) dst[m][k] = *(const LAS bf16x8*)(lds + PG8_SA(b, h) + aoff + m * 2048 + k * 1024); } while (0)
; #define PG8_MMA(ai, bj, At, Bt) do { __builtin_amdgcn_s_setprio(1); _Pragma("unroll") for (int m = 0; m < 4; ++m) _Pragma("unroll") for (int n = 0; n < 2; ++n) _Pragma("unroll") for (int k = 0; k < 2; ++k) \
;         acc[ai][bj][m][n] = __builtin_amdgcn_mfma_f32_16x16x32_bf16(Bt[n][k], At[m][k], acc[ai][bj][m][n], 0, 0, 0); __builtin_amdgcn_s_setprio(0); } while (0)
; #define PG8_WAIT_V(n) asm volatile("s_waitcnt vmcnt(" #n ")" ::: "memory")
; #define PG8_WAIT_L(n) asm volatile("s_waitcnt lgkmcnt(" #n ")" ::: "memory")
; #define PG8_BAR __builtin_amdgcn_s_barrier()
; #define PG8_SCHED __builtin_amdgcn_sched_barrier(0)
; template <class Sched, class Epi>
; __device__ __forceinline__ void gemm_run(LAS unsigned char* lds, const Sched& S, const Epi& E) {
;     ...
;             PG8_LDA(At, 1, 1); PG8_STAGE(PG8_SB(1, 0), b3, RB, lb2); PG8_STAGE(PG8_SB(1, 1), b3 + (size_t)HALF * lb2, RB, lb2); PG8_STAGE(PG8_SA(1, 0), a3, RA, la2);
;             PG8_WAIT_V(8); PG8_WAIT_L(0); PG8_BAR; PG8_MMA(1, 0, At, B0); PG8_MMA(1, 1, At, B1); PG8_BAR; PG8_SCHED;
;         }
;         if (wr == 0) PG8_BAR;
	s_mov_b32 m0, s60
	v_lshl_add_u64 v[184:185], v[184:185], 0, s[10:11]
	ds_read_b128 v[190:193], v150 offset:49152
	ds_read_b128 v[194:197], v150 offset:50176
	ds_read_b128 v[198:201], v150 offset:51200
	ds_read_b128 v[202:205], v150 offset:52224
	ds_read_b128 v[206:209], v150 offset:53248
	ds_read_b128 v[210:213], v150 offset:54272
	ds_read_b128 v[214:217], v150 offset:55296
	ds_read_b128 v[218:221], v150 offset:56320
	global_load_lds_dwordx4 v[184:185], off
	s_add_i32 m0, s60, 0x2000
	s_add_u32 s30, s30, 0x160080
	v_lshl_add_u64 v[184:185], v[222:223], 0, s[10:11]
	s_addc_u32 s31, s31, 0
	global_load_lds_dwordx4 v[184:185], off
	v_lshl_add_u64 v[184:185], s[30:31], 0, v[132:133]
	s_add_i32 s36, s59, s35
	v_lshl_add_u64 v[184:185], v[184:185], 0, v[130:131]
	s_mov_b32 m0, s36
	s_nop 0
	global_load_lds_dwordx4 v[184:185], off
	v_lshl_add_u64 v[184:185], s[30:31], 0, v[134:135]
	v_lshl_add_u64 v[184:185], v[184:185], 0, v[130:131]
	s_add_i32 m0, s36, 0x2000
	s_nop 0
	global_load_lds_dwordx4 v[184:185], off
	v_lshl_add_u64 v[184:185], v[224:225], 0, s[10:11]
	s_mov_b32 m0, s47
	s_nop 0
	global_load_lds_dwordx4 v[184:185], off
	v_lshl_add_u64 v[184:185], v[226:227], 0, s[10:11]
	s_mov_b32 m0, s48
	s_nop 0
	global_load_lds_dwordx4 v[184:185], off
	s_waitcnt vmcnt(8)
	s_waitcnt lgkmcnt(0)
	s_barrier
	s_waitcnt lgkmcnt(0)
	v_mfma_f32_16x16x32_bf16 v[62:65], v[152:155], v[190:193], v[62:65]
	v_mfma_f32_16x16x32_bf16 v[58:61], v[160:163], v[190:193], v[58:61]
	v_mfma_f32_16x16x32_bf16 v[46:49], v[152:155], v[198:201], v[46:49]
	v_mfma_f32_16x16x32_bf16 v[42:45], v[160:163], v[198:201], v[42:45]
	v_mfma_f32_16x16x32_bf16 v[30:33], v[152:155], v[206:209], v[30:33]
	v_mfma_f32_16x16x32_bf16 v[26:29], v[160:163], v[206:209], v[26:29]
	v_mfma_f32_16x16x32_bf16 v[14:17], v[152:155], v[214:217], v[14:17]
	v_mfma_f32_16x16x32_bf16 v[10:13], v[160:163], v[214:217], v[10:13]
	v_mfma_f32_16x16x32_bf16 v[62:65], v[156:159], v[194:197], v[62:65]
	v_mfma_f32_16x16x32_bf16 v[58:61], v[164:167], v[194:197], v[58:61]
	v_mfma_f32_16x16x32_bf16 v[46:49], v[156:159], v[202:205], v[46:49]
	v_mfma_f32_16x16x32_bf16 v[42:45], v[164:167], v[202:205], v[42:45]
	v_mfma_f32_16x16x32_bf16 v[30:33], v[156:159], v[210:213], v[30:33]
	v_mfma_f32_16x16x32_bf16 v[26:29], v[164:167], v[210:213], v[26:29]
	v_mfma_f32_16x16x32_bf16 v[14:17], v[156:159], v[218:221], v[14:17]
	v_mfma_f32_16x16x32_bf16 v[10:13], v[164:167], v[218:221], v[10:13]
	v_mfma_f32_16x16x32_bf16 v[54:57], v[168:171], v[190:193], v[54:57]
	v_mfma_f32_16x16x32_bf16 v[50:53], v[176:179], v[190:193], v[50:53]
	v_mfma_f32_16x16x32_bf16 v[38:41], v[168:171], v[198:201], v[38:41]
	v_mfma_f32_16x16x32_bf16 v[34:37], v[176:179], v[198:201], v[34:37]
	v_mfma_f32_16x16x32_bf16 v[22:25], v[168:171], v[206:209], v[22:25]
	v_mfma_f32_16x16x32_bf16 v[18:21], v[176:179], v[206:209], v[18:21]
	v_mfma_f32_16x16x32_bf16 v[6:9], v[168:171], v[214:217], v[6:9]
	v_mfma_f32_16x16x32_bf16 v[2:5], v[176:179], v[214:217], v[2:5]
	v_mfma_f32_16x16x32_bf16 v[54:57], v[172:175], v[194:197], v[54:57]
	v_mfma_f32_16x16x32_bf16 v[50:53], v[180:183], v[194:197], v[50:53]
	v_mfma_f32_16x16x32_bf16 v[38:41], v[172:175], v[202:205], v[38:41]
	v_mfma_f32_16x16x32_bf16 v[34:37], v[180:183], v[202:205], v[34:37]
	v_mfma_f32_16x16x32_bf16 v[22:25], v[172:175], v[210:213], v[22:25]
	v_mfma_f32_16x16x32_bf16 v[18:21], v[180:183], v[210:213], v[18:21]
	v_mfma_f32_16x16x32_bf16 v[6:9], v[172:175], v[218:221], v[6:9]
	v_mfma_f32_16x16x32_bf16 v[2:5], v[180:183], v[218:221], v[2:5]
	s_barrier
	s_add_i32 s67, s67, 2
	s_add_u32 s28, s28, 0x100
	s_addc_u32 s29, s29, 0
	s_cmpk_gt_u32 s67, 0x55
	s_cbranch_scc0 .LBB0_1068
	s_and_b64 vcc, exec, s[12:13]
	s_cbranch_vccz .LBB0_1071
	s_barrier

; #define PG8_STAGE(bufoff, gbase, RR, ld) do { _Pragma("unroll") for (int _i = 0; _i < 2; ++_i) \
;         __builtin_amdgcn_global_load_lds((const unsigned*)((const char*)(gbase) + (RR)[_i] * (ld) + C2[_i]), (LAS unsigned*)(lds + (bufoff) + ldsw + _i * 8192), 16, 0, 0); } while (0)
; #define PG8_LDA(dst, b, h) do { _Pragma("unroll") for (int m = 0; m < 4; ++m) _Pragma("unroll") for (int k = 0; k < 2; ++k) dst[m][k] = *(const LAS bf16x8*)(lds + PG8_SA(b, h) + aoff + m * 2048 + k * 1024); } while (0)
; #define PG8_LDB(dst, b, h) do { _Pragma("unroll") for (int n = 0; n < 2; ++n) _Pragma("unroll") for (int k = 0; k < 2; ++k) dst[n][k] = *(const LAS bf16x8*)(lds + PG8_SB(b, h) + boff + n * 2048 + k * 1024); } while (0)
; #define PG8_MMA(ai, bj, At, Bt) do { __builtin_amdgcn_s_setprio(1); _Pragma("unroll") for (int m = 0; m < 4; ++m) _Pragma("unroll") for (int n = 0; n < 2; ++n) _Pragma("unroll") for (int k = 0; k < 2; ++k) \
;         acc[ai][bj][m][n] = __builtin_amdgcn_mfma_f32_16x16x32_bf16(Bt[n][k], At[m][k], acc[ai][bj][m][n], 0, 0, 0); __builtin_amdgcn_s_setprio(0); } while (0)
; #define PG8_WAIT_V(n) asm volatile("s_waitcnt vmcnt(" #n ")" ::: "memory")
; #define PG8_WAIT_L(n) asm volatile("s_waitcnt lgkmcnt(" #n ")" ::: "memory")
; #define PG8_BAR __builtin_amdgcn_s_barrier()
; #define PG8_SCHED __builtin_amdgcn_sched_barrier(0)
; template <class Sched, class Epi>
; __device__ __forceinline__ void gemm_run(LAS unsigned char* lds, const Sched& S, const Epi& E) {
;     ...
;             PG8_LDB(B0, 0, 0); PG8_LDB(B1, 0, 1); PG8_SCHED; PG8_LDA(At, 0, 0); PG8_STAGE(PG8_SA(1, 1), a1 + (size_t)HALF * lda, RA, lda);
;             PG8_WAIT_V(8); PG8_WAIT_L(0); PG8_BAR; PG8_MMA(0, 0, At, B0); PG8_MMA(0, 1, At, B1); PG8_BAR; PG8_SCHED;
;             PG8_LDA(At, 0, 1); PG8_STAGE(PG8_SB(0, 0), b2, RB, lb2); PG8_STAGE(PG8_SB(0, 1), b2 + (size_t)HALF * lb2, RB, lb2); PG8_STAGE(PG8_SA(0, 0), a2, RA, la2);
;             PG8_WAIT_V(8); PG8_WAIT_L(0); PG8_BAR; PG8_MMA(1, 0, At, B0); PG8_MMA(1, 1, At, B1); PG8_BAR; PG8_SCHED;
.LBB0_1124:
	ds_read_b128 v[154:157], v150
	ds_read_b128 v[158:161], v150 offset:1024
	ds_read_b128 v[162:165], v150 offset:2048
	ds_read_b128 v[166:169], v150 offset:3072
	ds_read_b128 v[170:173], v151
	ds_read_b128 v[174:177], v151 offset:1024
	ds_read_b128 v[178:181], v151 offset:2048
	ds_read_b128 v[182:185], v151 offset:3072
	s_add_u32 s36, s28, s30
	s_addc_u32 s37, s29, s31
	s_add_u32 s36, s36, 0x100
	s_addc_u32 s37, s37, 0
	s_add_u32 s58, s55, s30
	s_addc_u32 s59, s56, s31
	s_cmpk_eq_i32 s30, 0x2b00
	s_cselect_b32 s39, s19, s37
	s_cselect_b32 s38, s18, s36
	s_cselect_b32 s37, s23, s59
	s_cselect_b32 s36, s22, s58
	v_lshl_add_u64 v[218:219], v[146:147], 0, s[30:31]
	s_add_i32 m0, s33, 0xc000
	ds_read_b128 v[186:189], v152
	ds_read_b128 v[190:193], v152 offset:1024
	ds_read_b128 v[194:197], v152 offset:2048
	ds_read_b128 v[198:201], v152 offset:3072
	ds_read_b128 v[202:205], v152 offset:4096
	ds_read_b128 v[206:209], v152 offset:5120
	ds_read_b128 v[210:213], v152 offset:6144
	ds_read_b128 v[214:217], v152 offset:7168
	global_load_lds_dwordx4 v[218:219], off
	v_lshl_add_u64 v[218:219], v[148:149], 0, s[30:31]
	s_add_i32 m0, s33, 0xe000
	s_nop 0
	global_load_lds_dwordx4 v[218:219], off
	s_waitcnt vmcnt(8)
	s_waitcnt lgkmcnt(0)
	s_barrier
	s_waitcnt lgkmcnt(0)
	v_mfma_f32_16x16x32_bf16 v[126:129], v[154:157], v[186:189], v[126:129]
	v_mfma_f32_16x16x32_bf16 v[122:125], v[162:165], v[186:189], v[122:125]
	v_mfma_f32_16x16x32_bf16 v[110:113], v[154:157], v[194:197], v[110:113]
	v_mfma_f32_16x16x32_bf16 v[106:109], v[162:165], v[194:197], v[106:109]
	v_mfma_f32_16x16x32_bf16 v[94:97], v[154:157], v[202:205], v[94:97]
	v_mfma_f32_16x16x32_bf16 v[90:93], v[162:165], v[202:205], v[90:93]
	v_mfma_f32_16x16x32_bf16 v[78:81], v[154:157], v[210:213], v[78:81]
	v_mfma_f32_16x16x32_bf16 v[74:77], v[162:165], v[210:213], v[74:77]
	v_mfma_f32_16x16x32_bf16 v[126:129], v[158:161], v[190:193], v[126:129]
	v_mfma_f32_16x16x32_bf16 v[122:125], v[166:169], v[190:193], v[122:125]
	v_mfma_f32_16x16x32_bf16 v[110:113], v[158:161], v[198:201], v[110:113]
	v_mfma_f32_16x16x32_bf16 v[106:109], v[166:169], v[198:201], v[106:109]
	v_mfma_f32_16x16x32_bf16 v[94:97], v[158:161], v[206:209], v[94:97]
	v_mfma_f32_16x16x32_bf16 v[90:93], v[166:169], v[206:209], v[90:93]
	v_mfma_f32_16x16x32_bf16 v[78:81], v[158:161], v[214:217], v[78:81]
	v_mfma_f32_16x16x32_bf16 v[74:77], v[166:169], v[214:217], v[74:77]
	v_mfma_f32_16x16x32_bf16 v[118:121], v[170:173], v[186:189], v[118:121]
	v_mfma_f32_16x16x32_bf16 v[114:117], v[178:181], v[186:189], v[114:117]
	v_mfma_f32_16x16x32_bf16 v[102:105], v[170:173], v[194:197], v[102:105]
	v_mfma_f32_16x16x32_bf16 v[98:101], v[178:181], v[194:197], v[98:101]
	v_mfma_f32_16x16x32_bf16 v[86:89], v[170:173], v[202:205], v[86:89]
	v_mfma_f32_16x16x32_bf16 v[82:85], v[178:181], v[202:205], v[82:85]
	v_mfma_f32_16x16x32_bf16 v[70:73], v[170:173], v[210:213], v[70:73]
	v_mfma_f32_16x16x32_bf16 v[66:69], v[178:181], v[210:213], v[66:69]
	v_mfma_f32_16x16x32_bf16 v[118:121], v[174:177], v[190:193], v[118:121]
	v_mfma_f32_16x16x32_bf16 v[114:117], v[182:185], v[190:193], v[114:117]
	v_mfma_f32_16x16x32_bf16 v[102:105], v[174:177], v[198:201], v[102:105]
	v_mfma_f32_16x16x32_bf16 v[98:101], v[182:185], v[198:201], v[98:101]
	v_mfma_f32_16x16x32_bf16 v[86:89], v[174:177], v[206:209], v[86:89]
	v_mfma_f32_16x16x32_bf16 v[82:85], v[182:185], v[206:209], v[82:85]
	v_mfma_f32_16x16x32_bf16 v[70:73], v[174:177], v[214:217], v[70:73]
	v_mfma_f32_16x16x32_bf16 v[66:69], v[182:185], v[214:217], v[66:69]
	s_barrier
	v_lshl_add_u64 v[218:219], s[36:37], 0, v[132:133]
	s_add_i32 s58, s49, s3
	v_lshl_add_u64 v[218:219], v[218:219], 0, v[130:131]
	s_mov_b32 m0, s58
	ds_read_b128 v[186:189], v152 offset:16384
	ds_read_b128 v[190:193], v152 offset:17408
	ds_read_b128 v[194:197], v152 offset:18432
	ds_read_b128 v[198:201], v152 offset:19456
	ds_read_b128 v[202:205], v152 offset:20480
	ds_read_b128 v[206:209], v152 offset:21504
	ds_read_b128 v[210:213], v152 offset:22528
	ds_read_b128 v[214:217], v152 offset:23552
	global_load_lds_dwordx4 v[218:219], off
	s_add_i32 m0, s58, 0x2000
	s_add_u32 s58, s36, 0x160000
	v_lshl_add_u64 v[220:221], s[36:37], 0, v[134:135]
	s_addc_u32 s59, s37, 0
	v_lshl_add_u64 v[220:221], v[220:221], 0, v[130:131]
	v_lshl_add_u64 v[222:223], s[58:59], 0, v[132:133]
	s_add_i32 s60, s50, s3
	global_load_lds_dwordx4 v[220:221], off
	v_lshl_add_u64 v[222:223], v[222:223], 0, v[130:131]
	s_mov_b32 m0, s60
	v_lshl_add_u64 v[224:225], s[38:39], 0, v[138:139]
	global_load_lds_dwordx4 v[222:223], off
	v_lshl_add_u64 v[222:223], s[58:59], 0, v[134:135]
	v_lshl_add_u64 v[222:223], v[222:223], 0, v[130:131]
	s_add_i32 m0, s60, 0x2000
	v_lshl_add_u64 v[224:225], v[224:225], 0, v[130:131]
	global_load_lds_dwordx4 v[222:223], off
	v_lshl_add_u64 v[222:223], s[38:39], 0, v[136:137]
	v_lshl_add_u64 v[222:223], v[222:223], 0, v[130:131]
	s_mov_b32 m0, s33
	s_nop 0
	global_load_lds_dwordx4 v[222:223], off
	s_mov_b32 m0, s35
	s_nop 0
	global_load_lds_dwordx4 v[224:225], off
	s_waitcnt vmcnt(8)
	s_waitcnt lgkmcnt(0)
	s_barrier
; #define PG8_STAGE(bufoff, gbase, RR, ld) do { _Pragma("unroll") for (int _i = 0; _i < 2; ++_i) \
;         __builtin_amdgcn_global_load_lds((const unsigned*)((const char*)(gbase) + (RR)[_i] * (ld) + C2[_i]), (LAS unsigned*)(lds + (bufoff) + ldsw + _i * 8192), 16, 0, 0); } while (0)
; #define PG8_LDA(dst, b, h) do { _Pragma("unroll") for (int m = 0; m < 4; ++m) _Pragma("unroll") for (int k = 0; k < 2; ++k) dst[m][k] = *(const LAS bf16x8*)(lds + PG8_SA(b, h) + aoff + m * 2048 + k * 1024); } while (0)
; #define PG8_LDB(dst, b, h) do { _Pragma("unroll") for (int n = 0; n < 2; ++n) _Pragma("unroll") for (int k = 0; k < 2; ++k) dst[n][k] = *(const LAS bf16x8*)(lds + PG8_SB(b, h) + boff + n * 2048 + k * 1024); } while (0)
; #define PG8_MMA(ai, bj, At, Bt) do { __builtin_amdgcn_s_setprio(1); _Pragma("unroll") for (int m = 0; m < 4; ++m) _Pragma("unroll") for (int n = 0; n < 2; ++n) _Pragma("unroll") for (int k = 0; k < 2; ++k) \
;         acc[ai][bj][m][n] = __builtin_amdgcn_mfma_f32_16x16x32_bf16(Bt[n][k], At[m][k], acc[ai][bj][m][n], 0, 0, 0); __builtin_amdgcn_s_setprio(0); } while (0)
; #define PG8_WAIT_V(n) asm volatile("s_waitcnt vmcnt(" #n ")" ::: "memory")
; #define PG8_WAIT_L(n) asm volatile("s_waitcnt lgkmcnt(" #n ")" ::: "memory")
; #define PG8_BAR __builtin_amdgcn_s_barrier()
; #define PG8_SCHED __builtin_amdgcn_sched_barrier(0)
; template <class Sched, class Epi>
; __device__ __forceinline__ void gemm_run(LAS unsigned char* lds, const Sched& S, const Epi& E) {
;     ...
;             PG8_WAIT_V(8); PG8_WAIT_L(0); PG8_BAR; PG8_MMA(1, 0, At, B0); PG8_MMA(1, 1, At, B1); PG8_BAR; PG8_SCHED;
;             PG8_LDB(B0, 1, 0); PG8_LDB(B1, 1, 1); PG8_SCHED; PG8_LDA(At, 1, 0); PG8_STAGE(PG8_SA(0, 1), a2 + (size_t)HALF * la2, RA, la2);
;             PG8_WAIT_V(8); PG8_WAIT_L(0); PG8_BAR; PG8_MMA(0, 0, At, B0); PG8_MMA(0, 1, At, B1); PG8_BAR; PG8_SCHED;
	s_waitcnt lgkmcnt(0)
	v_mfma_f32_16x16x32_bf16 v[62:65], v[154:157], v[186:189], v[62:65]
	v_mfma_f32_16x16x32_bf16 v[58:61], v[162:165], v[186:189], v[58:61]
	v_mfma_f32_16x16x32_bf16 v[46:49], v[154:157], v[194:197], v[46:49]
	v_mfma_f32_16x16x32_bf16 v[42:45], v[162:165], v[194:197], v[42:45]
	v_mfma_f32_16x16x32_bf16 v[30:33], v[154:157], v[202:205], v[30:33]
	v_mfma_f32_16x16x32_bf16 v[26:29], v[162:165], v[202:205], v[26:29]
	v_mfma_f32_16x16x32_bf16 v[14:17], v[154:157], v[210:213], v[14:17]
	v_mfma_f32_16x16x32_bf16 v[10:13], v[162:165], v[210:213], v[10:13]
	v_mfma_f32_16x16x32_bf16 v[62:65], v[158:161], v[190:193], v[62:65]
	v_mfma_f32_16x16x32_bf16 v[58:61], v[166:169], v[190:193], v[58:61]
	v_mfma_f32_16x16x32_bf16 v[46:49], v[158:161], v[198:201], v[46:49]
	v_mfma_f32_16x16x32_bf16 v[42:45], v[166:169], v[198:201], v[42:45]
	v_mfma_f32_16x16x32_bf16 v[30:33], v[158:161], v[206:209], v[30:33]
	v_mfma_f32_16x16x32_bf16 v[26:29], v[166:169], v[206:209], v[26:29]
	v_mfma_f32_16x16x32_bf16 v[14:17], v[158:161], v[214:217], v[14:17]
	v_mfma_f32_16x16x32_bf16 v[10:13], v[166:169], v[214:217], v[10:13]
	v_mfma_f32_16x16x32_bf16 v[54:57], v[170:173], v[186:189], v[54:57]
	v_mfma_f32_16x16x32_bf16 v[50:53], v[178:181], v[186:189], v[50:53]
	v_mfma_f32_16x16x32_bf16 v[38:41], v[170:173], v[194:197], v[38:41]
	v_mfma_f32_16x16x32_bf16 v[34:37], v[178:181], v[194:197], v[34:37]
	v_mfma_f32_16x16x32_bf16 v[22:25], v[170:173], v[202:205], v[22:25]
	v_mfma_f32_16x16x32_bf16 v[18:21], v[178:181], v[202:205], v[18:21]
	v_mfma_f32_16x16x32_bf16 v[6:9], v[170:173], v[210:213], v[6:9]
	v_mfma_f32_16x16x32_bf16 v[2:5], v[178:181], v[210:213], v[2:5]
	v_mfma_f32_16x16x32_bf16 v[54:57], v[174:177], v[190:193], v[54:57]
	v_mfma_f32_16x16x32_bf16 v[50:53], v[182:185], v[190:193], v[50:53]
	v_mfma_f32_16x16x32_bf16 v[38:41], v[174:177], v[198:201], v[38:41]
	v_mfma_f32_16x16x32_bf16 v[34:37], v[182:185], v[198:201], v[34:37]
	v_mfma_f32_16x16x32_bf16 v[22:25], v[174:177], v[206:209], v[22:25]
	v_mfma_f32_16x16x32_bf16 v[18:21], v[182:185], v[206:209], v[18:21]
	v_mfma_f32_16x16x32_bf16 v[6:9], v[174:177], v[214:217], v[6:9]
	v_mfma_f32_16x16x32_bf16 v[2:5], v[182:185], v[214:217], v[2:5]
	s_barrier
	s_add_i32 s58, 0, 0x18000
	s_add_i32 s59, 0, 0x1c000
	v_add_u32_e32 v166, s58, v141
	v_add_u32_e32 v182, s59, v141
	ds_read_b128 v[154:157], v166
	ds_read_b128 v[158:161], v166 offset:1024
	ds_read_b128 v[162:165], v166 offset:2048
	ds_read_b128 v[166:169], v166 offset:3072
	ds_read_b128 v[170:173], v182
	ds_read_b128 v[174:177], v182 offset:1024
	ds_read_b128 v[178:181], v182 offset:2048
	ds_read_b128 v[182:185], v182 offset:3072
	s_add_u32 s38, s38, 0x160000
	s_addc_u32 s39, s39, 0
	v_lshl_add_u64 v[226:227], s[38:39], 0, v[136:137]
	s_mov_b32 m0, s40
	v_lshl_add_u64 v[226:227], v[226:227], 0, v[130:131]
	ds_read_b128 v[186:189], v152 offset:32768
	ds_read_b128 v[190:193], v152 offset:33792
	ds_read_b128 v[194:197], v152 offset:34816
	ds_read_b128 v[198:201], v152 offset:35840
	ds_read_b128 v[202:205], v152 offset:36864
	ds_read_b128 v[206:209], v152 offset:37888
	ds_read_b128 v[210:213], v152 offset:38912
	ds_read_b128 v[214:217], v152 offset:39936
	global_load_lds_dwordx4 v[226:227], off
	v_lshl_add_u64 v[226:227], s[38:39], 0, v[138:139]
	v_lshl_add_u64 v[226:227], v[226:227], 0, v[130:131]
	s_mov_b32 m0, s41
	s_nop 0
	global_load_lds_dwordx4 v[226:227], off
	s_waitcnt vmcnt(8)
	s_waitcnt lgkmcnt(0)
	s_barrier
	s_waitcnt lgkmcnt(0)
	v_mfma_f32_16x16x32_bf16 v[126:129], v[154:157], v[186:189], v[126:129]
	v_mfma_f32_16x16x32_bf16 v[122:125], v[162:165], v[186:189], v[122:125]
	v_mfma_f32_16x16x32_bf16 v[110:113], v[154:157], v[194:197], v[110:113]
	v_mfma_f32_16x16x32_bf16 v[106:109], v[162:165], v[194:197], v[106:109]
	v_mfma_f32_16x16x32_bf16 v[94:97], v[154:157], v[202:205], v[94:97]
	v_mfma_f32_16x16x32_bf16 v[90:93], v[162:165], v[202:205], v[90:93]
	v_mfma_f32_16x16x32_bf16 v[78:81], v[154:157], v[210:213], v[78:81]
	v_mfma_f32_16x16x32_bf16 v[74:77], v[162:165], v[210:213], v[74:77]
	v_mfma_f32_16x16x32_bf16 v[126:129], v[158:161], v[190:193], v[126:129]
	v_mfma_f32_16x16x32_bf16 v[122:125], v[166:169], v[190:193], v[122:125]
	v_mfma_f32_16x16x32_bf16 v[110:113], v[158:161], v[198:201], v[110:113]
	v_mfma_f32_16x16x32_bf16 v[106:109], v[166:169], v[198:201], v[106:109]
	v_mfma_f32_16x16x32_bf16 v[94:97], v[158:161], v[206:209], v[94:97]
	v_mfma_f32_16x16x32_bf16 v[90:93], v[166:169], v[206:209], v[90:93]
	v_mfma_f32_16x16x32_bf16 v[78:81], v[158:161], v[214:217], v[78:81]
	v_mfma_f32_16x16x32_bf16 v[74:77], v[166:169], v[214:217], v[74:77]
	v_mfma_f32_16x16x32_bf16 v[118:121], v[170:173], v[186:189], v[118:121]
	v_mfma_f32_16x16x32_bf16 v[114:117], v[178:181], v[186:189], v[114:117]
	v_mfma_f32_16x16x32_bf16 v[102:105], v[170:173], v[194:197], v[102:105]
	v_mfma_f32_16x16x32_bf16 v[98:101], v[178:181], v[194:197], v[98:101]
	v_mfma_f32_16x16x32_bf16 v[86:89], v[170:173], v[202:205], v[86:89]
	v_mfma_f32_16x16x32_bf16 v[82:85], v[178:181], v[202:205], v[82:85]
	v_mfma_f32_16x16x32_bf16 v[70:73], v[170:173], v[210:213], v[70:73]
	v_mfma_f32_16x16x32_bf16 v[66:69], v[178:181], v[210:213], v[66:69]
	v_mfma_f32_16x16x32_bf16 v[118:121], v[174:177], v[190:193], v[118:121]
	v_mfma_f32_16x16x32_bf16 v[114:117], v[182:185], v[190:193], v[114:117]
	v_mfma_f32_16x16x32_bf16 v[102:105], v[174:177], v[198:201], v[102:105]
	v_mfma_f32_16x16x32_bf16 v[98:101], v[182:185], v[198:201], v[98:101]
	v_mfma_f32_16x16x32_bf16 v[86:89], v[174:177], v[206:209], v[86:89]
	v_mfma_f32_16x16x32_bf16 v[82:85], v[182:185], v[206:209], v[82:85]
	v_mfma_f32_16x16x32_bf16 v[70:73], v[174:177], v[214:217], v[70:73]
	v_mfma_f32_16x16x32_bf16 v[66:69], v[182:185], v[214:217], v[66:69]
	s_barrier
; #define PG8_STAGE(bufoff, gbase, RR, ld) do { _Pragma("unroll") for (int _i = 0; _i < 2; ++_i) \
;         __builtin_amdgcn_global_load_lds((const unsigned*)((const char*)(gbase) + (RR)[_i] * (ld) + C2[_i]), (LAS unsigned*)(lds + (bufoff) + ldsw + _i * 8192), 16, 0, 0); } while (0)
; #define PG8_LDA(dst, b, h) do { _Pragma("unroll") for (int m = 0; m < 4; ++m) _Pragma("unroll") for (int k = 0; k < 2; ++k) dst[m][k] = *(const LAS bf16x8*)(lds + PG8_SA(b, h) + aoff + m * 2048 + k * 1024); } while (0)
; #define PG8_MMA(ai, bj, At, Bt) do { __builtin_amdgcn_s_setprio(1); _Pragma("unroll") for (int m = 0; m < 4; ++m) _Pragma("unroll") for (int n = 0; n < 2; ++n) _Pragma("unroll") for (int k = 0; k < 2; ++k) \
;         acc[ai][bj][m][n] = __builtin_amdgcn_mfma_f32_16x16x32_bf16(Bt[n][k], At[m][k], acc[ai][bj][m][n], 0, 0, 0); __builtin_amdgcn_s_setprio(0); } while (0)
; #define PG8_WAIT_V(n) asm volatile("s_waitcnt vmcnt(" #n ")" ::: "memory")
; #define PG8_WAIT_L(n) asm volatile("s_waitcnt lgkmcnt(" #n ")" ::: "memory")
; #define PG8_BAR __builtin_amdgcn_s_barrier()
; #define PG8_SCHED __builtin_amdgcn_sched_barrier(0)
; template <class Sched, class Epi>
; __device__ __forceinline__ void gemm_run(LAS unsigned char* lds, const Sched& S, const Epi& E) {
;     ...
;             PG8_LDA(At, 1, 1); PG8_STAGE(PG8_SB(1, 0), b3, RB, lb2); PG8_STAGE(PG8_SB(1, 1), b3 + (size_t)HALF * lb2, RB, lb2); PG8_STAGE(PG8_SA(1, 0), a3, RA, la2);
;             PG8_WAIT_V(8); PG8_WAIT_L(0); PG8_BAR; PG8_MMA(1, 0, At, B0); PG8_MMA(1, 1, At, B1); PG8_BAR; PG8_SCHED;
;         }
;         if (wr == 0) PG8_BAR;
	s_add_i32 s38, s58, s3
	v_lshl_add_u64 v[218:219], v[218:219], 0, s[10:11]
	s_mov_b32 m0, s38
	ds_read_b128 v[186:189], v152 offset:49152
	ds_read_b128 v[190:193], v152 offset:50176
	ds_read_b128 v[194:197], v152 offset:51200
	ds_read_b128 v[198:201], v152 offset:52224
	ds_read_b128 v[202:205], v152 offset:53248
	ds_read_b128 v[206:209], v152 offset:54272
	ds_read_b128 v[210:213], v152 offset:55296
	ds_read_b128 v[214:217], v152 offset:56320
	global_load_lds_dwordx4 v[218:219], off
	s_add_i32 m0, s38, 0x2000
	s_add_u32 s36, s36, 0x160080
	v_lshl_add_u64 v[218:219], v[220:221], 0, s[10:11]
	s_addc_u32 s37, s37, 0
	global_load_lds_dwordx4 v[218:219], off
	v_lshl_add_u64 v[218:219], s[36:37], 0, v[132:133]
	s_add_i32 s38, s59, s3
	v_lshl_add_u64 v[218:219], v[218:219], 0, v[130:131]
	s_mov_b32 m0, s38
	s_nop 0
	global_load_lds_dwordx4 v[218:219], off
	v_lshl_add_u64 v[218:219], s[36:37], 0, v[134:135]
	v_lshl_add_u64 v[218:219], v[218:219], 0, v[130:131]
	s_add_i32 m0, s38, 0x2000
	s_nop 0
	global_load_lds_dwordx4 v[218:219], off
	v_lshl_add_u64 v[218:219], v[222:223], 0, s[10:11]
	s_mov_b32 m0, s43
	s_nop 0
	global_load_lds_dwordx4 v[218:219], off
	v_lshl_add_u64 v[218:219], v[224:225], 0, s[10:11]
	s_mov_b32 m0, s44
	s_nop 0
	global_load_lds_dwordx4 v[218:219], off
	s_waitcnt vmcnt(8)
	s_waitcnt lgkmcnt(0)
	s_barrier
	s_waitcnt lgkmcnt(0)
	v_mfma_f32_16x16x32_bf16 v[62:65], v[154:157], v[186:189], v[62:65]
	v_mfma_f32_16x16x32_bf16 v[58:61], v[162:165], v[186:189], v[58:61]
	v_mfma_f32_16x16x32_bf16 v[46:49], v[154:157], v[194:197], v[46:49]
	v_mfma_f32_16x16x32_bf16 v[42:45], v[162:165], v[194:197], v[42:45]
	v_mfma_f32_16x16x32_bf16 v[30:33], v[154:157], v[202:205], v[30:33]
	v_mfma_f32_16x16x32_bf16 v[26:29], v[162:165], v[202:205], v[26:29]
	v_mfma_f32_16x16x32_bf16 v[14:17], v[154:157], v[210:213], v[14:17]
	v_mfma_f32_16x16x32_bf16 v[10:13], v[162:165], v[210:213], v[10:13]
	v_mfma_f32_16x16x32_bf16 v[62:65], v[158:161], v[190:193], v[62:65]
	v_mfma_f32_16x16x32_bf16 v[58:61], v[166:169], v[190:193], v[58:61]
	v_mfma_f32_16x16x32_bf16 v[46:49], v[158:161], v[198:201], v[46:49]
	v_mfma_f32_16x16x32_bf16 v[42:45], v[166:169], v[198:201], v[42:45]
	v_mfma_f32_16x16x32_bf16 v[30:33], v[158:161], v[206:209], v[30:33]
	v_mfma_f32_16x16x32_bf16 v[26:29], v[166:169], v[206:209], v[26:29]
	v_mfma_f32_16x16x32_bf16 v[14:17], v[158:161], v[214:217], v[14:17]
	v_mfma_f32_16x16x32_bf16 v[10:13], v[166:169], v[214:217], v[10:13]
	v_mfma_f32_16x16x32_bf16 v[54:57], v[170:173], v[186:189], v[54:57]
	v_mfma_f32_16x16x32_bf16 v[50:53], v[178:181], v[186:189], v[50:53]
	v_mfma_f32_16x16x32_bf16 v[38:41], v[170:173], v[194:197], v[38:41]
	v_mfma_f32_16x16x32_bf16 v[34:37], v[178:181], v[194:197], v[34:37]
	v_mfma_f32_16x16x32_bf16 v[22:25], v[170:173], v[202:205], v[22:25]
	v_mfma_f32_16x16x32_bf16 v[18:21], v[178:181], v[202:205], v[18:21]
	v_mfma_f32_16x16x32_bf16 v[6:9], v[170:173], v[210:213], v[6:9]
	v_mfma_f32_16x16x32_bf16 v[2:5], v[178:181], v[210:213], v[2:5]
	v_mfma_f32_16x16x32_bf16 v[54:57], v[174:177], v[190:193], v[54:57]
	v_mfma_f32_16x16x32_bf16 v[50:53], v[182:185], v[190:193], v[50:53]
	v_mfma_f32_16x16x32_bf16 v[38:41], v[174:177], v[198:201], v[38:41]
	v_mfma_f32_16x16x32_bf16 v[34:37], v[182:185], v[198:201], v[34:37]
	v_mfma_f32_16x16x32_bf16 v[22:25], v[174:177], v[206:209], v[22:25]
	v_mfma_f32_16x16x32_bf16 v[18:21], v[182:185], v[206:209], v[18:21]
	v_mfma_f32_16x16x32_bf16 v[6:9], v[174:177], v[214:217], v[6:9]
	v_mfma_f32_16x16x32_bf16 v[2:5], v[182:185], v[214:217], v[2:5]
	s_barrier
	s_add_i32 s57, s57, 2
	s_add_u32 s30, s30, 0x100
	s_addc_u32 s31, s31, 0
	s_cmpk_gt_u32 s57, 0x55
	s_cbranch_scc0 .LBB0_1124
	s_and_b64 vcc, exec, s[12:13]
	s_cbranch_vccz .LBB0_1127
	s_barrier
